# baseline (speedup 1.0000x reference)
; __device__ __forceinline__ void nsa_quad(const Params& p, int qd, int g, float* slds, const int lane_in) {
;     ...
;     if (nch > 0) { load_k(A, kc, loff); load_v(A, vc, loff); }
;     for (int c = 0; c < nch; c += 2) {
;       if (c + 1 < nch) { load_k(B, kc + (c + 1) * 4096, loff); load_v(B, vc + (c + 1) * 4096, loff); }
;       if ((c + 1) * 64 <= nvmin) { CP2(A, c, 0) } else { CP2(A, c, 1) }
;       if (c + 1 < nch) {
;         if (c + 2 < nch) { load_k(A, kc + (c + 2) * 4096, loff); load_v(A, vc + (c + 2) * 4096, loff); }
;         if ((c + 2) * 64 <= nvmin) { CP2(B, c + 1, 0) } else { CP2(B, c + 1, 1) }
;       }
;     }
.LBB0_598:
	s_waitcnt lgkmcnt(1)
	ds_read_b128 v[168:171], v172 offset:12288
	s_waitcnt lgkmcnt(1)
	ds_read_b128 v[164:167], v172 offset:13312
	s_add_i32 s3, s9, 64
	s_cmp_gt_i32 s3, s31
	s_mov_b64 s[6:7], -1
	s_cbranch_scc1 .LBB0_611
	s_waitcnt vmcnt(7) lgkmcnt(1)
	v_mfma_f32_16x16x32_bf16 v[148:151], v[68:71], v[168:171], 0
	s_waitcnt vmcnt(6) lgkmcnt(0)
	v_mfma_f32_16x16x32_bf16 v[160:163], v[72:75], v[164:167], v[148:151]
	s_waitcnt vmcnt(5)
	v_mfma_f32_16x16x32_bf16 v[148:151], v[76:79], v[168:171], 0
	s_waitcnt vmcnt(4)
	v_mfma_f32_16x16x32_bf16 v[156:159], v[80:83], v[164:167], v[148:151]
	s_nop 3
	v_fma_f32 v0, v160, s49, -v195
	v_exp_f32_e32 v2, v0
	v_fma_f32 v0, v161, s49, -v195
	s_waitcnt vmcnt(3)
	v_mfma_f32_16x16x32_bf16 v[148:151], v[84:87], v[168:171], 0
	v_exp_f32_e32 v3, v0
	v_fma_f32 v160, v162, s49, -v195
	v_fma_f32 v161, v163, s49, -v195
	v_exp_f32_e32 v160, v160
	v_exp_f32_e32 v161, v161
	s_waitcnt vmcnt(2)
	v_mfma_f32_16x16x32_bf16 v[152:155], v[88:91], v[164:167], v[148:151]
	v_mul_f32_e64 v2, v190, v2
	v_mul_f32_e64 v3, v191, v3
	v_mul_f32_e32 v160, v160, v190
	v_mul_f32_e32 v161, v161, v191
	s_waitcnt vmcnt(1)
	v_mfma_f32_16x16x32_bf16 v[148:151], v[92:95], v[168:171], 0
	v_add_f32_e32 v0, 0, v2
	v_add_f32_e32 v0, v3, v0
	v_add_f32_e32 v0, v160, v0
	s_waitcnt vmcnt(0)
	v_mfma_f32_16x16x32_bf16 v[148:151], v[96:99], v[164:167], v[148:151]
	v_add_f32_e32 v0, v161, v0
	v_add_f32_dpp v163, v161, v161 quad_perm:[1,0,3,2] row_mask:0xf bank_mask:0xf bound_ctrl:1
	s_nop 0
	v_add_f32_dpp v0, v0, v0 quad_perm:[1,0,3,2] row_mask:0xf bank_mask:0xf bound_ctrl:1
	v_mov_b32_dpp v197, v163 quad_perm:[2,3,0,1] row_mask:0xf bank_mask:0xf bound_ctrl:1
	s_nop 0
	v_mov_b32_dpp v162, v0 quad_perm:[2,3,0,1] row_mask:0xf bank_mask:0xf bound_ctrl:1
	s_and_saveexec_b64 s[6:7], s[0:1]
	v_add_u32_e32 v198, s9, v196
	v_add_f32_e32 v0, v0, v162
	v_add_f32_e32 v162, v163, v197
	ds_write2st64_b32 v198, v0, v162 offset1:4
	s_or_b64 exec, exec, s[6:7]
	v_fma_f32 v0, v156, s49, -v195
	v_exp_f32_e32 v156, v0
	v_fma_f32 v0, v157, s49, -v195
	v_exp_f32_e32 v157, v0
	v_fma_f32 v0, v158, s49, -v195
	v_exp_f32_e32 v158, v0
	v_fma_f32 v0, v159, s49, -v195
	v_exp_f32_e32 v159, v0
	v_mul_f32_e32 v156, v156, v190
	v_mul_f32_e32 v157, v157, v191
	v_mul_f32_e32 v158, v158, v190
	v_mul_f32_e32 v159, v159, v191
	v_add_f32_e32 v0, 0, v156
	v_add_f32_e32 v0, v157, v0
	v_add_f32_e32 v0, v158, v0
	v_add_f32_e32 v0, v159, v0
	v_add_f32_dpp v163, v159, v159 quad_perm:[1,0,3,2] row_mask:0xf bank_mask:0xf bound_ctrl:1
	s_nop 0
	v_add_f32_dpp v0, v0, v0 quad_perm:[1,0,3,2] row_mask:0xf bank_mask:0xf bound_ctrl:1
	v_mov_b32_dpp v197, v163 quad_perm:[2,3,0,1] row_mask:0xf bank_mask:0xf bound_ctrl:1
	s_nop 0
	v_mov_b32_dpp v162, v0 quad_perm:[2,3,0,1] row_mask:0xf bank_mask:0xf bound_ctrl:1
	s_and_saveexec_b64 s[6:7], s[0:1]
	v_add_u32_e32 v198, s9, v196
	v_add_f32_e32 v0, v0, v162
	v_add_f32_e32 v162, v163, v197
	v_add_u32_e32 v163, 16, v198
	ds_write2st64_b32 v163, v0, v162 offset1:4
	s_or_b64 exec, exec, s[6:7]
	v_fma_f32 v0, v152, s49, -v195
	v_exp_f32_e32 v152, v0
	v_fma_f32 v0, v153, s49, -v195
	v_exp_f32_e32 v153, v0
	v_fma_f32 v0, v154, s49, -v195
	v_exp_f32_e32 v154, v0
	v_fma_f32 v0, v155, s49, -v195
	v_exp_f32_e32 v155, v0
	v_mul_f32_e32 v152, v152, v190
	v_mul_f32_e32 v153, v153, v191
	v_mul_f32_e32 v154, v154, v190
	v_mul_f32_e32 v155, v155, v191
	v_add_f32_e32 v0, 0, v152
	v_add_f32_e32 v0, v153, v0
	v_add_f32_e32 v0, v154, v0
	v_add_f32_e32 v0, v155, v0
	v_add_f32_dpp v163, v155, v155 quad_perm:[1,0,3,2] row_mask:0xf bank_mask:0xf bound_ctrl:1
	s_nop 0
	v_add_f32_dpp v0, v0, v0 quad_perm:[1,0,3,2] row_mask:0xf bank_mask:0xf bound_ctrl:1
	v_mov_b32_dpp v197, v163 quad_perm:[2,3,0,1] row_mask:0xf bank_mask:0xf bound_ctrl:1
	s_nop 0
	v_mov_b32_dpp v162, v0 quad_perm:[2,3,0,1] row_mask:0xf bank_mask:0xf bound_ctrl:1
	s_and_saveexec_b64 s[6:7], s[0:1]
	v_add_u32_e32 v198, s9, v196
	v_add_f32_e32 v0, v0, v162
	v_add_f32_e32 v162, v163, v197
	v_add_u32_e32 v163, 32, v198
	ds_write2st64_b32 v163, v0, v162 offset1:4
	s_or_b64 exec, exec, s[6:7]
	v_fma_f32 v0, v148, s49, -v195
	v_exp_f32_e32 v148, v0
	v_fma_f32 v0, v149, s49, -v195
	v_exp_f32_e32 v149, v0
	v_fma_f32 v0, v150, s49, -v195
	v_exp_f32_e32 v150, v0
	v_fma_f32 v0, v151, s49, -v195
	v_exp_f32_e32 v151, v0
	v_mul_f32_e32 v148, v148, v190
	v_mul_f32_e32 v149, v149, v191
	v_mul_f32_e32 v150, v150, v190
	v_mul_f32_e32 v151, v151, v191
	v_add_f32_e32 v0, 0, v148
	v_add_f32_e32 v0, v149, v0
	v_add_f32_e32 v0, v150, v0
	v_add_f32_e32 v0, v151, v0
	v_add_f32_dpp v163, v151, v151 quad_perm:[1,0,3,2] row_mask:0xf bank_mask:0xf bound_ctrl:1
	s_nop 0
	v_add_f32_dpp v0, v0, v0 quad_perm:[1,0,3,2] row_mask:0xf bank_mask:0xf bound_ctrl:1
	v_mov_b32_dpp v197, v163 quad_perm:[2,3,0,1] row_mask:0xf bank_mask:0xf bound_ctrl:1
	s_nop 0
	v_mov_b32_dpp v162, v0 quad_perm:[2,3,0,1] row_mask:0xf bank_mask:0xf bound_ctrl:1
	s_and_saveexec_b64 s[6:7], s[0:1]
	v_add_u32_e32 v198, s9, v196
	v_add_f32_e32 v0, v0, v162
	v_add_f32_e32 v162, v163, v197
	v_add_u32_e32 v163, 48, v198
	ds_write2st64_b32 v163, v0, v162 offset1:4
	s_or_b64 exec, exec, s[6:7]
	v_cvt_pk_bf16_f32 v198, v2, v3
	v_cvt_pk_bf16_f32 v199, v160, v161
	v_cvt_pk_bf16_f32 v200, v156, v157
	v_cvt_pk_bf16_f32 v201, v158, v159
	v_cvt_pk_bf16_f32 v206, v152, v153
	v_cvt_pk_bf16_f32 v207, v154, v155
	v_mfma_f32_16x16x32_bf16 v[156:159], v[100:103], v[198:201], v[144:147]
	v_cvt_pk_bf16_f32 v208, v148, v149
	v_cvt_pk_bf16_f32 v209, v150, v151
	v_mfma_f32_16x16x32_bf16 v[160:163], v[104:107], v[198:201], v[140:143]
	v_mfma_f32_16x16x32_bf16 v[202:205], v[108:111], v[198:201], v[136:139]
	v_mfma_f32_16x16x32_bf16 v[198:201], v[112:115], v[198:201], v[132:135]
	v_mfma_f32_16x16x32_bf16 v[148:151], v[116:119], v[206:209], v[156:159]
	v_mfma_f32_16x16x32_bf16 v[152:155], v[120:123], v[206:209], v[160:163]
	v_mfma_f32_16x16x32_bf16 v[156:159], v[124:127], v[206:209], v[202:205]
	v_mfma_f32_16x16x32_bf16 v[160:163], v[128:131], v[206:209], v[198:201]

; __device__ __forceinline__ void nsa_quad(const Params& p, int qd, int g, float* slds, const int lane_in) {
;     ...
;     if (nch > 0) { load_k(A, kc, loff); load_v(A, vc, loff); }
;     for (int c = 0; c < nch; c += 2) {
;       if (c + 1 < nch) { load_k(B, kc + (c + 1) * 4096, loff); load_v(B, vc + (c + 1) * 4096, loff); }
;       if ((c + 1) * 64 <= nvmin) { CP2(A, c, 0) } else { CP2(A, c, 1) }
;       if (c + 1 < nch) {
;         if (c + 2 < nch) { load_k(A, kc + (c + 2) * 4096, loff); load_v(A, vc + (c + 2) * 4096, loff); }
;         if ((c + 2) * 64 <= nvmin) { CP2(B, c + 1, 0) } else { CP2(B, c + 1, 1) }
;       }
;     }
.LBB0_611:
	s_and_b64 vcc, exec, s[6:7]
	s_cbranch_vccz .LBB0_608
	s_waitcnt vmcnt(7) lgkmcnt(1)
	v_mfma_f32_16x16x32_bf16 v[148:151], v[68:71], v[168:171], 0
	s_waitcnt vmcnt(6) lgkmcnt(0)
	v_mfma_f32_16x16x32_bf16 v[148:151], v[72:75], v[164:167], v[148:151]
	s_waitcnt vmcnt(5)
	v_mfma_f32_16x16x32_bf16 v[152:155], v[76:79], v[168:171], 0
	s_nop 5
	v_fma_f32 v0, v148, s49, -v195
	v_fma_f32 v3, v149, s49, -v195
	v_exp_f32_e32 v2, v0
	v_exp_f32_e32 v3, v3
	v_add_u32_e32 v0, s9, v194
	v_add_u32_e32 v156, 1, v0
	v_cmp_lt_i32_e32 vcc, v156, v187
	v_mul_f32_e32 v148, v2, v190
	v_mul_f32_e32 v149, v3, v191
	s_waitcnt vmcnt(4)
	v_mfma_f32_16x16x32_bf16 v[156:159], v[80:83], v[164:167], v[152:155]
	v_cndmask_b32_e32 v2, 0, v149, vcc
	v_cmp_lt_i32_e32 vcc, v0, v176
	v_or_b32_e32 v161, 3, v0
	s_waitcnt vmcnt(3)
	v_mfma_f32_16x16x32_bf16 v[152:155], v[84:87], v[168:171], 0
	v_cndmask_b32_e32 v160, 0, v148, vcc
	v_add_f32_e32 v3, 0, v160
	v_add_f32_e32 v197, v2, v3
	v_fma_f32 v3, v150, s49, -v195
	v_exp_f32_e32 v162, v3
	v_fma_f32 v3, v151, s49, -v195
	v_exp_f32_e32 v163, v3
	s_waitcnt vmcnt(1)
	v_mfma_f32_16x16x32_bf16 v[148:151], v[92:95], v[168:171], 0
	v_or_b32_e32 v198, 2, v0
	v_cmp_lt_i32_e32 vcc, v161, v187
	v_mul_f32_e32 v162, v162, v190
	v_mul_f32_e32 v163, v163, v191
	v_mfma_f32_16x16x32_bf16 v[152:155], v[88:91], v[164:167], v[152:155]
	v_cndmask_b32_e32 v161, 0, v163, vcc
	v_cmp_lt_i32_e32 vcc, v198, v176
	v_mov_b32_e32 v3, v0
	s_waitcnt vmcnt(0)
; __device__ __forceinline__ void nsa_quad(const Params& p, int qd, int g, float* slds, const int lane_in) {
;     ...
;     if (nch > 0) { load_k(A, kc, loff); load_v(A, vc, loff); }
;     for (int c = 0; c < nch; c += 2) {
;       if (c + 1 < nch) { load_k(B, kc + (c + 1) * 4096, loff); load_v(B, vc + (c + 1) * 4096, loff); }
;       if ((c + 1) * 64 <= nvmin) { CP2(A, c, 0) } else { CP2(A, c, 1) }
;       if (c + 1 < nch) {
;         if (c + 2 < nch) { load_k(A, kc + (c + 2) * 4096, loff); load_v(A, vc + (c + 2) * 4096, loff); }
;         if ((c + 2) * 64 <= nvmin) { CP2(B, c + 1, 0) } else { CP2(B, c + 1, 1) }
;       }
;     }
	v_mfma_f32_16x16x32_bf16 v[148:151], v[96:99], v[164:167], v[148:151]
	v_cndmask_b32_e32 v162, 0, v162, vcc
	v_add_f32_e32 v163, v162, v197
	v_add_f32_e32 v163, v161, v163
	v_add_f32_dpp v165, v161, v161 quad_perm:[1,0,3,2] row_mask:0xf bank_mask:0xf bound_ctrl:1
	s_nop 0
	v_add_f32_dpp v163, v163, v163 quad_perm:[1,0,3,2] row_mask:0xf bank_mask:0xf bound_ctrl:1
	v_mov_b32_dpp v166, v165 quad_perm:[2,3,0,1] row_mask:0xf bank_mask:0xf bound_ctrl:1
	s_nop 0
	v_mov_b32_dpp v164, v163 quad_perm:[2,3,0,1] row_mask:0xf bank_mask:0xf bound_ctrl:1
	s_and_saveexec_b64 s[6:7], s[0:1]
	v_add_u32_e32 v167, s9, v196
	v_add_f32_e32 v163, v163, v164
	v_add_f32_e32 v164, v165, v166
	ds_write2st64_b32 v167, v163, v164 offset1:4
	s_or_b64 exec, exec, s[6:7]
	v_fma_f32 v156, v156, s49, -v195
	v_fma_f32 v157, v157, s49, -v195
	v_exp_f32_e32 v156, v156
	v_exp_f32_e32 v157, v157
	v_cmp_lt_i32_e32 vcc, v3, v173
	v_mul_f32_e32 v164, v156, v190
	v_mul_f32_e32 v165, v157, v191
	v_fma_f32 v157, v158, s49, -v195
	v_exp_f32_e32 v158, v157
	v_fma_f32 v157, v159, s49, -v195
	v_exp_f32_e32 v159, v157
	v_cndmask_b32_e32 v156, 0, v165, vcc
	v_cmp_lt_i32_e32 vcc, v0, v178
	s_nop 1
	v_cndmask_b32_e32 v157, 0, v164, vcc
	v_mul_f32_e32 v164, v158, v190
	v_mul_f32_e32 v165, v159, v191
	v_cmp_lt_i32_e32 vcc, v3, v177
	v_add_f32_e32 v163, 0, v157
	v_add_f32_e32 v163, v156, v163
	v_cndmask_b32_e32 v158, 0, v165, vcc
	v_cmp_lt_i32_e32 vcc, v0, v180
	s_nop 0
	v_add_f32_dpp v165, v158, v158 quad_perm:[1,0,3,2] row_mask:0xf bank_mask:0xf bound_ctrl:1
	v_cndmask_b32_e32 v159, 0, v164, vcc
	v_add_f32_e32 v163, v159, v163
	v_add_f32_e32 v163, v158, v163
	v_mov_b32_dpp v166, v165 quad_perm:[2,3,0,1] row_mask:0xf bank_mask:0xf bound_ctrl:1
	s_nop 0
	v_add_f32_dpp v163, v163, v163 quad_perm:[1,0,3,2] row_mask:0xf bank_mask:0xf bound_ctrl:1
	s_nop 1
	v_mov_b32_dpp v164, v163 quad_perm:[2,3,0,1] row_mask:0xf bank_mask:0xf bound_ctrl:1
	s_and_saveexec_b64 s[6:7], s[0:1]
	v_add_u32_e32 v167, s9, v196
	v_add_f32_e32 v163, v163, v164
	v_add_f32_e32 v164, v165, v166
	v_add_u32_e32 v165, 16, v167
	ds_write2st64_b32 v165, v163, v164 offset1:4
	s_or_b64 exec, exec, s[6:7]
	v_fma_f32 v152, v152, s49, -v195
	v_fma_f32 v153, v153, s49, -v195
	v_exp_f32_e32 v152, v152
	v_exp_f32_e32 v153, v153
	v_cmp_lt_i32_e32 vcc, v3, v179
	v_mul_f32_e32 v164, v152, v190
	v_mul_f32_e32 v165, v153, v191
	v_fma_f32 v153, v154, s49, -v195
	v_exp_f32_e32 v154, v153
	v_fma_f32 v153, v155, s49, -v195
	v_exp_f32_e32 v155, v153
	v_cndmask_b32_e32 v152, 0, v165, vcc
	v_cmp_lt_i32_e32 vcc, v0, v182
	s_nop 1
	v_cndmask_b32_e32 v153, 0, v164, vcc
	v_mul_f32_e32 v164, v154, v190
	v_mul_f32_e32 v165, v155, v191
	v_cmp_lt_i32_e32 vcc, v3, v181
	v_add_f32_e32 v163, 0, v153
	v_add_f32_e32 v163, v152, v163
	v_cndmask_b32_e32 v154, 0, v165, vcc
	v_cmp_lt_i32_e32 vcc, v0, v184
	s_nop 0
	v_add_f32_dpp v165, v154, v154 quad_perm:[1,0,3,2] row_mask:0xf bank_mask:0xf bound_ctrl:1
	v_cndmask_b32_e32 v155, 0, v164, vcc
	v_add_f32_e32 v163, v155, v163
	v_add_f32_e32 v163, v154, v163
	v_mov_b32_dpp v166, v165 quad_perm:[2,3,0,1] row_mask:0xf bank_mask:0xf bound_ctrl:1
	s_nop 0
	v_add_f32_dpp v163, v163, v163 quad_perm:[1,0,3,2] row_mask:0xf bank_mask:0xf bound_ctrl:1
	s_nop 1
	v_mov_b32_dpp v164, v163 quad_perm:[2,3,0,1] row_mask:0xf bank_mask:0xf bound_ctrl:1
	s_and_saveexec_b64 s[6:7], s[0:1]
	v_add_u32_e32 v167, s9, v196
	v_add_f32_e32 v163, v163, v164
	v_add_f32_e32 v164, v165, v166
	v_add_u32_e32 v165, 32, v167
	ds_write2st64_b32 v165, v163, v164 offset1:4
	s_or_b64 exec, exec, s[6:7]
	v_fma_f32 v148, v148, s49, -v195
	v_fma_f32 v149, v149, s49, -v195
	v_exp_f32_e32 v148, v148
	v_exp_f32_e32 v149, v149
	v_cmp_lt_i32_e32 vcc, v3, v183
	v_mul_f32_e32 v164, v148, v190
	v_mul_f32_e32 v165, v149, v191
	v_fma_f32 v149, v150, s49, -v195
	v_exp_f32_e32 v150, v149
	v_fma_f32 v149, v151, s49, -v195
	v_exp_f32_e32 v151, v149
	v_cndmask_b32_e32 v148, 0, v165, vcc
	v_cmp_lt_i32_e32 vcc, v0, v186
	v_mul_f32_e32 v150, v150, v190
	v_mul_f32_e32 v151, v151, v191
	s_nop 0
	v_cndmask_b32_e32 v149, 0, v164, vcc
	v_cmp_lt_i32_e32 vcc, v3, v185
	v_add_f32_e32 v163, 0, v149
	v_add_f32_e32 v163, v148, v163
	v_cndmask_b32_e32 v3, 0, v151, vcc
	v_cmp_lt_i32_e32 vcc, v0, v188
	s_nop 1
	v_cndmask_b32_e32 v0, 0, v150, vcc
	v_add_f32_e32 v150, v0, v163
	v_add_f32_e32 v150, v3, v150
	v_add_f32_dpp v163, v3, v3 quad_perm:[1,0,3,2] row_mask:0xf bank_mask:0xf bound_ctrl:1
	s_nop 0
	v_add_f32_dpp v150, v150, v150 quad_perm:[1,0,3,2] row_mask:0xf bank_mask:0xf bound_ctrl:1
	v_mov_b32_dpp v164, v163 quad_perm:[2,3,0,1] row_mask:0xf bank_mask:0xf bound_ctrl:1
	s_nop 0
	v_mov_b32_dpp v151, v150 quad_perm:[2,3,0,1] row_mask:0xf bank_mask:0xf bound_ctrl:1
	s_and_saveexec_b64 s[6:7], s[0:1]
	v_add_u32_e32 v165, s9, v196
	v_add_f32_e32 v150, v150, v151
	v_add_f32_e32 v151, v163, v164
	v_add_u32_e32 v163, 48, v165
	ds_write2st64_b32 v163, v150, v151 offset1:4
	s_or_b64 exec, exec, s[6:7]
	v_cvt_pk_bf16_f32 v160, v160, v2
	v_cvt_pk_bf16_f32 v161, v162, v161
	v_cvt_pk_bf16_f32 v162, v157, v156
	v_cvt_pk_bf16_f32 v163, v159, v158
	s_nop 1
	v_mfma_f32_16x16x32_bf16 v[144:147], v[100:103], v[160:163], v[144:147]
	v_mfma_f32_16x16x32_bf16 v[140:143], v[104:107], v[160:163], v[140:143]
	v_mfma_f32_16x16x32_bf16 v[136:139], v[108:111], v[160:163], v[136:139]
	v_mfma_f32_16x16x32_bf16 v[132:135], v[112:115], v[160:163], v[132:135]
	v_cvt_pk_bf16_f32 v160, v153, v152
	v_cvt_pk_bf16_f32 v161, v155, v154
	v_cvt_pk_bf16_f32 v162, v149, v148
	v_cvt_pk_bf16_f32 v163, v0, v3
	s_nop 1
	v_mfma_f32_16x16x32_bf16 v[148:151], v[116:119], v[160:163], v[144:147]
	v_mfma_f32_16x16x32_bf16 v[152:155], v[120:123], v[160:163], v[140:143]
	v_mfma_f32_16x16x32_bf16 v[156:159], v[124:127], v[160:163], v[136:139]
	v_mfma_f32_16x16x32_bf16 v[160:163], v[128:131], v[160:163], v[132:135]
	s_andn2_b64 vcc, exec, s[4:5]
	s_mov_b64 s[4:5], -1
	s_cbranch_vccz .LBB0_609

; __device__ __forceinline__ void nsa_quad(const Params& p, int qd, int g, float* slds, const int lane_in) {
;     ...
;     if (nch > 0) { load_k(A, kc, loff); load_v(A, vc, loff); }
;     for (int c = 0; c < nch; c += 2) {
;       if (c + 1 < nch) { load_k(B, kc + (c + 1) * 4096, loff); load_v(B, vc + (c + 1) * 4096, loff); }
;       if ((c + 1) * 64 <= nvmin) { CP2(A, c, 0) } else { CP2(A, c, 1) }
;       if (c + 1 < nch) {
;         if (c + 2 < nch) { load_k(A, kc + (c + 2) * 4096, loff); load_v(A, vc + (c + 2) * 4096, loff); }
;         if ((c + 2) * 64 <= nvmin) { CP2(B, c + 1, 0) } else { CP2(B, c + 1, 1) }
;       }
;     }
.LBB0_624:
	s_waitcnt lgkmcnt(1)
	ds_read_b128 v[168:171], v172 offset:12288
	s_waitcnt lgkmcnt(1)
	ds_read_b128 v[164:167], v172 offset:13312
	s_add_i32 s3, s9, 0x80
	s_cmp_gt_i32 s3, s31
	s_mov_b64 s[4:5], -1
	s_cbranch_scc1 .LBB0_636
	s_waitcnt vmcnt(7) lgkmcnt(1)
	v_mfma_f32_16x16x32_bf16 v[132:135], v[4:7], v[168:171], 0
	s_waitcnt vmcnt(6) lgkmcnt(0)
	v_mfma_f32_16x16x32_bf16 v[144:147], v[8:11], v[164:167], v[132:135]
	s_waitcnt vmcnt(5)
	v_mfma_f32_16x16x32_bf16 v[132:135], v[12:15], v[168:171], 0
	s_waitcnt vmcnt(4)
	v_mfma_f32_16x16x32_bf16 v[140:143], v[16:19], v[164:167], v[132:135]
	s_nop 3
	v_fma_f32 v0, v144, s49, -v195
	v_exp_f32_e32 v2, v0
	v_fma_f32 v0, v145, s49, -v195
	s_waitcnt vmcnt(3)
	v_mfma_f32_16x16x32_bf16 v[132:135], v[20:23], v[168:171], 0
	v_exp_f32_e32 v3, v0
	v_fma_f32 v144, v146, s49, -v195
	v_fma_f32 v145, v147, s49, -v195
	v_exp_f32_e32 v144, v144
	v_exp_f32_e32 v145, v145
	s_waitcnt vmcnt(2)
	v_mfma_f32_16x16x32_bf16 v[136:139], v[24:27], v[164:167], v[132:135]
	v_mul_f32_e64 v2, v190, v2
	v_mul_f32_e64 v3, v191, v3
	v_mul_f32_e32 v144, v144, v190
	v_mul_f32_e32 v145, v145, v191
	s_waitcnt vmcnt(1)
	v_mfma_f32_16x16x32_bf16 v[132:135], v[28:31], v[168:171], 0
	v_add_f32_e32 v0, 0, v2
	v_add_f32_e32 v0, v3, v0
	v_add_f32_e32 v0, v144, v0
	s_waitcnt vmcnt(0)
	v_mfma_f32_16x16x32_bf16 v[132:135], v[32:35], v[164:167], v[132:135]
	v_add_f32_e32 v0, v145, v0
	v_add_f32_dpp v147, v145, v145 quad_perm:[1,0,3,2] row_mask:0xf bank_mask:0xf bound_ctrl:1
	s_nop 0
	v_add_f32_dpp v0, v0, v0 quad_perm:[1,0,3,2] row_mask:0xf bank_mask:0xf bound_ctrl:1
	v_mov_b32_dpp v197, v147 quad_perm:[2,3,0,1] row_mask:0xf bank_mask:0xf bound_ctrl:1
	s_nop 0
	v_mov_b32_dpp v146, v0 quad_perm:[2,3,0,1] row_mask:0xf bank_mask:0xf bound_ctrl:1
	s_and_saveexec_b64 s[4:5], s[0:1]
	v_add_u32_e32 v198, s9, v196
	v_add_f32_e32 v0, v0, v146
	v_add_f32_e32 v146, v147, v197
	v_add_u32_e32 v147, 64, v198
	ds_write2st64_b32 v147, v0, v146 offset1:4
	s_or_b64 exec, exec, s[4:5]
	v_fma_f32 v0, v140, s49, -v195
	v_exp_f32_e32 v140, v0
	v_fma_f32 v0, v141, s49, -v195
	v_exp_f32_e32 v141, v0
	v_fma_f32 v0, v142, s49, -v195
	v_exp_f32_e32 v142, v0
	v_fma_f32 v0, v143, s49, -v195
	v_exp_f32_e32 v143, v0
	v_mul_f32_e32 v140, v140, v190
	v_mul_f32_e32 v141, v141, v191
	v_mul_f32_e32 v142, v142, v190
	v_mul_f32_e32 v143, v143, v191
	v_add_f32_e32 v0, 0, v140
	v_add_f32_e32 v0, v141, v0
	v_add_f32_e32 v0, v142, v0
	v_add_f32_e32 v0, v143, v0
	v_add_f32_dpp v147, v143, v143 quad_perm:[1,0,3,2] row_mask:0xf bank_mask:0xf bound_ctrl:1
	s_nop 0
	v_add_f32_dpp v0, v0, v0 quad_perm:[1,0,3,2] row_mask:0xf bank_mask:0xf bound_ctrl:1
	v_mov_b32_dpp v197, v147 quad_perm:[2,3,0,1] row_mask:0xf bank_mask:0xf bound_ctrl:1
	s_nop 0
	v_mov_b32_dpp v146, v0 quad_perm:[2,3,0,1] row_mask:0xf bank_mask:0xf bound_ctrl:1
	s_and_saveexec_b64 s[4:5], s[0:1]
	v_add_u32_e32 v198, s9, v196
	v_add_f32_e32 v0, v0, v146
	v_add_f32_e32 v146, v147, v197
	v_add_u32_e32 v147, 0x50, v198
	ds_write2st64_b32 v147, v0, v146 offset1:4
	s_or_b64 exec, exec, s[4:5]
	v_fma_f32 v0, v136, s49, -v195
	v_exp_f32_e32 v136, v0
	v_fma_f32 v0, v137, s49, -v195
	v_exp_f32_e32 v137, v0
	v_fma_f32 v0, v138, s49, -v195
	v_exp_f32_e32 v138, v0
	v_fma_f32 v0, v139, s49, -v195
	v_exp_f32_e32 v139, v0
	v_mul_f32_e32 v136, v136, v190
	v_mul_f32_e32 v137, v137, v191
	v_mul_f32_e32 v138, v138, v190
	v_mul_f32_e32 v139, v139, v191
	v_add_f32_e32 v0, 0, v136
	v_add_f32_e32 v0, v137, v0
	v_add_f32_e32 v0, v138, v0
	v_add_f32_e32 v0, v139, v0
	v_add_f32_dpp v147, v139, v139 quad_perm:[1,0,3,2] row_mask:0xf bank_mask:0xf bound_ctrl:1
	s_nop 0
	v_add_f32_dpp v0, v0, v0 quad_perm:[1,0,3,2] row_mask:0xf bank_mask:0xf bound_ctrl:1
	v_mov_b32_dpp v197, v147 quad_perm:[2,3,0,1] row_mask:0xf bank_mask:0xf bound_ctrl:1
	s_nop 0
	v_mov_b32_dpp v146, v0 quad_perm:[2,3,0,1] row_mask:0xf bank_mask:0xf bound_ctrl:1
	s_and_saveexec_b64 s[4:5], s[0:1]
	v_add_u32_e32 v198, s9, v196
	v_add_f32_e32 v0, v0, v146
	v_add_f32_e32 v146, v147, v197
	v_add_u32_e32 v147, 0x60, v198
	ds_write2st64_b32 v147, v0, v146 offset1:4
	s_or_b64 exec, exec, s[4:5]
	v_fma_f32 v0, v132, s49, -v195
	v_exp_f32_e32 v132, v0
	v_fma_f32 v0, v133, s49, -v195
	v_exp_f32_e32 v133, v0
	v_fma_f32 v0, v134, s49, -v195
	v_exp_f32_e32 v134, v0
	v_fma_f32 v0, v135, s49, -v195
	v_exp_f32_e32 v135, v0
	v_mul_f32_e32 v132, v132, v190
	v_mul_f32_e32 v133, v133, v191
	v_mul_f32_e32 v134, v134, v190
	v_mul_f32_e32 v135, v135, v191
	v_add_f32_e32 v0, 0, v132
	v_add_f32_e32 v0, v133, v0
	v_add_f32_e32 v0, v134, v0
	v_add_f32_e32 v0, v135, v0
	v_add_f32_dpp v147, v135, v135 quad_perm:[1,0,3,2] row_mask:0xf bank_mask:0xf bound_ctrl:1
	s_nop 0
	v_add_f32_dpp v0, v0, v0 quad_perm:[1,0,3,2] row_mask:0xf bank_mask:0xf bound_ctrl:1
	v_mov_b32_dpp v197, v147 quad_perm:[2,3,0,1] row_mask:0xf bank_mask:0xf bound_ctrl:1
	s_nop 0
	v_mov_b32_dpp v146, v0 quad_perm:[2,3,0,1] row_mask:0xf bank_mask:0xf bound_ctrl:1
	s_and_saveexec_b64 s[4:5], s[0:1]
	v_add_u32_e32 v198, s9, v196
	v_add_f32_e32 v0, v0, v146
	v_add_f32_e32 v146, v147, v197
	v_add_u32_e32 v147, 0x70, v198
	ds_write2st64_b32 v147, v0, v146 offset1:4
	s_or_b64 exec, exec, s[4:5]
	v_cvt_pk_bf16_f32 v198, v2, v3
	v_cvt_pk_bf16_f32 v199, v144, v145
	v_cvt_pk_bf16_f32 v200, v140, v141
	v_cvt_pk_bf16_f32 v201, v142, v143
	v_cvt_pk_bf16_f32 v218, v136, v137
	v_cvt_pk_bf16_f32 v219, v138, v139
	v_mfma_f32_16x16x32_bf16 v[140:143], v[36:39], v[198:201], v[148:151]
	v_cvt_pk_bf16_f32 v220, v132, v133
	v_cvt_pk_bf16_f32 v221, v134, v135
	v_mfma_f32_16x16x32_bf16 v[202:205], v[40:43], v[198:201], v[152:155]
	v_mfma_f32_16x16x32_bf16 v[206:209], v[44:47], v[198:201], v[156:159]
	v_mfma_f32_16x16x32_bf16 v[198:201], v[48:51], v[198:201], v[160:163]
	v_mfma_f32_16x16x32_bf16 v[144:147], v[52:55], v[218:221], v[140:143]
	v_mfma_f32_16x16x32_bf16 v[140:143], v[56:59], v[218:221], v[202:205]
	v_mfma_f32_16x16x32_bf16 v[136:139], v[60:63], v[218:221], v[206:209]
	v_mfma_f32_16x16x32_bf16 v[132:135], v[64:67], v[218:221], v[198:201]

; __device__ __forceinline__ void nsa_quad(const Params& p, int qd, int g, float* slds, const int lane_in) {
;     ...
;     if (nch > 0) { load_k(A, kc, loff); load_v(A, vc, loff); }
;     for (int c = 0; c < nch; c += 2) {
;       if (c + 1 < nch) { load_k(B, kc + (c + 1) * 4096, loff); load_v(B, vc + (c + 1) * 4096, loff); }
;       if ((c + 1) * 64 <= nvmin) { CP2(A, c, 0) } else { CP2(A, c, 1) }
;       if (c + 1 < nch) {
;         if (c + 2 < nch) { load_k(A, kc + (c + 2) * 4096, loff); load_v(A, vc + (c + 2) * 4096, loff); }
;         if ((c + 2) * 64 <= nvmin) { CP2(B, c + 1, 0) } else { CP2(B, c + 1, 1) }
;       }
;     }
.LBB0_636:
	s_and_b64 vcc, exec, s[4:5]
	s_cbranch_vccz .LBB0_634
	s_waitcnt vmcnt(7) lgkmcnt(1)
	v_mfma_f32_16x16x32_bf16 v[132:135], v[4:7], v[168:171], 0
	v_add_u32_e32 v140, s9, v194
	s_waitcnt vmcnt(6) lgkmcnt(0)
	v_mfma_f32_16x16x32_bf16 v[132:135], v[8:11], v[164:167], v[132:135]
	s_waitcnt vmcnt(5)
	v_mfma_f32_16x16x32_bf16 v[136:139], v[12:15], v[168:171], 0
	s_nop 5
	v_fma_f32 v0, v132, s49, -v195
	v_fma_f32 v3, v133, s49, -v195
	v_exp_f32_e32 v2, v0
	v_exp_f32_e32 v3, v3
	v_add_u32_e32 v0, 64, v140
	v_add_u32_e32 v140, 0x41, v140
	v_cmp_lt_i32_e32 vcc, v140, v187
	v_mul_f32_e32 v132, v2, v190
	v_mul_f32_e32 v133, v3, v191
	s_waitcnt vmcnt(4)
	v_mfma_f32_16x16x32_bf16 v[140:143], v[16:19], v[164:167], v[136:139]
	v_cndmask_b32_e32 v2, 0, v133, vcc
	v_cmp_lt_i32_e32 vcc, v0, v176
	v_or_b32_e32 v145, 3, v0
	s_waitcnt vmcnt(3)
	v_mfma_f32_16x16x32_bf16 v[136:139], v[20:23], v[168:171], 0
	v_cndmask_b32_e32 v144, 0, v132, vcc
	v_add_f32_e32 v3, 0, v144
	v_add_f32_e32 v197, v2, v3
	v_fma_f32 v3, v134, s49, -v195
	v_exp_f32_e32 v146, v3
	v_fma_f32 v3, v135, s49, -v195
	v_exp_f32_e32 v147, v3
	s_waitcnt vmcnt(1)
	v_mfma_f32_16x16x32_bf16 v[132:135], v[28:31], v[168:171], 0
	v_or_b32_e32 v168, 2, v0
	v_cmp_lt_i32_e32 vcc, v145, v187
	v_mul_f32_e32 v146, v146, v190
	v_mul_f32_e32 v147, v147, v191
	v_mfma_f32_16x16x32_bf16 v[136:139], v[24:27], v[164:167], v[136:139]
	v_cndmask_b32_e32 v145, 0, v147, vcc
	v_cmp_lt_i32_e32 vcc, v168, v176
	v_mov_b32_e32 v3, v0
	s_waitcnt vmcnt(0)
; __device__ __forceinline__ void nsa_quad(const Params& p, int qd, int g, float* slds, const int lane_in) {
;     ...
;     if (nch > 0) { load_k(A, kc, loff); load_v(A, vc, loff); }
;     for (int c = 0; c < nch; c += 2) {
;       if (c + 1 < nch) { load_k(B, kc + (c + 1) * 4096, loff); load_v(B, vc + (c + 1) * 4096, loff); }
;       if ((c + 1) * 64 <= nvmin) { CP2(A, c, 0) } else { CP2(A, c, 1) }
;       if (c + 1 < nch) {
;         if (c + 2 < nch) { load_k(A, kc + (c + 2) * 4096, loff); load_v(A, vc + (c + 2) * 4096, loff); }
;         if ((c + 2) * 64 <= nvmin) { CP2(B, c + 1, 0) } else { CP2(B, c + 1, 1) }
;       }
;     }
	v_mfma_f32_16x16x32_bf16 v[132:135], v[32:35], v[164:167], v[132:135]
	v_cndmask_b32_e32 v146, 0, v146, vcc
	v_add_f32_e32 v147, v146, v197
	v_add_f32_e32 v147, v145, v147
	v_add_f32_dpp v166, v145, v145 quad_perm:[1,0,3,2] row_mask:0xf bank_mask:0xf bound_ctrl:1
	s_nop 0
	v_add_f32_dpp v164, v147, v147 quad_perm:[1,0,3,2] row_mask:0xf bank_mask:0xf bound_ctrl:1
	v_mov_b32_dpp v167, v166 quad_perm:[2,3,0,1] row_mask:0xf bank_mask:0xf bound_ctrl:1
	v_add_u32_e32 v147, s9, v196
	v_mov_b32_dpp v165, v164 quad_perm:[2,3,0,1] row_mask:0xf bank_mask:0xf bound_ctrl:1
	s_and_saveexec_b64 s[4:5], s[0:1]
	v_add_f32_e32 v164, v164, v165
	v_add_f32_e32 v165, v166, v167
	v_add_u32_e32 v166, 64, v147
	ds_write2st64_b32 v166, v164, v165 offset1:4
	s_or_b64 exec, exec, s[4:5]
	v_fma_f32 v140, v140, s49, -v195
	v_fma_f32 v141, v141, s49, -v195
	v_exp_f32_e32 v140, v140
	v_exp_f32_e32 v141, v141
	v_cmp_lt_i32_e32 vcc, v3, v173
	v_mul_f32_e32 v164, v140, v190
	v_mul_f32_e32 v165, v141, v191
	v_fma_f32 v141, v142, s49, -v195
	v_exp_f32_e32 v142, v141
	v_fma_f32 v141, v143, s49, -v195
	v_exp_f32_e32 v143, v141
	v_cndmask_b32_e32 v140, 0, v165, vcc
	v_cmp_lt_i32_e32 vcc, v0, v178
	s_nop 1
	v_cndmask_b32_e32 v141, 0, v164, vcc
	v_add_f32_e32 v164, 0, v141
	v_add_f32_e32 v166, v140, v164
	v_mul_f32_e32 v164, v142, v190
	v_mul_f32_e32 v165, v143, v191
	v_cmp_lt_i32_e32 vcc, v3, v177
	s_nop 1
	v_cndmask_b32_e32 v142, 0, v165, vcc
	v_cmp_lt_i32_e32 vcc, v0, v180
	s_nop 1
	v_cndmask_b32_e32 v143, 0, v164, vcc
	v_add_f32_e32 v164, v143, v166
	v_add_f32_e32 v164, v142, v164
	v_add_f32_dpp v166, v142, v142 quad_perm:[1,0,3,2] row_mask:0xf bank_mask:0xf bound_ctrl:1
	s_nop 0
	v_add_f32_dpp v164, v164, v164 quad_perm:[1,0,3,2] row_mask:0xf bank_mask:0xf bound_ctrl:1
	v_mov_b32_dpp v167, v166 quad_perm:[2,3,0,1] row_mask:0xf bank_mask:0xf bound_ctrl:1
	s_nop 0
	v_mov_b32_dpp v165, v164 quad_perm:[2,3,0,1] row_mask:0xf bank_mask:0xf bound_ctrl:1
	s_and_saveexec_b64 s[4:5], s[0:1]
	v_add_f32_e32 v164, v164, v165
	v_add_f32_e32 v165, v166, v167
	v_add_u32_e32 v166, 0x50, v147
	ds_write2st64_b32 v166, v164, v165 offset1:4
	s_or_b64 exec, exec, s[4:5]
	v_fma_f32 v136, v136, s49, -v195
	v_fma_f32 v137, v137, s49, -v195
	v_exp_f32_e32 v136, v136
	v_exp_f32_e32 v137, v137
	v_cmp_lt_i32_e32 vcc, v3, v179
	v_mul_f32_e32 v164, v136, v190
	v_mul_f32_e32 v165, v137, v191
	v_fma_f32 v137, v138, s49, -v195
	v_exp_f32_e32 v138, v137
	v_fma_f32 v137, v139, s49, -v195
	v_exp_f32_e32 v139, v137
	v_cndmask_b32_e32 v136, 0, v165, vcc
	v_cmp_lt_i32_e32 vcc, v0, v182
	s_nop 1
	v_cndmask_b32_e32 v137, 0, v164, vcc
	v_add_f32_e32 v164, 0, v137
	v_add_f32_e32 v166, v136, v164
	v_mul_f32_e32 v164, v138, v190
	v_mul_f32_e32 v165, v139, v191
	v_cmp_lt_i32_e32 vcc, v3, v181
	s_nop 1
	v_cndmask_b32_e32 v138, 0, v165, vcc
	v_cmp_lt_i32_e32 vcc, v0, v184
	s_nop 1
	v_cndmask_b32_e32 v139, 0, v164, vcc
	v_add_f32_e32 v164, v139, v166
	v_add_f32_e32 v164, v138, v164
	v_add_f32_dpp v166, v138, v138 quad_perm:[1,0,3,2] row_mask:0xf bank_mask:0xf bound_ctrl:1
	s_nop 0
	v_add_f32_dpp v164, v164, v164 quad_perm:[1,0,3,2] row_mask:0xf bank_mask:0xf bound_ctrl:1
	v_mov_b32_dpp v167, v166 quad_perm:[2,3,0,1] row_mask:0xf bank_mask:0xf bound_ctrl:1
	s_nop 0
	v_mov_b32_dpp v165, v164 quad_perm:[2,3,0,1] row_mask:0xf bank_mask:0xf bound_ctrl:1
	s_and_saveexec_b64 s[4:5], s[0:1]
	v_add_f32_e32 v164, v164, v165
	v_add_f32_e32 v165, v166, v167
	v_add_u32_e32 v166, 0x60, v147
	ds_write2st64_b32 v166, v164, v165 offset1:4
	s_or_b64 exec, exec, s[4:5]
	v_fma_f32 v132, v132, s49, -v195
	v_fma_f32 v133, v133, s49, -v195
	v_exp_f32_e32 v132, v132
	v_exp_f32_e32 v133, v133
	v_cmp_lt_i32_e32 vcc, v3, v183
	v_mul_f32_e32 v164, v132, v190
	v_mul_f32_e32 v165, v133, v191
	v_fma_f32 v133, v134, s49, -v195
	v_exp_f32_e32 v134, v133
	v_fma_f32 v133, v135, s49, -v195
	v_exp_f32_e32 v135, v133
	v_cndmask_b32_e32 v132, 0, v165, vcc
	v_cmp_lt_i32_e32 vcc, v0, v186
	v_mul_f32_e32 v134, v134, v190
	v_mul_f32_e32 v135, v135, v191
	s_nop 0
	v_cndmask_b32_e32 v133, 0, v164, vcc
	v_cmp_lt_i32_e32 vcc, v3, v185
	v_add_f32_e32 v164, 0, v133
	v_add_f32_e32 v164, v132, v164
	v_cndmask_b32_e32 v3, 0, v135, vcc
	v_cmp_lt_i32_e32 vcc, v0, v188
	s_nop 1
	v_cndmask_b32_e32 v0, 0, v134, vcc
	v_add_f32_e32 v134, v0, v164
	v_add_f32_e32 v134, v3, v134
	v_add_f32_dpp v164, v3, v3 quad_perm:[1,0,3,2] row_mask:0xf bank_mask:0xf bound_ctrl:1
	s_nop 0
	v_add_f32_dpp v134, v134, v134 quad_perm:[1,0,3,2] row_mask:0xf bank_mask:0xf bound_ctrl:1
	v_mov_b32_dpp v165, v164 quad_perm:[2,3,0,1] row_mask:0xf bank_mask:0xf bound_ctrl:1
	s_nop 0
	v_mov_b32_dpp v135, v134 quad_perm:[2,3,0,1] row_mask:0xf bank_mask:0xf bound_ctrl:1
	s_and_saveexec_b64 s[4:5], s[0:1]
	v_add_f32_e32 v134, v134, v135
	v_add_f32_e32 v135, v164, v165
	v_add_u32_e32 v147, 0x70, v147
	ds_write2st64_b32 v147, v134, v135 offset1:4
	s_or_b64 exec, exec, s[4:5]
	v_cvt_pk_bf16_f32 v144, v144, v2
	v_cvt_pk_bf16_f32 v145, v146, v145
	v_cvt_pk_bf16_f32 v146, v141, v140
	v_cvt_pk_bf16_f32 v147, v143, v142
	s_nop 1
	v_mfma_f32_16x16x32_bf16 v[140:143], v[36:39], v[144:147], v[148:151]
	v_mfma_f32_16x16x32_bf16 v[148:151], v[40:43], v[144:147], v[152:155]
	v_mfma_f32_16x16x32_bf16 v[152:155], v[44:47], v[144:147], v[156:159]
	v_mfma_f32_16x16x32_bf16 v[156:159], v[48:51], v[144:147], v[160:163]
	s_nop 2
	v_cvt_pk_bf16_f32 v160, v137, v136
	v_cvt_pk_bf16_f32 v161, v139, v138
	v_cvt_pk_bf16_f32 v162, v133, v132
	v_cvt_pk_bf16_f32 v163, v0, v3
	s_nop 1
	v_mfma_f32_16x16x32_bf16 v[144:147], v[52:55], v[160:163], v[140:143]
	v_mfma_f32_16x16x32_bf16 v[140:143], v[56:59], v[160:163], v[148:151]
	v_mfma_f32_16x16x32_bf16 v[136:139], v[60:63], v[160:163], v[152:155]
	v_mfma_f32_16x16x32_bf16 v[132:135], v[64:67], v[160:163], v[156:159]
	s_addk_i32 s2, 0x2000
	s_add_i32 s4, s8, 2
	s_cmp_ge_i32 s8, s30
	s_cbranch_scc0 .LBB0_635
	s_branch .LBB0_648

; template <bool MASK>
; __device__ __forceinline__ void online_chunk(const KV& b, int base, int lo, int hi, const bf16x8* qst, int fq, float& m,
;                                              float& l, f32x4 (&oacc)[4], const int lane) {
;   f32x4 s[4];
;   qk_from(b, qst, s);
;   float cm = NEGF;
;   const int klo = lo - base - fq * 4, khi = hi - base - fq * 4;
; #pragma unroll
;   for (int tile = 0; tile < 4; ++tile)
; #pragma unroll
;     for (int j = 0; j < 4; ++j) {
;       float v = s[tile][j];
;       if (MASK) { const bool ok = (tile * 16 + j >= klo) && (tile * 16 + j <= khi); v = ok ? v : NEGF; }
;       cm = fmaxf(cm, v);
;     }
;   cm = rows_max(cm);
;   const float mn = fmaxf(m, cm * SC_LOG2);
;   const float alpha = __builtin_amdgcn_exp2f(m - mn);
;   float ls = 0.f;
; #pragma unroll
;   for (int tile = 0; tile < 4; ++tile)
; #pragma unroll
;     for (int j = 0; j < 4; ++j) {
;       float pp = __builtin_amdgcn_exp2f(__builtin_fmaf(s[tile][j], SC_LOG2, -mn));
;       if (MASK) { const bool ok = (tile * 16 + j >= klo) && (tile * 16 + j <= khi); pp = ok ? pp : 0.f; }
;       s[tile][j] = pp;
;       ls += pp;
;     }
;   ls = rows_sum(ls);
;   l = l * alpha + ls;
;   m = mn;
; #pragma unroll
;   for (int dt = 0; dt < 4; ++dt) oacc[dt] *= alpha;
;   pv_from(b, s, oacc);
; }
.LBB0_707:
	s_andn2_b64 vcc, exec, s[62:63]
	s_cbranch_vccnz .LBB0_709
	s_waitcnt lgkmcnt(1)
	ds_read_b128 v[148:151], v2 offset:12288
	s_waitcnt lgkmcnt(1)
	ds_read_b128 v[152:155], v2 offset:13312
	s_waitcnt vmcnt(15) lgkmcnt(1)
	v_mfma_f32_16x16x32_bf16 v[168:171], v[4:7], v[148:151], 0
	s_waitcnt vmcnt(13)
	v_mfma_f32_16x16x32_bf16 v[172:175], v[12:15], v[148:151], 0
	s_waitcnt lgkmcnt(0)
	v_mfma_f32_16x16x32_bf16 v[168:171], v[8:11], v[152:155], v[168:171]
	s_waitcnt vmcnt(11)
	v_mfma_f32_16x16x32_bf16 v[176:179], v[20:23], v[148:151], 0
	v_mfma_f32_16x16x32_bf16 v[172:175], v[16:19], v[152:155], v[172:175]
	s_nop 4
	v_max3_f32 v0, v168, s37, v169
	v_max3_f32 v0, v0, v170, v171
	s_waitcnt vmcnt(9)
	v_mfma_f32_16x16x32_bf16 v[148:151], v[28:31], v[148:151], 0
	v_mfma_f32_16x16x32_bf16 v[176:179], v[24:27], v[152:155], v[176:179]
	v_max3_f32 v0, v0, v172, v173
	v_max3_f32 v0, v0, v174, v175
	s_waitcnt vmcnt(8)
	v_mfma_f32_16x16x32_bf16 v[148:151], v[32:35], v[152:155], v[148:151]
	s_nop 3
	v_max3_f32 v0, v0, v176, v177
	v_max3_f32 v0, v0, v178, v179
	s_nop 1
	v_max3_f32 v0, v0, v148, v149
	v_max3_f32 v0, v0, v150, v151
	v_mov_b32_e32 v152, v0
	s_nop 1
	v_permlane16_swap_b32_e32 v0, v152
	v_max_f32_e32 v152, v152, v152
	v_max_f32_e32 v0, v0, v0
	v_max_f32_e32 v0, v0, v152
	v_mov_b32_e32 v152, v0
	s_nop 1
	v_permlane32_swap_b32_e32 v0, v152
	v_max_f32_e32 v152, v152, v152
	v_max_f32_e32 v0, v0, v0
	v_max_f32_e32 v0, v0, v152
	v_mul_f32_e32 v0, 0x3e38aa3b, v0
	v_max_f32_e32 v152, v166, v166
	v_max_f32_e32 v152, v152, v0
	v_fma_f32 v153, v168, s49, -v152
	v_exp_f32_e32 v153, v153
	v_fma_f32 v155, v169, s49, -v152
	v_exp_f32_e32 v155, v155
	v_fma_f32 v157, v170, s49, -v152
	v_exp_f32_e32 v157, v157
	v_fma_f32 v158, v171, s49, -v152
	v_exp_f32_e32 v158, v158
	v_fma_f32 v159, v172, s49, -v152
	v_add_f32_e32 v154, 0, v153
	v_exp_f32_e32 v159, v159
	v_fma_f32 v161, v173, s49, -v152
	v_add_f32_e32 v154, v155, v154
	v_exp_f32_e32 v161, v161
	v_fma_f32 v162, v174, s49, -v152
	v_add_f32_e32 v154, v157, v154
	v_exp_f32_e32 v162, v162
	v_fma_f32 v163, v175, s49, -v152
	v_sub_f32_e32 v0, v166, v152
	v_add_f32_e32 v154, v158, v154
	v_exp_f32_e32 v163, v163
	v_fma_f32 v166, v176, s49, -v152
	v_add_f32_e32 v154, v159, v154
	v_exp_f32_e32 v166, v166
	v_fma_f32 v168, v177, s49, -v152
	v_add_f32_e32 v154, v161, v154
	v_exp_f32_e32 v168, v168
	v_fma_f32 v169, v178, s49, -v152
	v_add_f32_e32 v154, v162, v154
	v_exp_f32_e32 v169, v169
	v_fma_f32 v170, v179, s49, -v152
	v_add_f32_e32 v154, v163, v154
	v_exp_f32_e32 v170, v170
	v_fma_f32 v148, v148, s49, -v152
	v_add_f32_e32 v154, v166, v154
	v_exp_f32_e32 v171, v148
	v_add_f32_e32 v154, v168, v154
	v_add_f32_e32 v154, v169, v154
	v_add_f32_e32 v154, v170, v154
	v_fma_f32 v149, v149, s49, -v152
	v_add_f32_e32 v148, v171, v154
	v_exp_f32_e32 v154, v149
	v_fma_f32 v149, v150, s49, -v152
	v_exp_f32_e32 v172, v149
	v_fma_f32 v149, v151, s49, -v152
	v_exp_f32_e32 v173, v149
	v_add_f32_e32 v148, v154, v148
	v_add_f32_e32 v148, v172, v148
	v_exp_f32_e32 v0, v0
	v_add_f32_e32 v148, v173, v148
	v_mov_b32_e32 v149, v148
	s_nop 1
	v_permlane16_swap_b32_e32 v148, v149
	v_add_f32_e32 v148, v148, v149
	v_mov_b32_e32 v149, v148
	s_nop 1
	v_permlane32_swap_b32_e32 v148, v149
	v_add_f32_e32 v174, v148, v149
	v_mul_f32_e32 v102, v0, v102
	v_mul_f32_e32 v103, v0, v103
	v_mul_f32_e32 v100, v0, v100
	v_mul_f32_e32 v101, v0, v101
	v_mul_f32_e32 v106, v0, v106
	v_mul_f32_e32 v107, v0, v107
	v_mul_f32_e32 v104, v0, v104
	v_mul_f32_e32 v105, v0, v105
	v_mul_f32_e32 v110, v0, v110
	v_mul_f32_e32 v111, v0, v111
	v_mul_f32_e32 v108, v0, v108
	v_mul_f32_e32 v109, v0, v109
	v_mul_f32_e32 v114, v0, v114
	v_mul_f32_e32 v115, v0, v115
	v_mul_f32_e32 v112, v0, v112
	v_mul_f32_e32 v113, v0, v113
	v_cvt_pk_bf16_f32 v148, v153, v155
	v_cvt_pk_bf16_f32 v149, v157, v158
	v_cvt_pk_bf16_f32 v150, v159, v161
	v_cvt_pk_bf16_f32 v151, v162, v163
	v_fmac_f32_e32 v174, v167, v0
	v_mov_b32_e32 v167, v174
	s_waitcnt vmcnt(7)
	v_mfma_f32_16x16x32_bf16 v[100:103], v[36:39], v[148:151], v[100:103]
	s_waitcnt vmcnt(6)
	v_mfma_f32_16x16x32_bf16 v[104:107], v[40:43], v[148:151], v[104:107]
	s_waitcnt vmcnt(5)
	v_mfma_f32_16x16x32_bf16 v[108:111], v[44:47], v[148:151], v[108:111]
	s_waitcnt vmcnt(4)
	v_mfma_f32_16x16x32_bf16 v[112:115], v[48:51], v[148:151], v[112:115]
	v_cvt_pk_bf16_f32 v148, v166, v168
	v_cvt_pk_bf16_f32 v149, v169, v170
	v_cvt_pk_bf16_f32 v150, v171, v154
	v_cvt_pk_bf16_f32 v151, v172, v173
	v_mov_b32_e32 v166, v152
	s_waitcnt vmcnt(3)
	v_mfma_f32_16x16x32_bf16 v[100:103], v[52:55], v[148:151], v[100:103]
	s_waitcnt vmcnt(2)
	v_mfma_f32_16x16x32_bf16 v[104:107], v[56:59], v[148:151], v[104:107]
	s_waitcnt vmcnt(1)
	v_mfma_f32_16x16x32_bf16 v[108:111], v[60:63], v[148:151], v[108:111]
	s_waitcnt vmcnt(0)
	v_mfma_f32_16x16x32_bf16 v[112:115], v[64:67], v[148:151], v[112:115]
; template <bool MASK>
; __device__ __forceinline__ void online_chunk(const KV& b, int base, int lo, int hi, const bf16x8* qst, int fq, float& m,
;                                              float& l, f32x4 (&oacc)[4], const int lane) {
;   f32x4 s[4];
;   qk_from(b, qst, s);
;   float cm = NEGF;
;   const int klo = lo - base - fq * 4, khi = hi - base - fq * 4;
; #pragma unroll
;   for (int tile = 0; tile < 4; ++tile)
; #pragma unroll
;     for (int j = 0; j < 4; ++j) {
;       float v = s[tile][j];
;       if (MASK) { const bool ok = (tile * 16 + j >= klo) && (tile * 16 + j <= khi); v = ok ? v : NEGF; }
;       cm = fmaxf(cm, v);
;     }
;   cm = rows_max(cm);
;   const float mn = fmaxf(m, cm * SC_LOG2);
;   const float alpha = __builtin_amdgcn_exp2f(m - mn);
;   float ls = 0.f;
; #pragma unroll
;   for (int tile = 0; tile < 4; ++tile)
; #pragma unroll
;     for (int j = 0; j < 4; ++j) {
;       float pp = __builtin_amdgcn_exp2f(__builtin_fmaf(s[tile][j], SC_LOG2, -mn));
;       if (MASK) { const bool ok = (tile * 16 + j >= klo) && (tile * 16 + j <= khi); pp = ok ? pp : 0.f; }
;       s[tile][j] = pp;
;       ls += pp;
;     }
;   ls = rows_sum(ls);
;   l = l * alpha + ls;
;   m = mn;
; #pragma unroll
;   for (int dt = 0; dt < 4; ++dt) oacc[dt] *= alpha;
;   pv_from(b, s, oacc);
; }
.LBB0_709:
	s_and_b64 vcc, exec, s[0:1]
	s_cbranch_vccnz .LBB0_711
	s_waitcnt lgkmcnt(1)
	ds_read_b128 v[148:151], v2 offset:12288
	s_waitcnt lgkmcnt(1)
	ds_read_b128 v[152:155], v2 offset:13312
	s_lshl_b32 s0, s58, 6
	v_lshl_add_u32 v0, v156, 2, s0
	v_cmp_gt_i32_e64 s[0:1], -1, v0
	s_waitcnt vmcnt(15) lgkmcnt(1)
	v_mfma_f32_16x16x32_bf16 v[120:123], v[120:123], v[148:151], 0
	s_waitcnt vmcnt(13)
	v_mfma_f32_16x16x32_bf16 v[116:119], v[116:119], v[148:151], 0
	s_waitcnt lgkmcnt(0)
	v_mfma_f32_16x16x32_bf16 v[120:123], v[124:127], v[152:155], v[120:123]
	s_waitcnt vmcnt(12)
	v_mfma_f32_16x16x32_bf16 v[124:127], v[128:131], v[152:155], v[116:119]
	s_waitcnt vmcnt(11)
	v_mfma_f32_16x16x32_bf16 v[116:119], v[132:135], v[148:151], 0
	v_sub_u32_e32 v132, v165, v0
	v_cmp_gt_i32_e64 s[2:3], 1, v132
	s_or_b64 s[20:21], s[0:1], s[2:3]
	v_cmp_gt_i32_e64 s[0:1], -2, v0
	v_cmp_gt_i32_e64 s[2:3], 2, v132
	s_or_b64 s[28:29], s[0:1], s[2:3]
	v_cmp_gt_i32_e64 s[0:1], -3, v0
	v_cmp_gt_i32_e64 s[2:3], 3, v132
	s_or_b64 s[18:19], s[0:1], s[2:3]
	v_cmp_gt_i32_e64 s[0:1], -16, v0
	v_cmp_gt_i32_e64 s[2:3], 16, v132
	s_or_b64 s[26:27], s[0:1], s[2:3]
	s_movk_i32 s0, 0xffef
	v_cmp_gt_i32_e64 s[0:1], s0, v0
	v_cmp_gt_i32_e64 s[2:3], 17, v132
	s_or_b64 s[22:23], s[0:1], s[2:3]
	s_movk_i32 s0, 0xffee
	v_cmp_gt_i32_e64 s[0:1], s0, v0
	v_cmp_gt_i32_e64 s[2:3], 18, v132
	s_or_b64 s[24:25], s[0:1], s[2:3]
	s_movk_i32 s0, 0xffed
	v_cmp_gt_i32_e64 s[0:1], s0, v0
	v_cmp_gt_i32_e64 s[2:3], 19, v132
	s_or_b64 s[10:11], s[0:1], s[2:3]
	s_movk_i32 s0, 0xffe0
	v_cmp_gt_i32_e64 s[0:1], s0, v0
	v_cmp_gt_i32_e64 s[2:3], 32, v132
	s_or_b64 s[16:17], s[0:1], s[2:3]
	s_movk_i32 s0, 0xffdf
	v_cmp_gt_i32_e64 s[0:1], s0, v0
	v_cmp_gt_i32_e64 s[2:3], 33, v132
	s_or_b64 s[12:13], s[0:1], s[2:3]
	s_movk_i32 s0, 0xffde
	v_cmp_gt_i32_e64 s[0:1], s0, v0
	v_cmp_gt_i32_e64 s[2:3], 34, v132
	s_or_b64 s[14:15], s[0:1], s[2:3]
	s_movk_i32 s0, 0xffdd
	v_or_b32_e32 v133, v132, v0
	v_cmp_gt_i32_e64 s[0:1], s0, v0
	v_cmp_gt_i32_e64 s[2:3], 35, v132
	s_waitcnt vmcnt(10)
	v_mfma_f32_16x16x32_bf16 v[128:131], v[136:139], v[152:155], v[116:119]
	v_cmp_lt_i32_e32 vcc, -1, v133
	v_max_f32_e32 v133, v120, v120
	s_or_b64 s[2:3], s[0:1], s[2:3]
	s_waitcnt vmcnt(9)
	v_mfma_f32_16x16x32_bf16 v[116:119], v[140:143], v[148:151], 0
	s_movk_i32 s0, 0xffd0
	v_max_f32_e32 v133, 0xf149f2ca, v133
	v_cndmask_b32_e64 v134, v121, v217, s[20:21]
	v_cmp_gt_i32_e64 s[0:1], s0, v0
	v_cmp_gt_i32_e64 s[4:5], 48, v132
	v_cndmask_b32_e32 v133, v217, v133, vcc
	v_max_f32_e32 v134, v134, v134
	s_or_b64 s[8:9], s[0:1], s[4:5]
	s_movk_i32 s0, 0xffcf
	v_max_f32_e32 v133, v133, v134
	v_cndmask_b32_e64 v134, v122, v217, s[28:29]
	v_cndmask_b32_e64 v135, v123, v217, s[18:19]
	v_cmp_gt_i32_e64 s[0:1], s0, v0
	v_cmp_gt_i32_e64 s[4:5], 49, v132
	s_waitcnt vmcnt(8)
	v_mfma_f32_16x16x32_bf16 v[116:119], v[144:147], v[152:155], v[116:119]
	v_max3_f32 v133, v133, v134, v135
	v_cndmask_b32_e64 v134, v124, v217, s[26:27]
	v_cndmask_b32_e64 v135, v125, v217, s[22:23]
	s_or_b64 s[4:5], s[0:1], s[4:5]
	s_movk_i32 s0, 0xffce
	v_max3_f32 v133, v133, v134, v135
	v_cndmask_b32_e64 v134, v126, v217, s[24:25]
	v_cndmask_b32_e64 v135, v127, v217, s[10:11]
	v_cmp_gt_i32_e64 s[0:1], s0, v0
	v_cmp_gt_i32_e64 s[6:7], 50, v132
	v_max3_f32 v133, v133, v134, v135
	v_cndmask_b32_e64 v134, v128, v217, s[16:17]
	v_cndmask_b32_e64 v135, v129, v217, s[12:13]
	s_or_b64 s[6:7], s[0:1], s[6:7]
	s_movk_i32 s0, 0xffcd
	v_max3_f32 v133, v133, v134, v135
	v_cndmask_b32_e64 v134, v130, v217, s[14:15]
	v_cndmask_b32_e64 v135, v131, v217, s[2:3]
	v_cmp_gt_i32_e64 s[0:1], s0, v0
	v_cmp_gt_i32_e64 s[34:35], 51, v132
	v_max3_f32 v133, v133, v134, v135
	v_cndmask_b32_e64 v134, v116, v217, s[8:9]
	v_cndmask_b32_e64 v135, v117, v217, s[4:5]
	s_or_b64 s[0:1], s[0:1], s[34:35]
	v_max3_f32 v133, v133, v134, v135
	v_cndmask_b32_e64 v134, v118, v217, s[6:7]
	v_cndmask_b32_e64 v0, v119, v217, s[0:1]
	v_max3_f32 v0, v133, v134, v0
	v_mov_b32_e32 v132, v0
	s_nop 1
	v_permlane16_swap_b32_e32 v0, v132
	v_max_f32_e32 v132, v132, v132
	v_max_f32_e32 v0, v0, v0
	v_max_f32_e32 v0, v0, v132
	v_mov_b32_e32 v132, v0
	s_nop 1
	v_permlane32_swap_b32_e32 v0, v132
	v_max_f32_e32 v132, v132, v132
	v_max_f32_e32 v0, v0, v0
	v_max_f32_e32 v0, v0, v132
	v_mul_f32_e32 v0, 0x3e38aa3b, v0
	v_max_f32_e32 v132, v166, v166
	v_max_f32_e32 v132, v132, v0
	v_fma_f32 v0, v120, s49, -v132
	v_exp_f32_e32 v0, v0
	s_nop 0
	v_cndmask_b32_e32 v120, 0, v0, vcc
	v_fma_f32 v0, v121, s49, -v132
	v_exp_f32_e32 v0, v0
	s_nop 0
	v_cndmask_b32_e64 v121, v0, 0, s[20:21]
	v_fma_f32 v0, v122, s49, -v132
	v_exp_f32_e32 v0, v0
	s_nop 0
	v_cndmask_b32_e64 v122, v0, 0, s[28:29]
	v_fma_f32 v0, v123, s49, -v132
	v_exp_f32_e32 v0, v0
	s_nop 0
	v_cndmask_b32_e64 v123, v0, 0, s[18:19]
	v_fma_f32 v0, v124, s49, -v132
	v_exp_f32_e32 v0, v0
	s_nop 0
	v_cndmask_b32_e64 v124, v0, 0, s[26:27]
	v_fma_f32 v0, v125, s49, -v132
	v_exp_f32_e32 v0, v0
	s_nop 0
	v_cndmask_b32_e64 v125, v0, 0, s[22:23]
	v_fma_f32 v0, v126, s49, -v132
	v_exp_f32_e32 v0, v0
	s_nop 0
	v_cndmask_b32_e64 v126, v0, 0, s[24:25]
	v_fma_f32 v0, v127, s49, -v132
	v_exp_f32_e32 v0, v0
	s_nop 0
	v_cndmask_b32_e64 v127, v0, 0, s[10:11]
	v_fma_f32 v0, v128, s49, -v132
	v_exp_f32_e32 v0, v0
	s_nop 0
	v_cndmask_b32_e64 v128, v0, 0, s[16:17]
	v_fma_f32 v0, v129, s49, -v132
	v_exp_f32_e32 v0, v0
	s_nop 0
	v_cndmask_b32_e64 v129, v0, 0, s[12:13]
	v_fma_f32 v0, v130, s49, -v132
	v_exp_f32_e32 v0, v0
	s_nop 0
	v_cndmask_b32_e64 v130, v0, 0, s[14:15]
	v_fma_f32 v0, v131, s49, -v132
	v_exp_f32_e32 v0, v0
	s_nop 0
	v_cndmask_b32_e64 v131, v0, 0, s[2:3]
	v_fma_f32 v0, v116, s49, -v132
; __device__ __forceinline__ float bflo(unsigned w) { return __uint_as_float(w << 16); }
; __device__ __forceinline__ float bfhi(unsigned w) { return __uint_as_float(w & 0xffff0000u); }
; #define PSEL(QA, R) (__builtin_amdgcn_readfirstlane(sel[(QA) * 512 + (R)]))
; template <bool MASK>
; __device__ __forceinline__ void online_chunk(const KV& b, int base, int lo, int hi, const bf16x8* qst, int fq, float& m,
;                                              float& l, f32x4 (&oacc)[4], const int lane) {
;     ...
;   for (int tile = 0; tile < 4; ++tile)
; #pragma unroll
;     for (int j = 0; j < 4; ++j) {
;       float pp = __builtin_amdgcn_exp2f(__builtin_fmaf(s[tile][j], SC_LOG2, -mn));
;       if (MASK) { const bool ok = (tile * 16 + j >= klo) && (tile * 16 + j <= khi); pp = ok ? pp : 0.f; }
;       s[tile][j] = pp;
;       ls += pp;
;     }
;   ls = rows_sum(ls);
;   l = l * alpha + ls;
;   m = mn;
; #pragma unroll
;   for (int dt = 0; dt < 4; ++dt) oacc[dt] *= alpha;
;   pv_from(b, s, oacc);
; __device__ __forceinline__ void nsa_quad(const Params& p, int qd, int g, float* slds, const int lane_in) {
;     ...
;     if (npriv > 0) {
;       typedef long l64x2 __attribute__((ext_vector_type(2)));
;       l64x2 kvb[4][4];
;       const char* ks8 = (const char*)(p.ws + OFF_ks8) + (long)g * 256 * 4096;
;       const char* vs8 = (const char*)(p.ws + OFF_vs8) + (long)g * 256 * 4096;
;       long q8_0, q8_1;
;       {
;         const u32x4 qa_ = __builtin_bit_cast(u32x4, qst[0]), qb_ = __builtin_bit_cast(u32x4, qst[64]);
;         const unsigned a0 = pack_fp8x4(bflo(qa_[0]), bfhi(qa_[0]), bflo(qa_[1]), bfhi(qa_[1]));
;         const unsigned a1 = pack_fp8x4(bflo(qa_[2]), bfhi(qa_[2]), bflo(qa_[3]), bfhi(qa_[3]));
;         const unsigned b0 = pack_fp8x4(bflo(qb_[0]), bfhi(qb_[0]), bflo(qb_[1]), bfhi(qb_[1]));
;         const unsigned b1 = pack_fp8x4(bflo(qb_[2]), bfhi(qb_[2]), bflo(qb_[3]), bfhi(qb_[3]));
;         q8_0 = (long)(((unsigned long long)a1 << 32) | (unsigned long long)a0);
;         q8_1 = (long)(((unsigned long long)b1 << 32) | (unsigned long long)b0);
;       }
;     ...
; #pragma unroll
;       for (int qa = 0; qa < 4; ++qa) { const int blk = PSEL(qa, 0); PLOAD8(qa, ks8, blk) }
	v_exp_f32_e32 v0, v0
	v_sub_f32_e32 v116, v166, v132
	v_mov_b32_e32 v166, v132
	v_cndmask_b32_e64 v133, v0, 0, s[8:9]
	v_fma_f32 v0, v117, s49, -v132
	v_exp_f32_e32 v0, v0
	s_nop 0
	v_cndmask_b32_e64 v134, v0, 0, s[4:5]
	v_fma_f32 v0, v118, s49, -v132
	v_exp_f32_e32 v0, v0
	v_cvt_pk_bf16_f32 v118, v124, v125
	v_cndmask_b32_e64 v135, v0, 0, s[6:7]
	v_fma_f32 v0, v119, s49, -v132
	v_exp_f32_e32 v0, v0
	v_cvt_pk_bf16_f32 v119, v126, v127
	v_cndmask_b32_e64 v136, v0, 0, s[0:1]
	v_add_f32_e32 v0, 0, v120
	v_add_f32_e32 v0, v121, v0
	v_add_f32_e32 v0, v122, v0
	v_add_f32_e32 v0, v123, v0
	v_add_f32_e32 v0, v124, v0
	v_add_f32_e32 v0, v125, v0
	v_add_f32_e32 v0, v126, v0
	v_add_f32_e32 v0, v127, v0
	v_add_f32_e32 v0, v128, v0
	v_add_f32_e32 v0, v129, v0
	v_add_f32_e32 v0, v130, v0
	v_add_f32_e32 v0, v131, v0
	v_add_f32_e32 v0, v133, v0
	v_add_f32_e32 v0, v134, v0
	v_add_f32_e32 v0, v135, v0
	v_add_f32_e32 v117, v136, v0
	v_exp_f32_e32 v0, v116
	v_mov_b32_e32 v116, v117
	s_nop 1
	v_permlane16_swap_b32_e32 v117, v116
	v_add_f32_e32 v116, v117, v116
	v_mov_b32_e32 v117, v116
	s_nop 1
	v_permlane32_swap_b32_e32 v116, v117
	v_add_f32_e32 v137, v116, v117
	v_mul_f32_e32 v102, v0, v102
	v_mul_f32_e32 v103, v0, v103
	v_mul_f32_e32 v100, v0, v100
	v_mul_f32_e32 v101, v0, v101
	v_mul_f32_e32 v106, v0, v106
	v_mul_f32_e32 v107, v0, v107
	v_mul_f32_e32 v104, v0, v104
	v_mul_f32_e32 v105, v0, v105
	v_mul_f32_e32 v110, v0, v110
	v_mul_f32_e32 v111, v0, v111
	v_mul_f32_e32 v108, v0, v108
	v_mul_f32_e32 v109, v0, v109
	v_mul_f32_e32 v114, v0, v114
	v_mul_f32_e32 v115, v0, v115
	v_mul_f32_e32 v112, v0, v112
	v_mul_f32_e32 v113, v0, v113
	v_cvt_pk_bf16_f32 v116, v120, v121
	v_cvt_pk_bf16_f32 v117, v122, v123
	v_fmac_f32_e32 v137, v167, v0
	v_mov_b32_e32 v167, v137
	s_waitcnt vmcnt(7)
	v_mfma_f32_16x16x32_bf16 v[96:99], v[96:99], v[116:119], v[100:103]
	s_waitcnt vmcnt(6)
	v_mfma_f32_16x16x32_bf16 v[92:95], v[92:95], v[116:119], v[104:107]
	s_waitcnt vmcnt(5)
	v_mfma_f32_16x16x32_bf16 v[88:91], v[88:91], v[116:119], v[108:111]
	s_waitcnt vmcnt(4)
	v_mfma_f32_16x16x32_bf16 v[80:83], v[80:83], v[116:119], v[112:115]
	s_nop 2
	v_cvt_pk_bf16_f32 v112, v128, v129
	v_cvt_pk_bf16_f32 v113, v130, v131
	v_cvt_pk_bf16_f32 v114, v133, v134
	v_cvt_pk_bf16_f32 v115, v135, v136
	s_waitcnt vmcnt(3)
	s_nop 0
	v_mfma_f32_16x16x32_bf16 v[100:103], v[84:87], v[112:115], v[96:99]
	s_waitcnt vmcnt(2)
	v_mfma_f32_16x16x32_bf16 v[104:107], v[76:79], v[112:115], v[92:95]
	s_waitcnt vmcnt(1)
	v_mfma_f32_16x16x32_bf16 v[108:111], v[72:75], v[112:115], v[88:91]
	s_waitcnt vmcnt(0)
	v_mfma_f32_16x16x32_bf16 v[112:115], v[68:71], v[112:115], v[80:83]
.LBB0_711:
	v_readlane_b32 s0, v255, 57
	v_readlane_b32 s1, v255, 58
	s_sub_i32 s0, s0, s1
	s_min_i32 s12, s0, s91
	s_cmp_lt_i32 s12, 1
	s_cbranch_scc1 .LBB0_726
	v_mov_b32_e32 v0, s76
	s_waitcnt vmcnt(0)
	ds_read_b32 v68, v0
	s_waitcnt lgkmcnt(2)
	ds_read_b128 v[148:151], v2 offset:12288
	s_waitcnt lgkmcnt(2)
	ds_read_b128 v[152:155], v2 offset:13312
	v_mov_b32_e32 v69, v164
	s_waitcnt lgkmcnt(2)
	v_readfirstlane_b32 s0, v68
	ds_read_b32 v84, v0 offset:2048
	s_ashr_i32 s1, s0, 31
	s_lshl_b64 s[0:1], s[0:1], 12
	s_add_u32 s0, s77, s0
	s_addc_u32 s1, s94, s1
	global_load_dwordx4 v[80:83], v69, s[0:1]
	global_load_dwordx4 v[76:79], v69, s[0:1] offset:1024
	global_load_dwordx4 v[72:75], v69, s[0:1] offset:2048
	s_nop 0
	global_load_dwordx4 v[68:71], v69, s[0:1] offset:3072
	s_waitcnt lgkmcnt(0)
	v_readfirstlane_b32 s0, v84
	v_mov_b32_e32 v84, v164
	ds_read_b32 v116, v0 offset:4096
	s_ashr_i32 s1, s0, 31
	s_lshl_b64 s[0:1], s[0:1], 12
	s_add_u32 s0, s77, s0
	s_addc_u32 s1, s94, s1
	global_load_dwordx4 v[96:99], v84, s[0:1]
	global_load_dwordx4 v[92:95], v84, s[0:1] offset:1024
	global_load_dwordx4 v[88:91], v84, s[0:1] offset:2048
	s_nop 0
	global_load_dwordx4 v[84:87], v84, s[0:1] offset:3072
	s_waitcnt lgkmcnt(0)
	v_readfirstlane_b32 s0, v116
	v_mov_b32_e32 v116, v164
	ds_read_b32 v0, v0 offset:6144
	s_ashr_i32 s1, s0, 31
	s_lshl_b64 s[0:1], s[0:1], 12
	s_add_u32 s0, s77, s0
	s_addc_u32 s1, s94, s1
	global_load_dwordx4 v[128:131], v116, s[0:1]
	global_load_dwordx4 v[124:127], v116, s[0:1] offset:1024
	global_load_dwordx4 v[120:123], v116, s[0:1] offset:2048
	s_nop 0
	global_load_dwordx4 v[116:119], v116, s[0:1] offset:3072
	s_waitcnt lgkmcnt(0)
; __device__ __forceinline__ float bflo(unsigned w) { return __uint_as_float(w << 16); }
; __device__ __forceinline__ float bfhi(unsigned w) { return __uint_as_float(w & 0xffff0000u); }
; #define PSEL(QA, R) (__builtin_amdgcn_readfirstlane(sel[(QA) * 512 + (R)]))
; #define PLOAD8(QA, BASE, BLK) { unsigned off_ = loff; asm volatile("" : "+v"(off_)); const char* cb_ = (BASE) + (long)(BLK) * 4096; \
;       _Pragma("unroll") for (int i_ = 0; i_ < 4; ++i_) kvb[QA][i_] = *(const l64x2*)(cb_ + i_ * 1024 + off_); }
; __device__ __forceinline__ void nsa_quad(const Params& p, int qd, int g, float* slds, const int lane_in) {
;     ...
;       long q8_0, q8_1;
;       {
;         const u32x4 qa_ = __builtin_bit_cast(u32x4, qst[0]), qb_ = __builtin_bit_cast(u32x4, qst[64]);
;         const unsigned a0 = pack_fp8x4(bflo(qa_[0]), bfhi(qa_[0]), bflo(qa_[1]), bfhi(qa_[1]));
;         const unsigned a1 = pack_fp8x4(bflo(qa_[2]), bfhi(qa_[2]), bflo(qa_[3]), bfhi(qa_[3]));
;         const unsigned b0 = pack_fp8x4(bflo(qb_[0]), bfhi(qb_[0]), bflo(qb_[1]), bfhi(qb_[1]));
;         const unsigned b1 = pack_fp8x4(bflo(qb_[2]), bfhi(qb_[2]), bflo(qb_[3]), bfhi(qb_[3]));
;         q8_0 = (long)(((unsigned long long)a1 << 32) | (unsigned long long)a0);
;         q8_1 = (long)(((unsigned long long)b1 << 32) | (unsigned long long)b0);
;       }
;     ...
; #pragma unroll
;       for (int qa = 0; qa < 4; ++qa) { const int blk = PSEL(qa, 0); PLOAD8(qa, ks8, blk) }
; #pragma unroll
;       for (int dt = 0; dt < 4; ++dt) oacc[dt] *= 256.f;
;       for (int r = 0; r < npriv; ++r) {
;         f32x4 sc[4];
; #pragma unroll
;         for (int tile = 0; tile < 4; ++tile) sc[tile] = f32x4{0.f, 0.f, 0.f, 0.f};
; #pragma unroll
;         for (int qa = 0; qa < 4; ++qa) {
;           const bool mine = (qi == qa);
;           const long qm0 = mine ? q8_0 : 0L, qm1 = mine ? q8_1 : 0L;
; #pragma unroll
;           for (int tile = 0; tile < 4; ++tile) {
;             sc[tile] = __builtin_amdgcn_mfma_f32_16x16x32_fp8_fp8(kvb[qa][tile][0], qm0, sc[tile], 0, 0, 0);
;             sc[tile] = __builtin_amdgcn_mfma_f32_16x16x32_fp8_fp8(kvb[qa][tile][1], qm1, sc[tile], 0, 0, 0);
;           }
;           const int blk = PSEL(qa, r);
;           __builtin_amdgcn_sched_barrier(0);
;           PLOAD8(qa, vs8, blk)
	v_readfirstlane_b32 s0, v0
	s_ashr_i32 s1, s0, 31
	s_lshl_b64 s[0:1], s[0:1], 12
	v_mov_b32_e32 v0, v164
	s_add_u32 s0, s77, s0
	s_addc_u32 s1, s94, s1
	global_load_dwordx4 v[132:135], v0, s[0:1] offset:3072
	global_load_dwordx4 v[136:139], v0, s[0:1] offset:2048
	global_load_dwordx4 v[140:143], v0, s[0:1] offset:1024
	global_load_dwordx4 v[144:147], v0, s[0:1]
	v_lshlrev_b32_e32 v0, 16, v148
	v_and_b32_e32 v148, 0xffff0000, v148
	v_mov_b32_e32 v162, v1
	v_cvt_pk_fp8_f32 v162, v0, v148
	v_lshlrev_b32_e32 v0, 16, v150
	v_and_b32_e32 v148, 0xffff0000, v150
	v_mov_b32_e32 v161, v1
	v_cvt_pk_fp8_f32 v161, v0, v148
	v_lshlrev_b32_e32 v0, 16, v151
	v_and_b32_e32 v148, 0xffff0000, v151
	v_mov_b32_e32 v168, v1
	v_cvt_pk_fp8_f32 v161, v0, v148 op_sel:[0,0,1]
	v_lshlrev_b32_e32 v0, 16, v152
	v_and_b32_e32 v148, 0xffff0000, v152
	v_cvt_pk_fp8_f32 v168, v0, v148
	v_lshlrev_b32_e32 v0, 16, v154
	v_and_b32_e32 v148, 0xffff0000, v154
	v_mov_b32_e32 v163, v1
	v_cvt_pk_fp8_f32 v163, v0, v148
	v_lshlrev_b32_e32 v156, 16, v149
	v_and_b32_e32 v149, 0xffff0000, v149
	v_cvt_pk_fp8_f32 v162, v156, v149 op_sel:[0,0,1]
	v_lshlrev_b32_e32 v149, 16, v153
	v_and_b32_e32 v150, 0xffff0000, v153
	v_lshlrev_b32_e32 v0, 16, v155
	v_and_b32_e32 v148, 0xffff0000, v155
	v_cvt_pk_fp8_f32 v168, v149, v150 op_sel:[0,0,1]
	v_cvt_pk_fp8_f32 v163, v0, v148 op_sel:[0,0,1]
	s_mov_b32 s0, 0x43800000
	v_mul_f32_e32 v114, s0, v114
	v_mul_f32_e32 v115, s0, v115
	v_mul_f32_e32 v112, s0, v112
	v_mul_f32_e32 v113, s0, v113
	v_mul_f32_e32 v110, s0, v110
	v_mul_f32_e32 v111, s0, v111
	v_mul_f32_e32 v108, s0, v108
	v_mul_f32_e32 v109, s0, v109
	v_mul_f32_e32 v106, s0, v106
	v_mul_f32_e32 v107, s0, v107
	v_mul_f32_e32 v104, s0, v104
	v_mul_f32_e32 v105, s0, v105
	v_mul_f32_e32 v102, s0, v102
	v_mul_f32_e32 v103, s0, v103
	v_mul_f32_e32 v100, s0, v100
	v_mul_f32_e32 v101, s0, v101
	v_cmp_eq_u32_e64 s[0:1], 0, v160
	v_cmp_eq_u32_e64 s[2:3], 1, v160
	v_cmp_eq_u32_e64 s[4:5], 2, v160
	v_cmp_eq_u32_e64 s[6:7], 3, v160
	v_cndmask_b32_e64 v149, 0, v161, s[0:1]
	v_cndmask_b32_e64 v148, 0, v162, s[0:1]
	v_cndmask_b32_e64 v151, 0, v163, s[0:1]
	v_cndmask_b32_e64 v150, 0, v168, s[0:1]
	v_cndmask_b32_e64 v153, 0, v161, s[2:3]
	v_cndmask_b32_e64 v152, 0, v162, s[2:3]
	v_cndmask_b32_e64 v155, 0, v163, s[2:3]
	v_cndmask_b32_e64 v154, 0, v168, s[2:3]
	v_cndmask_b32_e64 v157, 0, v161, s[4:5]
	v_cndmask_b32_e64 v156, 0, v162, s[4:5]
	v_cndmask_b32_e64 v159, 0, v163, s[4:5]
	v_cndmask_b32_e64 v158, 0, v168, s[4:5]
	v_cndmask_b32_e64 v161, 0, v161, s[6:7]
	v_cndmask_b32_e64 v160, 0, v162, s[6:7]
	v_cndmask_b32_e64 v163, 0, v163, s[6:7]
	v_cndmask_b32_e64 v162, 0, v168, s[6:7]
	s_mov_b32 s13, 0
	s_mov_b32 s14, s76
	v_readlane_b32 s88, v253, 37
	v_readlane_b32 s89, v253, 38
	v_readlane_b32 s91, v255, 54
.LBB0_713:
	s_waitcnt vmcnt(15)
	v_mfma_f32_16x16x32_fp8_fp8 v[168:171], v[80:81], v[148:149], 0
	v_mov_b32_e32 v0, s14
	v_mfma_f32_16x16x32_fp8_fp8 v[168:171], v[82:83], v[150:151], v[168:171]
	s_waitcnt vmcnt(14)
	v_mfma_f32_16x16x32_fp8_fp8 v[80:83], v[76:77], v[148:149], 0
	v_mfma_f32_16x16x32_fp8_fp8 v[172:175], v[78:79], v[150:151], v[80:83]
	s_waitcnt vmcnt(13)
	v_mfma_f32_16x16x32_fp8_fp8 v[76:79], v[72:73], v[148:149], 0
	v_mfma_f32_16x16x32_fp8_fp8 v[176:179], v[74:75], v[150:151], v[76:79]
	s_waitcnt vmcnt(12)
	v_mfma_f32_16x16x32_fp8_fp8 v[72:75], v[68:69], v[148:149], 0
	ds_read_b32 v68, v0
	s_waitcnt lgkmcnt(0)
	v_readfirstlane_b32 s8, v68
	v_mfma_f32_16x16x32_fp8_fp8 v[180:183], v[70:71], v[150:151], v[72:75]
	s_ashr_i32 s9, s8, 31
	s_lshl_b64 s[8:9], s[8:9], 12
	v_mov_b32_e32 v68, v164
	s_add_u32 s8, s95, s8
	s_addc_u32 s9, s51, s9
	global_load_dwordx4 v[80:83], v68, s[8:9]
	global_load_dwordx4 v[76:79], v68, s[8:9] offset:1024
	global_load_dwordx4 v[72:75], v68, s[8:9] offset:2048
	s_nop 0
	global_load_dwordx4 v[68:71], v68, s[8:9] offset:3072
	s_waitcnt vmcnt(15)
	v_mfma_f32_16x16x32_fp8_fp8 v[168:171], v[96:97], v[152:153], v[168:171]
	v_mfma_f32_16x16x32_fp8_fp8 v[168:171], v[98:99], v[154:155], v[168:171]
	s_waitcnt vmcnt(14)
	v_mfma_f32_16x16x32_fp8_fp8 v[96:99], v[92:93], v[152:153], v[172:175]
	v_mfma_f32_16x16x32_fp8_fp8 v[172:175], v[94:95], v[154:155], v[96:99]
	s_waitcnt vmcnt(13)
	v_mfma_f32_16x16x32_fp8_fp8 v[92:95], v[88:89], v[152:153], v[176:179]
	v_mfma_f32_16x16x32_fp8_fp8 v[176:179], v[90:91], v[154:155], v[92:95]
	s_waitcnt vmcnt(12)
	v_mfma_f32_16x16x32_fp8_fp8 v[88:91], v[84:85], v[152:153], v[180:183]
	ds_read_b32 v84, v0 offset:2048
	s_waitcnt lgkmcnt(0)
	v_readfirstlane_b32 s8, v84
	v_mfma_f32_16x16x32_fp8_fp8 v[180:183], v[86:87], v[154:155], v[88:91]
	s_ashr_i32 s9, s8, 31
	s_lshl_b64 s[8:9], s[8:9], 12
	v_mov_b32_e32 v84, v164
	s_add_u32 s8, s95, s8
	s_addc_u32 s9, s51, s9
	global_load_dwordx4 v[96:99], v84, s[8:9]
	global_load_dwordx4 v[92:95], v84, s[8:9] offset:1024
	global_load_dwordx4 v[88:91], v84, s[8:9] offset:2048
	s_nop 0
	global_load_dwordx4 v[84:87], v84, s[8:9] offset:3072
	s_waitcnt vmcnt(15)
	v_mfma_f32_16x16x32_fp8_fp8 v[168:171], v[128:129], v[156:157], v[168:171]
	v_mfma_f32_16x16x32_fp8_fp8 v[168:171], v[130:131], v[158:159], v[168:171]
	s_waitcnt vmcnt(14)
	v_mfma_f32_16x16x32_fp8_fp8 v[128:131], v[124:125], v[156:157], v[172:175]
	v_mfma_f32_16x16x32_fp8_fp8 v[172:175], v[126:127], v[158:159], v[128:131]
	s_waitcnt vmcnt(13)
	v_mfma_f32_16x16x32_fp8_fp8 v[124:127], v[120:121], v[156:157], v[176:179]
	v_mfma_f32_16x16x32_fp8_fp8 v[176:179], v[122:123], v[158:159], v[124:127]
	s_waitcnt vmcnt(12)
	v_mfma_f32_16x16x32_fp8_fp8 v[120:123], v[116:117], v[156:157], v[180:183]
	ds_read_b32 v116, v0 offset:4096
	s_waitcnt lgkmcnt(0)
; __device__ __forceinline__ void nsa_quad(const Params& p, int qd, int g, float* slds, const int lane_in) {
;     ...
;             sc[tile] = __builtin_amdgcn_mfma_f32_16x16x32_fp8_fp8(kvb[qa][tile][0], qm0, sc[tile], 0, 0, 0);
;             sc[tile] = __builtin_amdgcn_mfma_f32_16x16x32_fp8_fp8(kvb[qa][tile][1], qm1, sc[tile], 0, 0, 0);
;           }
;           const int blk = PSEL(qa, r);
;           __builtin_amdgcn_sched_barrier(0);
;           PLOAD8(qa, vs8, blk)
;           __builtin_amdgcn_sched_barrier(0);
;         }
;         float cm = NEGF;
; #pragma unroll
;         for (int tile = 0; tile < 4; ++tile)
; #pragma unroll
;           for (int j = 0; j < 4; ++j) cm = fmaxf(cm, sc[tile][j]);
;         cm = rows_max(cm);
;         const float mn = fmaxf(m, cm * SC_LOG2);
;         const float alpha = __builtin_amdgcn_exp2f(m - mn);
;         float ls = 0.f;
; #pragma unroll
;         for (int tile = 0; tile < 4; ++tile)
; #pragma unroll
;           for (int j = 0; j < 4; ++j) { const float pp = __builtin_amdgcn_exp2f(__builtin_fmaf(sc[tile][j], SC_LOG2, -mn)); sc[tile][j] = pp; ls += pp; }
;         ls = rows_sum(ls);
;         l = l * alpha + ls;
;         m = mn;
; #pragma unroll
;         for (int dt = 0; dt < 4; ++dt) oacc[dt] *= alpha;
;         unsigned pu[2][2];
; #pragma unroll
;         for (int s2 = 0; s2 < 2; ++s2) {
;           pu[s2][0] = pack_fp8x4(sc[2 * s2][0] * 256.f, sc[2 * s2][1] * 256.f, sc[2 * s2][2] * 256.f, sc[2 * s2][3] * 256.f);
;           pu[s2][1] = pack_fp8x4(sc[2 * s2 + 1][0] * 256.f, sc[2 * s2 + 1][1] * 256.f, sc[2 * s2 + 1][2] * 256.f,
;                                  sc[2 * s2 + 1][3] * 256.f);
;         }
; #pragma unroll
;         for (int qa = 0; qa < 4; ++qa) {
;           const bool mine = (qi == qa);
; #pragma unroll
;           for (int s2 = 0; s2 < 2; ++s2) {
;             const unsigned plo = mine ? pu[s2][0] : 0u, phi = mine ? pu[s2][1] : 0u;
;             const long pm = (long)(((unsigned long long)phi << 32) | (unsigned long long)plo);
; #pragma unroll
;             for (int dt = 0; dt < 4; ++dt)
;               oacc[dt] = __builtin_amdgcn_mfma_f32_16x16x32_fp8_fp8(kvb[qa][dt][s2], pm, oacc[dt], 0, 0, 0);
;           }
;           __builtin_amdgcn_sched_barrier(0);
;           if (r + 1 < npriv) { const int blk = PSEL(qa, r + 1); PLOAD8(qa, ks8, blk) }
;           __builtin_amdgcn_sched_barrier(0);
;         }
	v_readfirstlane_b32 s8, v116
	v_mfma_f32_16x16x32_fp8_fp8 v[180:183], v[118:119], v[158:159], v[120:123]
	s_ashr_i32 s9, s8, 31
	s_lshl_b64 s[8:9], s[8:9], 12
	v_mov_b32_e32 v116, v164
	s_add_u32 s8, s95, s8
	s_addc_u32 s9, s51, s9
	global_load_dwordx4 v[128:131], v116, s[8:9]
	global_load_dwordx4 v[124:127], v116, s[8:9] offset:1024
	global_load_dwordx4 v[120:123], v116, s[8:9] offset:2048
	s_nop 0
	global_load_dwordx4 v[116:119], v116, s[8:9] offset:3072
	s_waitcnt vmcnt(12)
	v_mfma_f32_16x16x32_fp8_fp8 v[168:171], v[144:145], v[160:161], v[168:171]
	ds_read_b32 v0, v0 offset:6144
	s_waitcnt lgkmcnt(0)
	v_readfirstlane_b32 s8, v0
	v_mfma_f32_16x16x32_fp8_fp8 v[168:171], v[146:147], v[162:163], v[168:171]
	v_mfma_f32_16x16x32_fp8_fp8 v[144:147], v[140:141], v[160:161], v[172:175]
	v_mfma_f32_16x16x32_fp8_fp8 v[172:175], v[142:143], v[162:163], v[144:147]
	v_mfma_f32_16x16x32_fp8_fp8 v[140:143], v[136:137], v[160:161], v[176:179]
	v_mfma_f32_16x16x32_fp8_fp8 v[176:179], v[138:139], v[162:163], v[140:143]
	v_mfma_f32_16x16x32_fp8_fp8 v[136:139], v[132:133], v[160:161], v[180:183]
	v_mfma_f32_16x16x32_fp8_fp8 v[180:183], v[134:135], v[162:163], v[136:139]
	s_ashr_i32 s9, s8, 31
	s_lshl_b64 s[8:9], s[8:9], 12
	v_mov_b32_e32 v0, v164
	s_add_u32 s8, s95, s8
	s_addc_u32 s9, s51, s9
	global_load_dwordx4 v[144:147], v0, s[8:9]
	global_load_dwordx4 v[140:143], v0, s[8:9] offset:1024
	global_load_dwordx4 v[136:139], v0, s[8:9] offset:2048
	global_load_dwordx4 v[132:135], v0, s[8:9] offset:3072
	v_max3_f32 v0, v168, s37, v169
	v_max3_f32 v0, v0, v170, v171
	v_max3_f32 v0, v0, v172, v173
	v_max3_f32 v0, v0, v174, v175
	v_max3_f32 v0, v0, v176, v177
	v_max3_f32 v0, v0, v178, v179
	v_max3_f32 v0, v0, v180, v181
	v_max3_f32 v0, v0, v182, v183
	v_mov_b32_e32 v184, v0
	s_nop 1
	v_permlane16_swap_b32_e32 v0, v184
	v_max_f32_e32 v184, v184, v184
	v_max_f32_e32 v0, v0, v0
	v_max_f32_e32 v0, v0, v184
	v_mov_b32_e32 v184, v0
	s_nop 1
	v_permlane32_swap_b32_e32 v0, v184
	v_max_f32_e32 v184, v184, v184
	v_max_f32_e32 v0, v0, v0
	v_max_f32_e32 v0, v0, v184
	v_mov_b32_e32 v184, v166
	v_mul_f32_e32 v0, 0x3e38aa3b, v0
	v_max_f32_e32 v166, v184, v184
	v_max_f32_e32 v166, v166, v0
	v_fma_f32 v0, v168, s49, -v166
	v_exp_f32_e32 v168, v0
	v_fma_f32 v169, v169, s49, -v166
	v_exp_f32_e32 v169, v169
	v_fma_f32 v170, v170, s49, -v166
	v_exp_f32_e32 v170, v170
	v_fma_f32 v171, v171, s49, -v166
	v_exp_f32_e32 v171, v171
	v_fma_f32 v172, v172, s49, -v166
	v_sub_f32_e32 v0, v184, v166
	v_add_f32_e32 v184, 0, v168
	v_exp_f32_e32 v172, v172
	v_fma_f32 v173, v173, s49, -v166
	v_add_f32_e32 v184, v169, v184
	v_exp_f32_e32 v173, v173
	v_add_f32_e32 v184, v170, v184
	v_add_f32_e32 v184, v171, v184
	v_add_f32_e32 v184, v172, v184
	v_fma_f32 v174, v174, s49, -v166
	v_fma_f32 v175, v175, s49, -v166
	v_mul_f32_e32 v185, 0x43800000, v168
	v_mul_f32_e32 v169, 0x43800000, v169
	v_mov_b32_e32 v168, v1
	v_exp_f32_e32 v174, v174
	v_exp_f32_e32 v175, v175
	v_fma_f32 v176, v176, s49, -v166
	v_add_f32_e32 v184, v173, v184
	v_fma_f32 v177, v177, s49, -v166
	v_cvt_pk_fp8_f32 v168, v185, v169
	v_mul_f32_e32 v169, 0x43800000, v172
	v_mul_f32_e32 v173, 0x43800000, v173
	v_mov_b32_e32 v172, v1
	v_exp_f32_e32 v176, v176
	v_exp_f32_e32 v177, v177
	v_cvt_pk_fp8_f32 v172, v169, v173
	v_mul_f32_e32 v170, 0x43800000, v170
	v_mul_f32_e32 v171, 0x43800000, v171
	v_fma_f32 v178, v178, s49, -v166
	v_fma_f32 v179, v179, s49, -v166
	v_cvt_pk_fp8_f32 v168, v170, v171 op_sel:[0,0,1]
	v_mul_f32_e32 v169, 0x43800000, v174
	v_mul_f32_e32 v170, 0x43800000, v175
	v_exp_f32_e32 v178, v178
	v_exp_f32_e32 v179, v179
	v_fma_f32 v180, v180, s49, -v166
	v_fma_f32 v181, v181, s49, -v166
	v_cvt_pk_fp8_f32 v172, v169, v170 op_sel:[0,0,1]
	v_mul_f32_e32 v169, 0x43800000, v176
	v_mul_f32_e32 v170, 0x43800000, v177
	v_mov_b32_e32 v171, v1
	v_exp_f32_e32 v180, v180
	v_exp_f32_e32 v181, v181
	v_cvt_pk_fp8_f32 v171, v169, v170
	v_add_f32_e32 v184, v174, v184
	v_fma_f32 v182, v182, s49, -v166
	v_fma_f32 v183, v183, s49, -v166
	v_mul_f32_e32 v173, 0x43800000, v178
	v_mul_f32_e32 v169, 0x43800000, v179
	v_add_f32_e32 v184, v175, v184
	v_exp_f32_e32 v182, v182
	v_exp_f32_e32 v183, v183
	v_cvt_pk_fp8_f32 v171, v173, v169 op_sel:[0,0,1]
	v_mul_f32_e32 v169, 0x43800000, v180
	v_mul_f32_e32 v170, 0x43800000, v181
	v_mov_b32_e32 v173, v1
	v_add_f32_e32 v184, v176, v184
	v_exp_f32_e32 v0, v0
	v_cvt_pk_fp8_f32 v173, v169, v170
	v_add_f32_e32 v184, v177, v184
	v_add_f32_e32 v184, v178, v184
	v_add_f32_e32 v184, v179, v184
	v_mul_f32_e32 v169, 0x43800000, v182
	v_mul_f32_e32 v170, 0x43800000, v183
	v_add_f32_e32 v184, v180, v184
	v_mul_f32_e32 v102, v0, v102
	v_mul_f32_e32 v103, v0, v103
	v_mul_f32_e32 v100, v0, v100
	v_mul_f32_e32 v101, v0, v101
	v_mul_f32_e32 v106, v0, v106
	v_mul_f32_e32 v107, v0, v107
	v_mul_f32_e32 v104, v0, v104
	v_mul_f32_e32 v105, v0, v105
	v_mul_f32_e32 v110, v0, v110
	v_mul_f32_e32 v111, v0, v111
	v_mul_f32_e32 v108, v0, v108
	v_mul_f32_e32 v109, v0, v109
	v_mul_f32_e32 v114, v0, v114
	v_mul_f32_e32 v115, v0, v115
	v_mul_f32_e32 v112, v0, v112
	v_mul_f32_e32 v113, v0, v113
	v_cndmask_b32_e64 v174, 0, v168, s[0:1]
	v_cndmask_b32_e64 v175, 0, v172, s[0:1]
	v_cvt_pk_fp8_f32 v173, v169, v170 op_sel:[0,0,1]
	v_add_f32_e32 v184, v181, v184
	s_waitcnt vmcnt(15)
	v_mfma_f32_16x16x32_fp8_fp8 v[100:103], v[80:81], v[174:175], v[100:103]
	v_add_f32_e32 v184, v182, v184
	v_add_f32_e32 v184, v183, v184
	v_mov_b32_e32 v169, v184
	s_waitcnt vmcnt(14)
	v_mfma_f32_16x16x32_fp8_fp8 v[104:107], v[76:77], v[174:175], v[104:107]
	v_permlane16_swap_b32_e32 v184, v169
	v_add_f32_e32 v169, v184, v169
	s_waitcnt vmcnt(13)
	v_mfma_f32_16x16x32_fp8_fp8 v[108:111], v[72:73], v[174:175], v[108:111]
	s_add_i32 s13, s13, 1
	v_mov_b32_e32 v170, v169
	s_cmp_lt_i32 s13, s12
	s_waitcnt vmcnt(12)
	v_mfma_f32_16x16x32_fp8_fp8 v[112:115], v[68:69], v[174:175], v[112:115]
	v_cndmask_b32_e64 v174, 0, v171, s[0:1]
	v_cndmask_b32_e64 v175, 0, v173, s[0:1]
	v_permlane32_swap_b32_e32 v169, v170
	s_nop 0
	v_mfma_f32_16x16x32_fp8_fp8 v[100:103], v[82:83], v[174:175], v[100:103]
	s_cselect_b64 s[10:11], -1, 0
	s_cmp_ge_i32 s13, s12
	v_mfma_f32_16x16x32_fp8_fp8 v[104:107], v[78:79], v[174:175], v[104:107]
	v_mfma_f32_16x16x32_fp8_fp8 v[108:111], v[74:75], v[174:175], v[108:111]
	v_mfma_f32_16x16x32_fp8_fp8 v[112:115], v[70:71], v[174:175], v[112:115]
	s_cbranch_scc1 .LBB0_715
	v_mov_b32_e32 v68, s14
	ds_read_b32 v68, v68 offset:4
	v_mov_b32_e32 v69, v164
	s_waitcnt lgkmcnt(0)
	v_readfirstlane_b32 s8, v68
	s_ashr_i32 s9, s8, 31
	s_lshl_b64 s[8:9], s[8:9], 12
	s_add_u32 s8, s77, s8
	s_addc_u32 s9, s94, s9
	s_nop 0
	global_load_dwordx4 v[80:83], v69, s[8:9]
	global_load_dwordx4 v[76:79], v69, s[8:9] offset:1024
	global_load_dwordx4 v[72:75], v69, s[8:9] offset:2048
	s_nop 0
	global_load_dwordx4 v[68:71], v69, s[8:9] offset:3072

; #define ONLINE(BUF, BASE, LO, HI, NOMASK)                                                   \
;   { if (NOMASK) online_chunk<false>(BUF, (BASE), (LO), (HI), qst, fq, m, l, oacc, lane);       \
;     else online_chunk<true>(BUF, (BASE), (LO), (HI), qst, fq, m, l, oacc, lane); }
; template <bool MASK>
; __device__ __forceinline__ void online_chunk(const KV& b, int base, int lo, int hi, const bf16x8* qst, int fq, float& m,
;                                              float& l, f32x4 (&oacc)[4], const int lane) {
;   f32x4 s[4];
;   qk_from(b, qst, s);
;   float cm = NEGF;
;   const int klo = lo - base - fq * 4, khi = hi - base - fq * 4;
; #pragma unroll
;   for (int tile = 0; tile < 4; ++tile)
; #pragma unroll
;     for (int j = 0; j < 4; ++j) {
;       float v = s[tile][j];
;       if (MASK) { const bool ok = (tile * 16 + j >= klo) && (tile * 16 + j <= khi); v = ok ? v : NEGF; }
;       cm = fmaxf(cm, v);
;     }
;   cm = rows_max(cm);
;   const float mn = fmaxf(m, cm * SC_LOG2);
;   const float alpha = __builtin_amdgcn_exp2f(m - mn);
;   float ls = 0.f;
; #pragma unroll
;   for (int tile = 0; tile < 4; ++tile)
; #pragma unroll
;     for (int j = 0; j < 4; ++j) {
;       float pp = __builtin_amdgcn_exp2f(__builtin_fmaf(s[tile][j], SC_LOG2, -mn));
;       if (MASK) { const bool ok = (tile * 16 + j >= klo) && (tile * 16 + j <= khi); pp = ok ? pp : 0.f; }
;       s[tile][j] = pp;
;       ls += pp;
;     }
;   ls = rows_sum(ls);
;   l = l * alpha + ls;
;   m = mn;
; #pragma unroll
;   for (int dt = 0; dt < 4; ++dt) oacc[dt] *= alpha;
;   pv_from(b, s, oacc);
; }
; __device__ __forceinline__ void nsa_quad(const Params& p, int qd, int g, float* slds, const int lane_in) {
;     ...
;     for (int c = c0; c <= c1; c += 2) {
;       if (c + 1 <= c1) { load_k(B, kw + (long)(c + 1) * 4096, loff); load_v(B, vw + (long)(c + 1) * 4096, loff); }
;       ONLINE(A, c * 64, lo, my_t, (c * 64 >= t0 + 3 - 511) && (c * 64 + 63 <= t0))
.LBB0_731:
	s_sub_i32 s0, s30, 63
	s_cmp_lt_i32 s0, s36
	s_waitcnt lgkmcnt(1)
	ds_read_b128 v[164:167], v172 offset:12288
	s_waitcnt lgkmcnt(1)
	ds_read_b128 v[168:171], v172 offset:13312
	s_cselect_b64 s[0:1], -1, 0
	s_cmp_gt_i32 s30, s90
	s_cselect_b64 s[2:3], -1, 0
	s_or_b64 s[2:3], s[0:1], s[2:3]
	s_mov_b64 s[0:1], -1
	s_and_b64 vcc, exec, s[2:3]
	v_max_f32_e32 v0, v181, v181
	s_cbranch_vccnz .LBB0_740
	s_waitcnt vmcnt(9) lgkmcnt(1)
	v_mfma_f32_16x16x32_bf16 v[148:151], v[80:83], v[164:167], 0
	s_waitcnt vmcnt(13)
	v_mfma_f32_16x16x32_bf16 v[152:155], v[72:75], v[164:167], 0
	s_waitcnt lgkmcnt(0)
	v_mfma_f32_16x16x32_bf16 v[148:151], v[68:71], v[168:171], v[148:151]
	s_waitcnt vmcnt(11)
	v_mfma_f32_16x16x32_bf16 v[156:159], v[84:87], v[164:167], 0
	v_mfma_f32_16x16x32_bf16 v[152:155], v[76:79], v[168:171], v[152:155]
	s_nop 4
	v_max3_f32 v2, v148, s37, v149
	v_max3_f32 v2, v2, v150, v151
	s_waitcnt vmcnt(9)
	v_mfma_f32_16x16x32_bf16 v[160:163], v[92:95], v[164:167], 0
	v_mfma_f32_16x16x32_bf16 v[156:159], v[88:91], v[168:171], v[156:159]
	v_max3_f32 v2, v2, v152, v153
	v_max3_f32 v2, v2, v154, v155
	s_waitcnt vmcnt(8)
	v_mfma_f32_16x16x32_bf16 v[160:163], v[96:99], v[168:171], v[160:163]
	s_nop 3
	v_max3_f32 v2, v2, v156, v157
	v_max3_f32 v2, v2, v158, v159
	s_nop 1
	v_max3_f32 v2, v2, v160, v161
	v_max3_f32 v2, v2, v162, v163
	v_mov_b32_e32 v3, v2
	s_nop 1
	v_permlane16_swap_b32_e32 v2, v3
	v_max_f32_e32 v3, v3, v3
	v_max_f32_e32 v2, v2, v2
	v_max_f32_e32 v2, v2, v3
	v_mov_b32_e32 v3, v2
	s_nop 1
	v_permlane32_swap_b32_e32 v2, v3
	v_max_f32_e32 v3, v3, v3
	v_max_f32_e32 v2, v2, v2
	v_max_f32_e32 v2, v2, v3
	v_mul_f32_e32 v2, 0x3e38aa3b, v2
	v_max_f32_e32 v2, v0, v2
	v_fma_f32 v148, v148, s49, -v2
	v_exp_f32_e32 v183, v148
	v_fma_f32 v149, v149, s49, -v2
	v_exp_f32_e32 v184, v149
	v_fma_f32 v149, v150, s49, -v2
	v_exp_f32_e32 v185, v149
	v_fma_f32 v149, v151, s49, -v2
	v_exp_f32_e32 v186, v149
	v_fma_f32 v149, v152, s49, -v2
	v_add_f32_e32 v148, 0, v183
	v_exp_f32_e32 v187, v149
	v_fma_f32 v149, v153, s49, -v2
	v_add_f32_e32 v148, v184, v148
	v_exp_f32_e32 v188, v149
	v_fma_f32 v149, v154, s49, -v2
	v_add_f32_e32 v148, v185, v148
	v_exp_f32_e32 v190, v149
	v_fma_f32 v149, v155, s49, -v2
	v_add_f32_e32 v148, v186, v148
	v_exp_f32_e32 v191, v149
	v_fma_f32 v149, v156, s49, -v2
	v_add_f32_e32 v148, v187, v148
	v_exp_f32_e32 v192, v149
	v_fma_f32 v149, v157, s49, -v2
	v_add_f32_e32 v148, v188, v148
	v_exp_f32_e32 v193, v149
	v_fma_f32 v149, v158, s49, -v2
	v_add_f32_e32 v148, v190, v148
	v_exp_f32_e32 v194, v149
	v_fma_f32 v149, v159, s49, -v2
	v_add_f32_e32 v148, v191, v148
	v_exp_f32_e32 v195, v149
	v_fma_f32 v149, v160, s49, -v2
	v_add_f32_e32 v148, v192, v148
	v_exp_f32_e32 v196, v149
	v_fma_f32 v149, v161, s49, -v2
	v_add_f32_e32 v148, v193, v148
	v_exp_f32_e32 v197, v149
	v_fma_f32 v149, v162, s49, -v2
	v_add_f32_e32 v148, v194, v148
	v_exp_f32_e32 v198, v149
	v_fma_f32 v149, v163, s49, -v2
	v_add_f32_e32 v148, v195, v148
	v_exp_f32_e32 v199, v149
	v_add_f32_e32 v148, v196, v148
	v_add_f32_e32 v148, v197, v148
	v_add_f32_e32 v148, v198, v148
	v_sub_f32_e32 v3, v181, v2
	v_add_f32_e32 v148, v199, v148
	v_exp_f32_e32 v160, v3
	v_mov_b32_e32 v3, v148
	s_nop 1
	v_permlane16_swap_b32_e32 v148, v3
	v_add_f32_e32 v3, v148, v3
	v_mov_b32_e32 v148, v3
	s_nop 1
	v_permlane32_swap_b32_e32 v3, v148
	v_add_f32_e32 v3, v3, v148
	v_fmac_f32_e32 v3, v182, v160
	v_mul_f32_e32 v150, v160, v146
	v_mul_f32_e32 v151, v160, v147
	v_mul_f32_e32 v148, v160, v144
	v_mul_f32_e32 v149, v160, v145
	v_mul_f32_e32 v154, v160, v134
	v_mul_f32_e32 v155, v160, v135
	v_mul_f32_e32 v152, v160, v132
	v_mul_f32_e32 v153, v160, v133
	v_mul_f32_e32 v158, v160, v138
	v_mul_f32_e32 v159, v160, v139
	v_mul_f32_e32 v156, v160, v136
	v_mul_f32_e32 v157, v160, v137
	v_mul_f32_e32 v162, v160, v142
	v_mul_f32_e32 v163, v160, v143
	v_mul_f32_e32 v161, v160, v141
	v_mul_f32_e32 v160, v160, v140
	v_cvt_pk_bf16_f32 v184, v183, v184
	v_cvt_pk_bf16_f32 v185, v185, v186
	v_cvt_pk_bf16_f32 v186, v187, v188
	v_cvt_pk_bf16_f32 v187, v190, v191
	s_waitcnt vmcnt(0)
	s_nop 0
	v_mfma_f32_16x16x32_bf16 v[148:151], v[100:103], v[184:187], v[148:151]
	v_mfma_f32_16x16x32_bf16 v[152:155], v[104:107], v[184:187], v[152:155]
	v_mfma_f32_16x16x32_bf16 v[156:159], v[108:111], v[184:187], v[156:159]
	v_mfma_f32_16x16x32_bf16 v[160:163], v[112:115], v[184:187], v[160:163]
	v_cvt_pk_bf16_f32 v184, v192, v193
	v_cvt_pk_bf16_f32 v185, v194, v195
	v_cvt_pk_bf16_f32 v186, v196, v197
	v_cvt_pk_bf16_f32 v187, v198, v199
	s_nop 1
	v_mfma_f32_16x16x32_bf16 v[148:151], v[116:119], v[184:187], v[148:151]
	v_mfma_f32_16x16x32_bf16 v[152:155], v[120:123], v[184:187], v[152:155]
	v_mfma_f32_16x16x32_bf16 v[156:159], v[124:127], v[184:187], v[156:159]
	v_mfma_f32_16x16x32_bf16 v[160:163], v[128:131], v[184:187], v[160:163]
	s_cbranch_execz .LBB0_741

; #define ONLINE(BUF, BASE, LO, HI, NOMASK)                                                   \
;   { if (NOMASK) online_chunk<false>(BUF, (BASE), (LO), (HI), qst, fq, m, l, oacc, lane);       \
;     else online_chunk<true>(BUF, (BASE), (LO), (HI), qst, fq, m, l, oacc, lane); }
; template <bool MASK>
; __device__ __forceinline__ void online_chunk(const KV& b, int base, int lo, int hi, const bf16x8* qst, int fq, float& m,
;                                              float& l, f32x4 (&oacc)[4], const int lane) {
;   f32x4 s[4];
;   qk_from(b, qst, s);
;   float cm = NEGF;
;   const int klo = lo - base - fq * 4, khi = hi - base - fq * 4;
; #pragma unroll
;   for (int tile = 0; tile < 4; ++tile)
; #pragma unroll
;     for (int j = 0; j < 4; ++j) {
;       float v = s[tile][j];
;       if (MASK) { const bool ok = (tile * 16 + j >= klo) && (tile * 16 + j <= khi); v = ok ? v : NEGF; }
;       cm = fmaxf(cm, v);
;     }
;   cm = rows_max(cm);
;   const float mn = fmaxf(m, cm * SC_LOG2);
;   const float alpha = __builtin_amdgcn_exp2f(m - mn);
;   float ls = 0.f;
; #pragma unroll
;   for (int tile = 0; tile < 4; ++tile)
; #pragma unroll
;     for (int j = 0; j < 4; ++j) {
;       float pp = __builtin_amdgcn_exp2f(__builtin_fmaf(s[tile][j], SC_LOG2, -mn));
;       if (MASK) { const bool ok = (tile * 16 + j >= klo) && (tile * 16 + j <= khi); pp = ok ? pp : 0.f; }
;       s[tile][j] = pp;
;       ls += pp;
;     }
;   ls = rows_sum(ls);
;   l = l * alpha + ls;
;   m = mn;
; #pragma unroll
;   for (int dt = 0; dt < 4; ++dt) oacc[dt] *= alpha;
;   pv_from(b, s, oacc);
; }
; __device__ __forceinline__ void nsa_quad(const Params& p, int qd, int g, float* slds, const int lane_in) {
;     ...
;       if (c + 1 <= c1) {
;         if (c + 2 <= c1) { load_k(A, kw + (long)(c + 2) * 4096, loff); load_v(A, vw + (long)(c + 2) * 4096, loff); }
;         ONLINE(B, (c + 1) * 64, lo, my_t, ((c + 1) * 64 >= t0 + 3 - 511) && ((c + 1) * 64 + 63 <= t0))
.LBB0_736:
	s_add_i32 s0, s30, 1
	s_cmp_lt_i32 s0, s36
	s_cselect_b64 s[0:1], -1, 0
	s_add_i32 s2, s30, 64
	s_waitcnt lgkmcnt(1)
	ds_read_b128 v[164:167], v172 offset:12288
	s_waitcnt lgkmcnt(1)
	ds_read_b128 v[168:171], v172 offset:13312
	s_cmp_gt_i32 s2, s90
	s_cselect_b64 s[2:3], -1, 0
	s_or_b64 s[2:3], s[0:1], s[2:3]
	s_mov_b64 s[0:1], -1
	s_and_b64 vcc, exec, s[2:3]
	v_max_f32_e32 v0, v2, v2
	s_cbranch_vccnz .LBB0_738
	s_waitcnt vmcnt(15) lgkmcnt(1)
	v_mfma_f32_16x16x32_bf16 v[132:135], v[4:7], v[164:167], 0
	s_mov_b64 s[0:1], 0
	s_waitcnt vmcnt(13)
	v_mfma_f32_16x16x32_bf16 v[136:139], v[12:15], v[164:167], 0
	s_waitcnt lgkmcnt(0)
	v_mfma_f32_16x16x32_bf16 v[132:135], v[8:11], v[168:171], v[132:135]
	s_waitcnt vmcnt(11)
	v_mfma_f32_16x16x32_bf16 v[140:143], v[20:23], v[164:167], 0
	v_mfma_f32_16x16x32_bf16 v[136:139], v[16:19], v[168:171], v[136:139]
	s_nop 4
	v_max3_f32 v181, v132, s37, v133
	v_max3_f32 v181, v181, v134, v135
	s_waitcnt vmcnt(9)
	v_mfma_f32_16x16x32_bf16 v[144:147], v[28:31], v[164:167], 0
	v_mfma_f32_16x16x32_bf16 v[140:143], v[24:27], v[168:171], v[140:143]
	v_max3_f32 v181, v181, v136, v137
	v_max3_f32 v181, v181, v138, v139
	s_waitcnt vmcnt(8)
	v_mfma_f32_16x16x32_bf16 v[144:147], v[32:35], v[168:171], v[144:147]
	s_nop 3
	v_max3_f32 v181, v181, v140, v141
	v_max3_f32 v181, v181, v142, v143
	s_nop 1
	v_max3_f32 v181, v181, v144, v145
	v_max3_f32 v181, v181, v146, v147
	v_mov_b32_e32 v182, v181
	s_nop 1
	v_permlane16_swap_b32_e32 v181, v182
	v_max_f32_e32 v182, v182, v182
	v_max_f32_e32 v181, v181, v181
	v_max_f32_e32 v181, v181, v182
	v_mov_b32_e32 v182, v181
	s_nop 1
	v_permlane32_swap_b32_e32 v181, v182
	v_max_f32_e32 v182, v182, v182
	v_max_f32_e32 v181, v181, v181
	v_max_f32_e32 v181, v181, v182
	v_mul_f32_e32 v181, 0x3e38aa3b, v181
	v_max_f32_e32 v181, v0, v181
	v_fma_f32 v132, v132, s49, -v181
	v_exp_f32_e32 v183, v132
	v_fma_f32 v133, v133, s49, -v181
	v_exp_f32_e32 v184, v133
	v_fma_f32 v133, v134, s49, -v181
	v_exp_f32_e32 v185, v133
	v_fma_f32 v133, v135, s49, -v181
	v_exp_f32_e32 v186, v133
	v_fma_f32 v133, v136, s49, -v181
	v_add_f32_e32 v132, 0, v183
	v_exp_f32_e32 v187, v133
	v_fma_f32 v133, v137, s49, -v181
	v_add_f32_e32 v132, v184, v132
	v_exp_f32_e32 v188, v133
	v_fma_f32 v133, v138, s49, -v181
	v_add_f32_e32 v132, v185, v132
	v_exp_f32_e32 v190, v133
	v_fma_f32 v133, v139, s49, -v181
	v_add_f32_e32 v132, v186, v132
	v_exp_f32_e32 v191, v133
	v_fma_f32 v133, v140, s49, -v181
	v_add_f32_e32 v132, v187, v132
	v_exp_f32_e32 v192, v133
	v_fma_f32 v133, v141, s49, -v181
	v_add_f32_e32 v132, v188, v132
	v_exp_f32_e32 v193, v133
	v_fma_f32 v133, v142, s49, -v181
	v_add_f32_e32 v132, v190, v132
	v_exp_f32_e32 v194, v133
	v_fma_f32 v133, v143, s49, -v181
	v_add_f32_e32 v132, v191, v132
	v_exp_f32_e32 v195, v133
	v_fma_f32 v133, v144, s49, -v181
	v_add_f32_e32 v132, v192, v132
	v_exp_f32_e32 v196, v133
	v_fma_f32 v133, v145, s49, -v181
	v_add_f32_e32 v132, v193, v132
	v_exp_f32_e32 v197, v133
	v_fma_f32 v133, v146, s49, -v181
	v_add_f32_e32 v132, v194, v132
	v_exp_f32_e32 v198, v133
	v_fma_f32 v133, v147, s49, -v181
	v_add_f32_e32 v132, v195, v132
	v_exp_f32_e32 v199, v133
	v_add_f32_e32 v132, v196, v132
	v_add_f32_e32 v132, v197, v132
	v_add_f32_e32 v132, v198, v132
	v_add_f32_e32 v132, v199, v132
	v_mov_b32_e32 v133, v132
	v_sub_f32_e32 v182, v2, v181
	s_nop 0
	v_permlane16_swap_b32_e32 v132, v133
	v_exp_f32_e32 v144, v182
	v_add_f32_e32 v132, v132, v133
	v_mov_b32_e32 v133, v132
	s_nop 1
	v_permlane32_swap_b32_e32 v132, v133
	v_add_f32_e32 v182, v132, v133
	v_fmac_f32_e32 v182, v3, v144
	v_mul_f32_e32 v134, v144, v150
	v_mul_f32_e32 v135, v144, v151
	v_mul_f32_e32 v132, v144, v148
	v_mul_f32_e32 v133, v144, v149
	v_mul_f32_e32 v138, v144, v154
	v_mul_f32_e32 v139, v144, v155
	v_mul_f32_e32 v136, v144, v152
	v_mul_f32_e32 v137, v144, v153
	v_mul_f32_e32 v142, v144, v158
	v_mul_f32_e32 v143, v144, v159
	v_mul_f32_e32 v140, v144, v156
	v_mul_f32_e32 v141, v144, v157
	v_mul_f32_e32 v146, v144, v162
	v_mul_f32_e32 v147, v144, v163
	v_mul_f32_e32 v145, v144, v161
	v_mul_f32_e32 v144, v144, v160
	v_cvt_pk_bf16_f32 v184, v183, v184
	v_cvt_pk_bf16_f32 v185, v185, v186
	v_cvt_pk_bf16_f32 v186, v187, v188
	v_cvt_pk_bf16_f32 v187, v190, v191
	v_cvt_pk_bf16_f32 v190, v192, v193
	v_cvt_pk_bf16_f32 v191, v194, v195
	s_waitcnt vmcnt(7)
	v_mfma_f32_16x16x32_bf16 v[132:135], v[36:39], v[184:187], v[132:135]
	v_cvt_pk_bf16_f32 v192, v196, v197
	v_cvt_pk_bf16_f32 v193, v198, v199
	s_waitcnt vmcnt(6)
	v_mfma_f32_16x16x32_bf16 v[136:139], v[40:43], v[184:187], v[136:139]
	s_waitcnt vmcnt(5)
	v_mfma_f32_16x16x32_bf16 v[140:143], v[44:47], v[184:187], v[140:143]
	s_waitcnt vmcnt(4)
	v_mfma_f32_16x16x32_bf16 v[184:187], v[48:51], v[184:187], v[144:147]
	s_waitcnt vmcnt(3)
	v_mfma_f32_16x16x32_bf16 v[144:147], v[52:55], v[190:193], v[132:135]
	s_waitcnt vmcnt(2)
	v_mfma_f32_16x16x32_bf16 v[132:135], v[56:59], v[190:193], v[136:139]
	s_waitcnt vmcnt(1)
	v_mfma_f32_16x16x32_bf16 v[136:139], v[60:63], v[190:193], v[140:143]
	s_waitcnt vmcnt(0)
	v_mfma_f32_16x16x32_bf16 v[140:143], v[64:67], v[190:193], v[184:187]
; template <bool MASK>
; __device__ __forceinline__ void online_chunk(const KV& b, int base, int lo, int hi, const bf16x8* qst, int fq, float& m,
;                                              float& l, f32x4 (&oacc)[4], const int lane) {
;   f32x4 s[4];
;   qk_from(b, qst, s);
;   float cm = NEGF;
;   const int klo = lo - base - fq * 4, khi = hi - base - fq * 4;
; #pragma unroll
;   for (int tile = 0; tile < 4; ++tile)
; #pragma unroll
;     for (int j = 0; j < 4; ++j) {
;       float v = s[tile][j];
;       if (MASK) { const bool ok = (tile * 16 + j >= klo) && (tile * 16 + j <= khi); v = ok ? v : NEGF; }
;       cm = fmaxf(cm, v);
;     }
;   cm = rows_max(cm);
.LBB0_738:
	s_andn2_b64 vcc, exec, s[0:1]
	s_cbranch_vccnz .LBB0_743
	s_waitcnt vmcnt(15) lgkmcnt(1)
	v_mfma_f32_16x16x32_bf16 v[132:135], v[4:7], v[164:167], 0
	s_waitcnt vmcnt(13)
	v_mfma_f32_16x16x32_bf16 v[136:139], v[12:15], v[164:167], 0
	s_waitcnt vmcnt(11)
	v_mfma_f32_16x16x32_bf16 v[140:143], v[20:23], v[164:167], 0
	s_waitcnt vmcnt(9)
	v_mfma_f32_16x16x32_bf16 v[144:147], v[28:31], v[164:167], 0
	v_add_u32_e32 v164, v173, v180
	v_add_u32_e32 v165, v173, v179
	v_cmp_lt_i32_e32 vcc, 0, v164
	v_cmp_gt_i32_e64 s[0:1], 0, v165
	s_or_b64 s[10:11], vcc, s[0:1]
	v_cmp_lt_i32_e32 vcc, 1, v164
	v_cmp_gt_i32_e64 s[0:1], 1, v165
	s_or_b64 s[20:21], vcc, s[0:1]
	v_cmp_lt_i32_e32 vcc, 2, v164
	v_cmp_gt_i32_e64 s[0:1], 2, v165
	s_or_b64 s[26:27], vcc, s[0:1]
	v_cmp_lt_i32_e32 vcc, 3, v164
	v_cmp_gt_i32_e64 s[0:1], 3, v165
	s_waitcnt lgkmcnt(0)
	v_mfma_f32_16x16x32_bf16 v[132:135], v[8:11], v[168:171], v[132:135]
	s_or_b64 s[18:19], vcc, s[0:1]
	v_cmp_lt_i32_e32 vcc, 16, v164
	v_cmp_gt_i32_e64 s[0:1], 16, v165
	s_or_b64 s[28:29], vcc, s[0:1]
	v_cmp_lt_i32_e32 vcc, 17, v164
	v_cmp_gt_i32_e64 s[0:1], 17, v165
	s_or_b64 s[24:25], vcc, s[0:1]
	v_cmp_lt_i32_e32 vcc, 18, v164
	v_cmp_gt_i32_e64 s[0:1], 18, v165
	s_or_b64 s[22:23], vcc, s[0:1]
	v_cmp_lt_i32_e32 vcc, 19, v164
	v_cmp_gt_i32_e64 s[0:1], 19, v165
	v_mfma_f32_16x16x32_bf16 v[136:139], v[16:19], v[168:171], v[136:139]
	v_max_f32_e32 v166, v132, v132
	s_or_b64 s[12:13], vcc, s[0:1]
	v_cmp_lt_i32_e32 vcc, 32, v164
	v_cmp_gt_i32_e64 s[0:1], 32, v165
	v_max_f32_e32 v166, 0xf149f2ca, v166
	v_cndmask_b32_e64 v167, v133, v217, s[20:21]
	s_or_b64 s[16:17], vcc, s[0:1]
	v_cmp_lt_i32_e32 vcc, 33, v164
	v_cmp_gt_i32_e64 s[0:1], 33, v165
	v_mfma_f32_16x16x32_bf16 v[140:143], v[24:27], v[168:171], v[140:143]
	v_cndmask_b32_e64 v166, v166, v217, s[10:11]
	v_max_f32_e32 v167, v167, v167
	s_or_b64 s[14:15], vcc, s[0:1]
	v_cmp_lt_i32_e32 vcc, 34, v164
	v_cmp_gt_i32_e64 s[0:1], 34, v165
	s_waitcnt vmcnt(8)
; template <bool MASK>
; __device__ __forceinline__ void online_chunk(const KV& b, int base, int lo, int hi, const bf16x8* qst, int fq, float& m,
;                                              float& l, f32x4 (&oacc)[4], const int lane) {
;     ...
; #pragma unroll
;   for (int tile = 0; tile < 4; ++tile)
; #pragma unroll
;     for (int j = 0; j < 4; ++j) {
;       float v = s[tile][j];
;       if (MASK) { const bool ok = (tile * 16 + j >= klo) && (tile * 16 + j <= khi); v = ok ? v : NEGF; }
;       cm = fmaxf(cm, v);
;     }
;   cm = rows_max(cm);
;   const float mn = fmaxf(m, cm * SC_LOG2);
;   const float alpha = __builtin_amdgcn_exp2f(m - mn);
;   float ls = 0.f;
; #pragma unroll
;   for (int tile = 0; tile < 4; ++tile)
; #pragma unroll
;     for (int j = 0; j < 4; ++j) {
;       float pp = __builtin_amdgcn_exp2f(__builtin_fmaf(s[tile][j], SC_LOG2, -mn));
;       if (MASK) { const bool ok = (tile * 16 + j >= klo) && (tile * 16 + j <= khi); pp = ok ? pp : 0.f; }
;       s[tile][j] = pp;
;       ls += pp;
;     }
;   ls = rows_sum(ls);
;   l = l * alpha + ls;
;   m = mn;
; #pragma unroll
;   for (int dt = 0; dt < 4; ++dt) oacc[dt] *= alpha;
;   pv_from(b, s, oacc);
	v_mfma_f32_16x16x32_bf16 v[144:147], v[32:35], v[168:171], v[144:147]
	v_max_f32_e32 v166, v166, v167
	v_cndmask_b32_e64 v167, v134, v217, s[26:27]
	v_cndmask_b32_e64 v168, v135, v217, s[18:19]
	s_or_b64 s[8:9], vcc, s[0:1]
	v_cmp_lt_i32_e32 vcc, 35, v164
	v_cmp_gt_i32_e64 s[0:1], 35, v165
	v_max3_f32 v166, v166, v167, v168
	v_cndmask_b32_e64 v167, v136, v217, s[28:29]
	v_cndmask_b32_e64 v168, v137, v217, s[24:25]
	s_or_b64 s[2:3], vcc, s[0:1]
	v_cmp_lt_i32_e32 vcc, 48, v164
	v_cmp_gt_i32_e64 s[0:1], 48, v165
	v_max3_f32 v166, v166, v167, v168
	v_cndmask_b32_e64 v167, v138, v217, s[22:23]
	v_cndmask_b32_e64 v168, v139, v217, s[12:13]
	s_or_b64 s[6:7], vcc, s[0:1]
	v_cmp_lt_i32_e32 vcc, 49, v164
	v_cmp_gt_i32_e64 s[0:1], 49, v165
	v_max3_f32 v166, v166, v167, v168
	v_cndmask_b32_e64 v167, v140, v217, s[16:17]
	v_cndmask_b32_e64 v168, v141, v217, s[14:15]
	s_or_b64 s[4:5], vcc, s[0:1]
	v_cmp_lt_i32_e32 vcc, 50, v164
	v_cmp_gt_i32_e64 s[0:1], 50, v165
	v_max3_f32 v166, v166, v167, v168
	v_cndmask_b32_e64 v167, v142, v217, s[8:9]
	v_cndmask_b32_e64 v168, v143, v217, s[2:3]
	s_or_b64 s[0:1], vcc, s[0:1]
	v_cmp_lt_i32_e32 vcc, 51, v164
	v_cmp_gt_i32_e64 s[34:35], 51, v165
	v_max3_f32 v166, v166, v167, v168
	v_cndmask_b32_e64 v167, v144, v217, s[6:7]
	v_cndmask_b32_e64 v168, v145, v217, s[4:5]
	s_or_b64 vcc, vcc, s[34:35]
	v_max3_f32 v166, v166, v167, v168
	v_cndmask_b32_e64 v167, v146, v217, s[0:1]
	v_cndmask_b32_e32 v164, v147, v217, vcc
	v_max3_f32 v164, v166, v167, v164
	v_mov_b32_e32 v165, v164
	s_nop 1
	v_permlane16_swap_b32_e32 v164, v165
	v_max_f32_e32 v165, v165, v165
	v_max_f32_e32 v164, v164, v164
	v_max_f32_e32 v164, v164, v165
	v_mov_b32_e32 v165, v164
	s_nop 1
	v_permlane32_swap_b32_e32 v164, v165
	v_max_f32_e32 v165, v165, v165
	v_max_f32_e32 v164, v164, v164
	v_max_f32_e32 v164, v164, v165
	v_mul_f32_e32 v164, 0x3e38aa3b, v164
	v_max_f32_e32 v181, v0, v164
	v_fma_f32 v0, v132, s49, -v181
	v_exp_f32_e32 v0, v0
	v_sub_f32_e32 v2, v2, v181
	v_cndmask_b32_e64 v164, v0, 0, s[10:11]
	v_fma_f32 v0, v133, s49, -v181
	v_exp_f32_e32 v0, v0
	s_nop 0
	v_cndmask_b32_e64 v165, v0, 0, s[20:21]
	v_fma_f32 v0, v134, s49, -v181
	v_exp_f32_e32 v0, v0
	s_nop 0
	v_cndmask_b32_e64 v166, v0, 0, s[26:27]
	v_fma_f32 v0, v135, s49, -v181
	v_exp_f32_e32 v0, v0
	s_nop 0
	v_cndmask_b32_e64 v167, v0, 0, s[18:19]
	v_fma_f32 v0, v136, s49, -v181
	v_exp_f32_e32 v0, v0
	s_nop 0
	v_cndmask_b32_e64 v168, v0, 0, s[28:29]
	v_fma_f32 v0, v137, s49, -v181
	v_exp_f32_e32 v0, v0
	s_nop 0
	v_cndmask_b32_e64 v169, v0, 0, s[24:25]
	v_fma_f32 v0, v138, s49, -v181
	v_exp_f32_e32 v0, v0
	s_nop 0
	v_cndmask_b32_e64 v170, v0, 0, s[22:23]
	v_fma_f32 v0, v139, s49, -v181
	v_exp_f32_e32 v0, v0
	s_nop 0
	v_cndmask_b32_e64 v171, v0, 0, s[12:13]
	v_fma_f32 v0, v140, s49, -v181
	v_exp_f32_e32 v0, v0
	s_nop 0
	v_cndmask_b32_e64 v183, v0, 0, s[16:17]
	v_fma_f32 v0, v141, s49, -v181
	v_exp_f32_e32 v0, v0
	s_nop 0
	v_cndmask_b32_e64 v184, v0, 0, s[14:15]
	v_fma_f32 v0, v142, s49, -v181
	v_exp_f32_e32 v0, v0
	s_nop 0
	v_cndmask_b32_e64 v185, v0, 0, s[8:9]
	v_fma_f32 v0, v143, s49, -v181
	v_exp_f32_e32 v0, v0
	s_nop 0
	v_cndmask_b32_e64 v186, v0, 0, s[2:3]
	v_fma_f32 v0, v144, s49, -v181
	v_exp_f32_e32 v0, v0
	s_nop 0
	v_cndmask_b32_e64 v187, v0, 0, s[6:7]
	v_fma_f32 v0, v145, s49, -v181
	v_exp_f32_e32 v0, v0
	s_nop 0
	v_cndmask_b32_e64 v188, v0, 0, s[4:5]
	v_fma_f32 v0, v146, s49, -v181
	v_exp_f32_e32 v0, v0
	s_nop 0
	v_cndmask_b32_e64 v190, v0, 0, s[0:1]
	v_fma_f32 v0, v147, s49, -v181
	v_exp_f32_e32 v0, v0
	s_nop 0
	v_cndmask_b32_e64 v191, v0, 0, vcc
	v_add_f32_e32 v0, 0, v164
	v_add_f32_e32 v0, v165, v0
	v_add_f32_e32 v0, v166, v0
	v_add_f32_e32 v0, v167, v0
	v_add_f32_e32 v0, v168, v0
	v_add_f32_e32 v0, v169, v0
	v_add_f32_e32 v0, v170, v0
	v_add_f32_e32 v0, v171, v0
	v_add_f32_e32 v0, v183, v0
	v_add_f32_e32 v0, v184, v0
	v_add_f32_e32 v0, v185, v0
	v_add_f32_e32 v0, v186, v0
	v_add_f32_e32 v0, v187, v0
	v_add_f32_e32 v0, v188, v0
	v_add_f32_e32 v0, v190, v0
	v_add_f32_e32 v132, v191, v0
	v_exp_f32_e32 v0, v2
	v_mov_b32_e32 v2, v132
	s_nop 1
	v_permlane16_swap_b32_e32 v132, v2
	v_add_f32_e32 v2, v132, v2
	v_mov_b32_e32 v132, v2
	s_nop 1
	v_permlane32_swap_b32_e32 v2, v132
	v_add_f32_e32 v182, v2, v132
	v_mul_f32_e32 v134, v0, v150
	v_mul_f32_e32 v135, v0, v151
	v_mul_f32_e32 v132, v0, v148
	v_mul_f32_e32 v133, v0, v149
	v_mul_f32_e32 v138, v0, v154
	v_mul_f32_e32 v139, v0, v155
	v_mul_f32_e32 v136, v0, v152
	v_mul_f32_e32 v137, v0, v153
	v_mul_f32_e32 v142, v0, v158
	v_mul_f32_e32 v143, v0, v159
	v_mul_f32_e32 v140, v0, v156
	v_mul_f32_e32 v141, v0, v157
	v_mul_f32_e32 v146, v0, v162
	v_mul_f32_e32 v147, v0, v163
	v_mul_f32_e32 v144, v0, v160
	v_mul_f32_e32 v145, v0, v161
	v_cvt_pk_bf16_f32 v148, v164, v165
	v_cvt_pk_bf16_f32 v149, v166, v167
	v_cvt_pk_bf16_f32 v150, v168, v169
	v_cvt_pk_bf16_f32 v151, v170, v171
	v_cvt_pk_bf16_f32 v152, v183, v184
	v_cvt_pk_bf16_f32 v153, v185, v186
	s_waitcnt vmcnt(7)
	v_mfma_f32_16x16x32_bf16 v[132:135], v[36:39], v[148:151], v[132:135]
	v_cvt_pk_bf16_f32 v154, v187, v188
	v_cvt_pk_bf16_f32 v155, v190, v191
	v_fmac_f32_e32 v182, v3, v0
	s_waitcnt vmcnt(6)
	v_mfma_f32_16x16x32_bf16 v[136:139], v[40:43], v[148:151], v[136:139]
	s_waitcnt vmcnt(5)
	v_mfma_f32_16x16x32_bf16 v[140:143], v[44:47], v[148:151], v[140:143]
	s_waitcnt vmcnt(4)
	v_mfma_f32_16x16x32_bf16 v[148:151], v[48:51], v[148:151], v[144:147]
	s_waitcnt vmcnt(3)
	v_mfma_f32_16x16x32_bf16 v[144:147], v[52:55], v[152:155], v[132:135]
	s_waitcnt vmcnt(2)
	v_mfma_f32_16x16x32_bf16 v[132:135], v[56:59], v[152:155], v[136:139]
	s_waitcnt vmcnt(1)
	v_mfma_f32_16x16x32_bf16 v[136:139], v[60:63], v[152:155], v[140:143]
	s_waitcnt vmcnt(0)
	v_mfma_f32_16x16x32_bf16 v[140:143], v[64:67], v[152:155], v[148:151]
	s_branch .LBB0_743

; template <bool MASK>
; __device__ __forceinline__ void online_chunk(const KV& b, int base, int lo, int hi, const bf16x8* qst, int fq, float& m,
;                                              float& l, f32x4 (&oacc)[4], const int lane) {
;   f32x4 s[4];
;   qk_from(b, qst, s);
;   float cm = NEGF;
;   const int klo = lo - base - fq * 4, khi = hi - base - fq * 4;
; #pragma unroll
;   for (int tile = 0; tile < 4; ++tile)
; #pragma unroll
;     for (int j = 0; j < 4; ++j) {
;       float v = s[tile][j];
;       if (MASK) { const bool ok = (tile * 16 + j >= klo) && (tile * 16 + j <= khi); v = ok ? v : NEGF; }
;       cm = fmaxf(cm, v);
;     }
;   cm = rows_max(cm);
.LBB0_741:
	v_add_u32_e32 v2, v173, v178
	v_add_u32_e32 v3, v173, v177
	s_waitcnt vmcnt(9) lgkmcnt(1)
	v_mfma_f32_16x16x32_bf16 v[148:151], v[80:83], v[164:167], 0
	v_cmp_lt_i32_e32 vcc, 0, v2
	v_cmp_gt_i32_e64 s[0:1], 0, v3
	s_or_b64 s[10:11], vcc, s[0:1]
	v_cmp_lt_i32_e32 vcc, 1, v2
	v_cmp_gt_i32_e64 s[0:1], 1, v3
	s_or_b64 s[20:21], vcc, s[0:1]
	v_cmp_lt_i32_e32 vcc, 2, v2
	v_cmp_gt_i32_e64 s[0:1], 2, v3
	s_or_b64 s[26:27], vcc, s[0:1]
	v_cmp_lt_i32_e32 vcc, 3, v2
	v_cmp_gt_i32_e64 s[0:1], 3, v3
	s_waitcnt vmcnt(14) lgkmcnt(0)
	v_mfma_f32_16x16x32_bf16 v[148:151], v[68:71], v[168:171], v[148:151]
	s_or_b64 s[18:19], vcc, s[0:1]
	v_cmp_lt_i32_e32 vcc, 16, v2
	v_cmp_gt_i32_e64 s[0:1], 16, v3
	s_waitcnt vmcnt(13)
	v_mfma_f32_16x16x32_bf16 v[152:155], v[72:75], v[164:167], 0
	s_or_b64 s[28:29], vcc, s[0:1]
	v_cmp_lt_i32_e32 vcc, 17, v2
	v_cmp_gt_i32_e64 s[0:1], 17, v3
	s_waitcnt vmcnt(11)
	v_mfma_f32_16x16x32_bf16 v[156:159], v[84:87], v[164:167], 0
	s_or_b64 s[24:25], vcc, s[0:1]
	v_cmp_lt_i32_e32 vcc, 18, v2
	v_cmp_gt_i32_e64 s[0:1], 18, v3
	s_or_b64 s[22:23], vcc, s[0:1]
	v_cmp_lt_i32_e32 vcc, 19, v2
	v_cmp_gt_i32_e64 s[0:1], 19, v3
	v_mfma_f32_16x16x32_bf16 v[152:155], v[76:79], v[168:171], v[152:155]
	s_or_b64 s[12:13], vcc, s[0:1]
	v_cmp_lt_i32_e32 vcc, 32, v2
	v_cmp_gt_i32_e64 s[0:1], 32, v3
	s_waitcnt vmcnt(9)
	v_mfma_f32_16x16x32_bf16 v[160:163], v[92:95], v[164:167], 0
	v_max_f32_e32 v164, v148, v148
	v_max_f32_e32 v164, 0xf149f2ca, v164
	v_cndmask_b32_e64 v165, v149, v217, s[20:21]
	s_or_b64 s[16:17], vcc, s[0:1]
	v_cmp_lt_i32_e32 vcc, 33, v2
	v_cmp_gt_i32_e64 s[0:1], 33, v3
	v_mfma_f32_16x16x32_bf16 v[156:159], v[88:91], v[168:171], v[156:159]
	v_cndmask_b32_e64 v164, v164, v217, s[10:11]
	v_max_f32_e32 v165, v165, v165
	s_or_b64 s[14:15], vcc, s[0:1]
	v_cmp_lt_i32_e32 vcc, 34, v2
	v_cmp_gt_i32_e64 s[0:1], 34, v3
	v_max_f32_e32 v164, v164, v165
	v_cndmask_b32_e64 v165, v150, v217, s[26:27]
	v_cndmask_b32_e64 v166, v151, v217, s[18:19]
	s_or_b64 s[8:9], vcc, s[0:1]
	v_cmp_lt_i32_e32 vcc, 35, v2
	v_cmp_gt_i32_e64 s[0:1], 35, v3
	s_waitcnt vmcnt(8)
; template <bool MASK>
; __device__ __forceinline__ void online_chunk(const KV& b, int base, int lo, int hi, const bf16x8* qst, int fq, float& m,
;                                              float& l, f32x4 (&oacc)[4], const int lane) {
;     ...
; #pragma unroll
;   for (int tile = 0; tile < 4; ++tile)
; #pragma unroll
;     for (int j = 0; j < 4; ++j) {
;       float v = s[tile][j];
;       if (MASK) { const bool ok = (tile * 16 + j >= klo) && (tile * 16 + j <= khi); v = ok ? v : NEGF; }
;       cm = fmaxf(cm, v);
;     }
;   cm = rows_max(cm);
;   const float mn = fmaxf(m, cm * SC_LOG2);
;   const float alpha = __builtin_amdgcn_exp2f(m - mn);
;   float ls = 0.f;
; #pragma unroll
;   for (int tile = 0; tile < 4; ++tile)
; #pragma unroll
;     for (int j = 0; j < 4; ++j) {
;       float pp = __builtin_amdgcn_exp2f(__builtin_fmaf(s[tile][j], SC_LOG2, -mn));
;       if (MASK) { const bool ok = (tile * 16 + j >= klo) && (tile * 16 + j <= khi); pp = ok ? pp : 0.f; }
;       s[tile][j] = pp;
;       ls += pp;
;     }
;   ls = rows_sum(ls);
;   l = l * alpha + ls;
;   m = mn;
; #pragma unroll
;   for (int dt = 0; dt < 4; ++dt) oacc[dt] *= alpha;
;   pv_from(b, s, oacc);
	v_mfma_f32_16x16x32_bf16 v[160:163], v[96:99], v[168:171], v[160:163]
	v_max3_f32 v164, v164, v165, v166
	v_cndmask_b32_e64 v165, v152, v217, s[28:29]
	v_cndmask_b32_e64 v166, v153, v217, s[24:25]
	s_or_b64 s[2:3], vcc, s[0:1]
	v_cmp_lt_i32_e32 vcc, 48, v2
	v_cmp_gt_i32_e64 s[0:1], 48, v3
	v_max3_f32 v164, v164, v165, v166
	v_cndmask_b32_e64 v165, v154, v217, s[22:23]
	v_cndmask_b32_e64 v166, v155, v217, s[12:13]
	s_or_b64 s[6:7], vcc, s[0:1]
	v_cmp_lt_i32_e32 vcc, 49, v2
	v_cmp_gt_i32_e64 s[0:1], 49, v3
	v_max3_f32 v164, v164, v165, v166
	v_cndmask_b32_e64 v165, v156, v217, s[16:17]
	v_cndmask_b32_e64 v166, v157, v217, s[14:15]
	s_or_b64 s[4:5], vcc, s[0:1]
	v_cmp_lt_i32_e32 vcc, 50, v2
	v_cmp_gt_i32_e64 s[0:1], 50, v3
	v_max3_f32 v164, v164, v165, v166
	v_cndmask_b32_e64 v165, v158, v217, s[8:9]
	v_cndmask_b32_e64 v166, v159, v217, s[2:3]
	s_or_b64 s[0:1], vcc, s[0:1]
	v_cmp_lt_i32_e32 vcc, 51, v2
	v_cmp_gt_i32_e64 s[34:35], 51, v3
	v_max3_f32 v164, v164, v165, v166
	v_cndmask_b32_e64 v165, v160, v217, s[6:7]
	v_cndmask_b32_e64 v166, v161, v217, s[4:5]
	s_or_b64 vcc, vcc, s[34:35]
	v_max3_f32 v164, v164, v165, v166
	v_cndmask_b32_e64 v165, v162, v217, s[0:1]
	v_cndmask_b32_e32 v2, v163, v217, vcc
	v_max3_f32 v2, v164, v165, v2
	v_mov_b32_e32 v3, v2
	s_nop 1
	v_permlane16_swap_b32_e32 v2, v3
	v_max_f32_e32 v3, v3, v3
	v_max_f32_e32 v2, v2, v2
	v_max_f32_e32 v2, v2, v3
	v_mov_b32_e32 v3, v2
	s_nop 1
	v_permlane32_swap_b32_e32 v2, v3
	v_max_f32_e32 v3, v3, v3
	v_max_f32_e32 v2, v2, v2
	v_max_f32_e32 v2, v2, v3
	v_mul_f32_e32 v2, 0x3e38aa3b, v2
	v_max_f32_e32 v2, v0, v2
	v_fma_f32 v0, v148, s49, -v2
	v_exp_f32_e32 v0, v0
	v_sub_f32_e32 v3, v181, v2
	v_cndmask_b32_e64 v148, v0, 0, s[10:11]
	v_fma_f32 v0, v149, s49, -v2
	v_exp_f32_e32 v0, v0
	s_nop 0
	v_cndmask_b32_e64 v149, v0, 0, s[20:21]
	v_fma_f32 v0, v150, s49, -v2
	v_exp_f32_e32 v0, v0
	s_nop 0
	v_cndmask_b32_e64 v150, v0, 0, s[26:27]
	v_fma_f32 v0, v151, s49, -v2
	v_exp_f32_e32 v0, v0
	s_nop 0
	v_cndmask_b32_e64 v151, v0, 0, s[18:19]
	v_fma_f32 v0, v152, s49, -v2
	v_exp_f32_e32 v0, v0
	s_nop 0
	v_cndmask_b32_e64 v152, v0, 0, s[28:29]
	v_fma_f32 v0, v153, s49, -v2
	v_exp_f32_e32 v0, v0
	s_nop 0
	v_cndmask_b32_e64 v153, v0, 0, s[24:25]
	v_fma_f32 v0, v154, s49, -v2
	v_exp_f32_e32 v0, v0
	s_nop 0
	v_cndmask_b32_e64 v154, v0, 0, s[22:23]
	v_fma_f32 v0, v155, s49, -v2
	v_exp_f32_e32 v0, v0
	s_nop 0
	v_cndmask_b32_e64 v155, v0, 0, s[12:13]
	v_fma_f32 v0, v156, s49, -v2
	v_exp_f32_e32 v0, v0
	s_nop 0
	v_cndmask_b32_e64 v156, v0, 0, s[16:17]
	v_fma_f32 v0, v157, s49, -v2
	v_exp_f32_e32 v0, v0
	s_nop 0
	v_cndmask_b32_e64 v157, v0, 0, s[14:15]
	v_fma_f32 v0, v158, s49, -v2
	v_exp_f32_e32 v0, v0
	s_nop 0
	v_cndmask_b32_e64 v158, v0, 0, s[8:9]
	v_fma_f32 v0, v159, s49, -v2
	v_exp_f32_e32 v0, v0
	s_nop 0
	v_cndmask_b32_e64 v159, v0, 0, s[2:3]
	v_fma_f32 v0, v160, s49, -v2
	v_exp_f32_e32 v0, v0
	s_nop 0
	v_cndmask_b32_e64 v164, v0, 0, s[6:7]
	v_fma_f32 v0, v161, s49, -v2
	v_exp_f32_e32 v0, v0
	v_cvt_pk_bf16_f32 v161, v158, v159
	v_cndmask_b32_e64 v165, v0, 0, s[4:5]
	v_fma_f32 v0, v162, s49, -v2
	v_exp_f32_e32 v0, v0
	v_cvt_pk_bf16_f32 v162, v164, v165
	v_cndmask_b32_e64 v166, v0, 0, s[0:1]
	v_fma_f32 v0, v163, s49, -v2
	v_exp_f32_e32 v0, v0
	s_nop 0
	v_cndmask_b32_e64 v163, v0, 0, vcc
	v_add_f32_e32 v0, 0, v148
	v_add_f32_e32 v0, v149, v0
	v_add_f32_e32 v0, v150, v0
	v_add_f32_e32 v0, v151, v0
	v_add_f32_e32 v0, v152, v0
	v_add_f32_e32 v0, v153, v0
	v_add_f32_e32 v0, v154, v0
	v_add_f32_e32 v0, v155, v0
	v_add_f32_e32 v0, v156, v0
	v_add_f32_e32 v0, v157, v0
	v_add_f32_e32 v0, v158, v0
	v_add_f32_e32 v0, v159, v0
	v_add_f32_e32 v0, v164, v0
	v_add_f32_e32 v0, v165, v0
	v_add_f32_e32 v0, v166, v0
	v_add_f32_e32 v160, v163, v0
	v_exp_f32_e32 v0, v3
	v_mov_b32_e32 v3, v160
	s_nop 1
	v_permlane16_swap_b32_e32 v160, v3
	v_mul_f32_e32 v146, v0, v146
	v_mul_f32_e32 v147, v0, v147
	v_mul_f32_e32 v144, v0, v144
	v_mul_f32_e32 v145, v0, v145
	v_mul_f32_e32 v134, v0, v134
	v_mul_f32_e32 v135, v0, v135
	v_mul_f32_e32 v132, v0, v132
	v_mul_f32_e32 v133, v0, v133
	v_mul_f32_e32 v138, v0, v138
	v_mul_f32_e32 v139, v0, v139
	v_mul_f32_e32 v136, v0, v136
	v_mul_f32_e32 v137, v0, v137
	v_mul_f32_e32 v142, v0, v142
	v_mul_f32_e32 v143, v0, v143
	v_mul_f32_e32 v140, v0, v140
	v_mul_f32_e32 v141, v0, v141
	v_cvt_pk_bf16_f32 v148, v148, v149
	v_cvt_pk_bf16_f32 v149, v150, v151
	v_cvt_pk_bf16_f32 v150, v152, v153
	v_cvt_pk_bf16_f32 v151, v154, v155
	v_add_f32_e32 v3, v160, v3
	v_mov_b32_e32 v160, v3
	s_waitcnt vmcnt(0)
	v_mfma_f32_16x16x32_bf16 v[144:147], v[100:103], v[148:151], v[144:147]
	v_permlane32_swap_b32_e32 v3, v160
	v_add_f32_e32 v3, v3, v160
	v_mfma_f32_16x16x32_bf16 v[132:135], v[104:107], v[148:151], v[132:135]
	v_cvt_pk_bf16_f32 v160, v156, v157
	v_cvt_pk_bf16_f32 v163, v166, v163
	v_fmac_f32_e32 v3, v182, v0
	v_mfma_f32_16x16x32_bf16 v[136:139], v[108:111], v[148:151], v[136:139]
	v_mfma_f32_16x16x32_bf16 v[140:143], v[112:115], v[148:151], v[140:143]
	v_mfma_f32_16x16x32_bf16 v[148:151], v[116:119], v[160:163], v[144:147]
	v_mfma_f32_16x16x32_bf16 v[152:155], v[120:123], v[160:163], v[132:135]
	v_mfma_f32_16x16x32_bf16 v[156:159], v[124:127], v[160:163], v[136:139]
	v_mfma_f32_16x16x32_bf16 v[160:163], v[128:131], v[160:163], v[140:143]
	s_andn2_b64 vcc, exec, s[66:67]
	s_cbranch_vccz .LBB0_734

; __device__ __forceinline__ float sigmoid_f(float x) { return 1.f / (1.f + __expf(-x)); }
; template <int NT, int BM, int BN, bool PLAIN, int NSTAGE, bool EPI_LDS>
; __device__ __forceinline__ void gemm_tile(const Params& p, const GemmDesc& g, bf16_t* lds, const int tid) {
;     ...
;     for (int i = 0; i < NIT; ++i) {
;       const int id = tid + NT * i;
;       const int row = id / PPR, pc = id % PPR;
;       u32x4 v = *(const u32x4*)(ct + row * CST + pc * 8);
;       bf16_t* op = o + (long)(m0e + row) * ldo + n0e + pc * 8;
;       if (g.epi == E_MERGE0 || g.epi == E_MERGEN) {
;         const u32x4 gt = *(const u32x4*)(((bf16_t*)(p.ws + OFF_proj)) + (long)(m0e + row) * LDP + gcol + n0e + pc * 8);
;         u32x4 pv = u32x4{0u, 0u, 0u, 0u};
;         if (g.epi == E_MERGEN) pv = *(const u32x4*)op;
; #pragma unroll
;         for (int e = 0; e < 4; ++e) {
;           const float g0 = sigmoid_f(__uint_as_float(gt[e] << 16)), g1 = sigmoid_f(__uint_as_float(gt[e] & 0xffff0000u));
;           const float a0 = __uint_as_float(v[e] << 16), a1 = __uint_as_float(v[e] & 0xffff0000u);
;           const float p0 = __uint_as_float(pv[e] << 16), p1 = __uint_as_float(pv[e] & 0xffff0000u);
;           v[e] = pack2(p0 + g0 * a0, p1 + g1 * a1);
;         }
;       }
;       *(u32x4*)op = v;
.Lmy_merge0_loop:
	ds_read_b128 v[148:151], v18
	v_add_u32_e32 v18, 0x2200, v18
	s_waitcnt vmcnt(3)
	v_lshlrev_b32_e32 v2, 16, v186
	v_and_b32_e32 v3, 0xffff0000, v186
	v_mul_f32_e32 v2, 0xbfb8aa3b, v2
	v_mul_f32_e32 v3, 0xbfb8aa3b, v3
	v_exp_f32_e32 v2, v2
	v_exp_f32_e32 v3, v3
	v_add_f32_e32 v2, 1.0, v2
	v_add_f32_e32 v3, 1.0, v3
	v_div_scale_f32 v5, s[30:31], v3, v3, 1.0
	v_div_scale_f32 v4, s[30:31], v2, v2, 1.0
	v_rcp_f32_e32 v7, v5
	v_rcp_f32_e32 v6, v4
	v_fma_f32 v9, -v5, v7, 1.0
	v_fma_f32 v8, -v4, v6, 1.0
	v_fmac_f32_e32 v7, v9, v7
	v_fmac_f32_e32 v6, v8, v6
	v_div_scale_f32 v9, vcc, 1.0, v3, 1.0
	v_mul_f32_e32 v11, v9, v7
	v_fma_f32 v13, -v5, v11, v9
	v_fmac_f32_e32 v11, v13, v7
	v_fma_f32 v5, -v5, v11, v9
	v_div_fmas_f32 v5, v5, v7, v11
	v_div_fixup_f32 v3, v5, v3, 1.0
	v_div_scale_f32 v8, vcc, 1.0, v2, 1.0
	v_mul_f32_e32 v10, v8, v6
	v_fma_f32 v12, -v4, v10, v8
	v_fmac_f32_e32 v10, v12, v6
	v_fma_f32 v4, -v4, v10, v8
	v_div_fmas_f32 v4, v4, v6, v10
	v_div_fixup_f32 v2, v4, v2, 1.0
	s_waitcnt lgkmcnt(0)
	v_lshlrev_b32_e32 v14, 16, v148
	v_and_b32_e32 v15, 0xffff0000, v148
	v_fma_f32 v2, v2, v14, v16
	v_fma_f32 v3, v3, v15, v17
	v_cvt_pk_bf16_f32 v156, v2, v3
	v_lshlrev_b32_e32 v2, 16, v187
	v_and_b32_e32 v3, 0xffff0000, v187
	v_mul_f32_e32 v2, 0xbfb8aa3b, v2
	v_mul_f32_e32 v3, 0xbfb8aa3b, v3
	v_exp_f32_e32 v2, v2
	v_exp_f32_e32 v3, v3
	v_add_f32_e32 v2, 1.0, v2
	v_add_f32_e32 v3, 1.0, v3
	v_div_scale_f32 v5, s[30:31], v3, v3, 1.0
	v_div_scale_f32 v4, s[30:31], v2, v2, 1.0
	v_rcp_f32_e32 v7, v5
	v_rcp_f32_e32 v6, v4
	v_fma_f32 v9, -v5, v7, 1.0
	v_fma_f32 v8, -v4, v6, 1.0
	v_fmac_f32_e32 v7, v9, v7
	v_fmac_f32_e32 v6, v8, v6
	v_div_scale_f32 v9, vcc, 1.0, v3, 1.0
	v_mul_f32_e32 v11, v9, v7
	v_fma_f32 v13, -v5, v11, v9
	v_fmac_f32_e32 v11, v13, v7
	v_fma_f32 v5, -v5, v11, v9
	v_div_fmas_f32 v5, v5, v7, v11
	v_div_fixup_f32 v3, v5, v3, 1.0
	v_div_scale_f32 v8, vcc, 1.0, v2, 1.0
	v_mul_f32_e32 v10, v8, v6
	v_fma_f32 v12, -v4, v10, v8
	v_fmac_f32_e32 v10, v12, v6
	v_fma_f32 v4, -v4, v10, v8
	v_div_fmas_f32 v4, v4, v6, v10
	v_div_fixup_f32 v2, v4, v2, 1.0
	v_lshlrev_b32_e32 v14, 16, v149
	v_and_b32_e32 v15, 0xffff0000, v149
	v_fma_f32 v2, v2, v14, v16
	v_fma_f32 v3, v3, v15, v17
	v_cvt_pk_bf16_f32 v157, v2, v3
	v_lshlrev_b32_e32 v2, 16, v188
	v_and_b32_e32 v3, 0xffff0000, v188
	v_mul_f32_e32 v2, 0xbfb8aa3b, v2
	v_mul_f32_e32 v3, 0xbfb8aa3b, v3
	v_exp_f32_e32 v2, v2
	v_exp_f32_e32 v3, v3
	v_add_f32_e32 v2, 1.0, v2
	v_add_f32_e32 v3, 1.0, v3
	v_div_scale_f32 v5, s[30:31], v3, v3, 1.0
	v_div_scale_f32 v4, s[30:31], v2, v2, 1.0
	v_rcp_f32_e32 v7, v5
	v_rcp_f32_e32 v6, v4
	v_fma_f32 v9, -v5, v7, 1.0
	v_fma_f32 v8, -v4, v6, 1.0
	v_fmac_f32_e32 v7, v9, v7
	v_fmac_f32_e32 v6, v8, v6
	v_div_scale_f32 v9, vcc, 1.0, v3, 1.0
	v_mul_f32_e32 v11, v9, v7
	v_fma_f32 v13, -v5, v11, v9
	v_fmac_f32_e32 v11, v13, v7
	v_fma_f32 v5, -v5, v11, v9
	v_div_fmas_f32 v5, v5, v7, v11
	v_div_fixup_f32 v3, v5, v3, 1.0
	v_div_scale_f32 v8, vcc, 1.0, v2, 1.0
	v_mul_f32_e32 v10, v8, v6
	v_fma_f32 v12, -v4, v10, v8
	v_fmac_f32_e32 v10, v12, v6
	v_fma_f32 v4, -v4, v10, v8
	v_div_fmas_f32 v4, v4, v6, v10
	v_div_fixup_f32 v2, v4, v2, 1.0
	v_lshlrev_b32_e32 v14, 16, v150
	v_and_b32_e32 v15, 0xffff0000, v150
	v_fma_f32 v2, v2, v14, v16
	v_fma_f32 v3, v3, v15, v17
	v_cvt_pk_bf16_f32 v158, v2, v3
	v_lshlrev_b32_e32 v2, 16, v189
	v_and_b32_e32 v3, 0xffff0000, v189
	v_mul_f32_e32 v2, 0xbfb8aa3b, v2
	v_mul_f32_e32 v3, 0xbfb8aa3b, v3
	v_exp_f32_e32 v2, v2
	v_exp_f32_e32 v3, v3
	v_add_f32_e32 v2, 1.0, v2
	v_add_f32_e32 v3, 1.0, v3
	v_div_scale_f32 v5, s[30:31], v3, v3, 1.0
	v_div_scale_f32 v4, s[30:31], v2, v2, 1.0
	v_rcp_f32_e32 v7, v5
	v_rcp_f32_e32 v6, v4
	v_fma_f32 v9, -v5, v7, 1.0
	v_fma_f32 v8, -v4, v6, 1.0
	v_fmac_f32_e32 v7, v9, v7
	v_fmac_f32_e32 v6, v8, v6
	v_div_scale_f32 v9, vcc, 1.0, v3, 1.0
	v_mul_f32_e32 v11, v9, v7
	v_fma_f32 v13, -v5, v11, v9
	v_fmac_f32_e32 v11, v13, v7
	v_fma_f32 v5, -v5, v11, v9
	v_div_fmas_f32 v5, v5, v7, v11
	v_div_fixup_f32 v3, v5, v3, 1.0
	v_div_scale_f32 v8, vcc, 1.0, v2, 1.0
	v_mul_f32_e32 v10, v8, v6
	v_fma_f32 v12, -v4, v10, v8
	v_fmac_f32_e32 v10, v12, v6
	v_fma_f32 v4, -v4, v10, v8
	v_div_fmas_f32 v4, v4, v6, v10
	v_div_fixup_f32 v2, v4, v2, 1.0
	v_lshlrev_b32_e32 v14, 16, v151
	v_and_b32_e32 v15, 0xffff0000, v151
	v_fma_f32 v2, v2, v14, v16
	v_fma_f32 v3, v3, v15, v17
	v_cvt_pk_bf16_f32 v159, v2, v3
	global_load_dwordx4 v[186:189], v160, s[60:61]
	s_add_u32 s60, s60, 0x51000
	s_addc_u32 s61, s61, 0
	global_store_dwordx4 v19, v[156:159], s[64:65]
	s_add_u32 s64, s64, 0x10000
	s_addc_u32 s65, s65, 0
	ds_read_b128 v[148:151], v18
	v_add_u32_e32 v18, 0x2200, v18
	s_waitcnt vmcnt(4)
	v_lshlrev_b32_e32 v2, 16, v190
	v_and_b32_e32 v3, 0xffff0000, v190
	v_mul_f32_e32 v2, 0xbfb8aa3b, v2
	v_mul_f32_e32 v3, 0xbfb8aa3b, v3
	v_exp_f32_e32 v2, v2
	v_exp_f32_e32 v3, v3
	v_add_f32_e32 v2, 1.0, v2
	v_add_f32_e32 v3, 1.0, v3
	v_div_scale_f32 v5, s[30:31], v3, v3, 1.0
	v_div_scale_f32 v4, s[30:31], v2, v2, 1.0
	v_rcp_f32_e32 v7, v5
	v_rcp_f32_e32 v6, v4
	v_fma_f32 v9, -v5, v7, 1.0
	v_fma_f32 v8, -v4, v6, 1.0
	v_fmac_f32_e32 v7, v9, v7
	v_fmac_f32_e32 v6, v8, v6
	v_div_scale_f32 v9, vcc, 1.0, v3, 1.0
	v_mul_f32_e32 v11, v9, v7
	v_fma_f32 v13, -v5, v11, v9
	v_fmac_f32_e32 v11, v13, v7
	v_fma_f32 v5, -v5, v11, v9
	v_div_fmas_f32 v5, v5, v7, v11
	v_div_fixup_f32 v3, v5, v3, 1.0
	v_div_scale_f32 v8, vcc, 1.0, v2, 1.0
	v_mul_f32_e32 v10, v8, v6
	v_fma_f32 v12, -v4, v10, v8
	v_fmac_f32_e32 v10, v12, v6
	v_fma_f32 v4, -v4, v10, v8
	v_div_fmas_f32 v4, v4, v6, v10
	v_div_fixup_f32 v2, v4, v2, 1.0
	s_waitcnt lgkmcnt(0)
; __device__ __forceinline__ float sigmoid_f(float x) { return 1.f / (1.f + __expf(-x)); }
; template <int NT, int BM, int BN, bool PLAIN, int NSTAGE, bool EPI_LDS>
; __device__ __forceinline__ void gemm_tile(const Params& p, const GemmDesc& g, bf16_t* lds, const int tid) {
;     ...
;     for (int i = 0; i < NIT; ++i) {
;       const int id = tid + NT * i;
;       const int row = id / PPR, pc = id % PPR;
;       u32x4 v = *(const u32x4*)(ct + row * CST + pc * 8);
;       bf16_t* op = o + (long)(m0e + row) * ldo + n0e + pc * 8;
;       if (g.epi == E_MERGE0 || g.epi == E_MERGEN) {
;         const u32x4 gt = *(const u32x4*)(((bf16_t*)(p.ws + OFF_proj)) + (long)(m0e + row) * LDP + gcol + n0e + pc * 8);
;         u32x4 pv = u32x4{0u, 0u, 0u, 0u};
;         if (g.epi == E_MERGEN) pv = *(const u32x4*)op;
; #pragma unroll
;         for (int e = 0; e < 4; ++e) {
;           const float g0 = sigmoid_f(__uint_as_float(gt[e] << 16)), g1 = sigmoid_f(__uint_as_float(gt[e] & 0xffff0000u));
;           const float a0 = __uint_as_float(v[e] << 16), a1 = __uint_as_float(v[e] & 0xffff0000u);
;           const float p0 = __uint_as_float(pv[e] << 16), p1 = __uint_as_float(pv[e] & 0xffff0000u);
;           v[e] = pack2(p0 + g0 * a0, p1 + g1 * a1);
;         }
;       }
;       *(u32x4*)op = v;
	v_lshlrev_b32_e32 v14, 16, v148
	v_and_b32_e32 v15, 0xffff0000, v148
	v_fma_f32 v2, v2, v14, v16
	v_fma_f32 v3, v3, v15, v17
	v_cvt_pk_bf16_f32 v156, v2, v3
	v_lshlrev_b32_e32 v2, 16, v191
	v_and_b32_e32 v3, 0xffff0000, v191
	v_mul_f32_e32 v2, 0xbfb8aa3b, v2
	v_mul_f32_e32 v3, 0xbfb8aa3b, v3
	v_exp_f32_e32 v2, v2
	v_exp_f32_e32 v3, v3
	v_add_f32_e32 v2, 1.0, v2
	v_add_f32_e32 v3, 1.0, v3
	v_div_scale_f32 v5, s[30:31], v3, v3, 1.0
	v_div_scale_f32 v4, s[30:31], v2, v2, 1.0
	v_rcp_f32_e32 v7, v5
	v_rcp_f32_e32 v6, v4
	v_fma_f32 v9, -v5, v7, 1.0
	v_fma_f32 v8, -v4, v6, 1.0
	v_fmac_f32_e32 v7, v9, v7
	v_fmac_f32_e32 v6, v8, v6
	v_div_scale_f32 v9, vcc, 1.0, v3, 1.0
	v_mul_f32_e32 v11, v9, v7
	v_fma_f32 v13, -v5, v11, v9
	v_fmac_f32_e32 v11, v13, v7
	v_fma_f32 v5, -v5, v11, v9
	v_div_fmas_f32 v5, v5, v7, v11
	v_div_fixup_f32 v3, v5, v3, 1.0
	v_div_scale_f32 v8, vcc, 1.0, v2, 1.0
	v_mul_f32_e32 v10, v8, v6
	v_fma_f32 v12, -v4, v10, v8
	v_fmac_f32_e32 v10, v12, v6
	v_fma_f32 v4, -v4, v10, v8
	v_div_fmas_f32 v4, v4, v6, v10
	v_div_fixup_f32 v2, v4, v2, 1.0
	v_lshlrev_b32_e32 v14, 16, v149
	v_and_b32_e32 v15, 0xffff0000, v149
	v_fma_f32 v2, v2, v14, v16
	v_fma_f32 v3, v3, v15, v17
	v_cvt_pk_bf16_f32 v157, v2, v3
	v_lshlrev_b32_e32 v2, 16, v192
	v_and_b32_e32 v3, 0xffff0000, v192
	v_mul_f32_e32 v2, 0xbfb8aa3b, v2
	v_mul_f32_e32 v3, 0xbfb8aa3b, v3
	v_exp_f32_e32 v2, v2
	v_exp_f32_e32 v3, v3
	v_add_f32_e32 v2, 1.0, v2
	v_add_f32_e32 v3, 1.0, v3
	v_div_scale_f32 v5, s[30:31], v3, v3, 1.0
	v_div_scale_f32 v4, s[30:31], v2, v2, 1.0
	v_rcp_f32_e32 v7, v5
	v_rcp_f32_e32 v6, v4
	v_fma_f32 v9, -v5, v7, 1.0
	v_fma_f32 v8, -v4, v6, 1.0
	v_fmac_f32_e32 v7, v9, v7
	v_fmac_f32_e32 v6, v8, v6
	v_div_scale_f32 v9, vcc, 1.0, v3, 1.0
	v_mul_f32_e32 v11, v9, v7
	v_fma_f32 v13, -v5, v11, v9
	v_fmac_f32_e32 v11, v13, v7
	v_fma_f32 v5, -v5, v11, v9
	v_div_fmas_f32 v5, v5, v7, v11
	v_div_fixup_f32 v3, v5, v3, 1.0
	v_div_scale_f32 v8, vcc, 1.0, v2, 1.0
	v_mul_f32_e32 v10, v8, v6
	v_fma_f32 v12, -v4, v10, v8
	v_fmac_f32_e32 v10, v12, v6
	v_fma_f32 v4, -v4, v10, v8
	v_div_fmas_f32 v4, v4, v6, v10
	v_div_fixup_f32 v2, v4, v2, 1.0
	v_lshlrev_b32_e32 v14, 16, v150
	v_and_b32_e32 v15, 0xffff0000, v150
	v_fma_f32 v2, v2, v14, v16
	v_fma_f32 v3, v3, v15, v17
	v_cvt_pk_bf16_f32 v158, v2, v3
	v_lshlrev_b32_e32 v2, 16, v193
	v_and_b32_e32 v3, 0xffff0000, v193
	v_mul_f32_e32 v2, 0xbfb8aa3b, v2
	v_mul_f32_e32 v3, 0xbfb8aa3b, v3
	v_exp_f32_e32 v2, v2
	v_exp_f32_e32 v3, v3
	v_add_f32_e32 v2, 1.0, v2
	v_add_f32_e32 v3, 1.0, v3
	v_div_scale_f32 v5, s[30:31], v3, v3, 1.0
	v_div_scale_f32 v4, s[30:31], v2, v2, 1.0
	v_rcp_f32_e32 v7, v5
	v_rcp_f32_e32 v6, v4
	v_fma_f32 v9, -v5, v7, 1.0
	v_fma_f32 v8, -v4, v6, 1.0
	v_fmac_f32_e32 v7, v9, v7
	v_fmac_f32_e32 v6, v8, v6
	v_div_scale_f32 v9, vcc, 1.0, v3, 1.0
	v_mul_f32_e32 v11, v9, v7
	v_fma_f32 v13, -v5, v11, v9
	v_fmac_f32_e32 v11, v13, v7
	v_fma_f32 v5, -v5, v11, v9
	v_div_fmas_f32 v5, v5, v7, v11
	v_div_fixup_f32 v3, v5, v3, 1.0
	v_div_scale_f32 v8, vcc, 1.0, v2, 1.0
	v_mul_f32_e32 v10, v8, v6
	v_fma_f32 v12, -v4, v10, v8
	v_fmac_f32_e32 v10, v12, v6
	v_fma_f32 v4, -v4, v10, v8
	v_div_fmas_f32 v4, v4, v6, v10
	v_div_fixup_f32 v2, v4, v2, 1.0
	v_lshlrev_b32_e32 v14, 16, v151
	v_and_b32_e32 v15, 0xffff0000, v151
	v_fma_f32 v2, v2, v14, v16
	v_fma_f32 v3, v3, v15, v17
	v_cvt_pk_bf16_f32 v159, v2, v3
	global_load_dwordx4 v[190:193], v160, s[60:61]
	s_add_u32 s60, s60, 0x51000
	s_addc_u32 s61, s61, 0
	global_store_dwordx4 v19, v[156:159], s[64:65]
	s_add_u32 s64, s64, 0x10000
	s_addc_u32 s65, s65, 0
	ds_read_b128 v[148:151], v18
	v_add_u32_e32 v18, 0x2200, v18
	s_waitcnt vmcnt(5)
	v_lshlrev_b32_e32 v2, 16, v194
	v_and_b32_e32 v3, 0xffff0000, v194
	v_mul_f32_e32 v2, 0xbfb8aa3b, v2
	v_mul_f32_e32 v3, 0xbfb8aa3b, v3
	v_exp_f32_e32 v2, v2
	v_exp_f32_e32 v3, v3
	v_add_f32_e32 v2, 1.0, v2
	v_add_f32_e32 v3, 1.0, v3
	v_div_scale_f32 v5, s[30:31], v3, v3, 1.0
	v_div_scale_f32 v4, s[30:31], v2, v2, 1.0
	v_rcp_f32_e32 v7, v5
	v_rcp_f32_e32 v6, v4
	v_fma_f32 v9, -v5, v7, 1.0
	v_fma_f32 v8, -v4, v6, 1.0
	v_fmac_f32_e32 v7, v9, v7
	v_fmac_f32_e32 v6, v8, v6
	v_div_scale_f32 v9, vcc, 1.0, v3, 1.0
	v_mul_f32_e32 v11, v9, v7
	v_fma_f32 v13, -v5, v11, v9
	v_fmac_f32_e32 v11, v13, v7
	v_fma_f32 v5, -v5, v11, v9
	v_div_fmas_f32 v5, v5, v7, v11
	v_div_fixup_f32 v3, v5, v3, 1.0
	v_div_scale_f32 v8, vcc, 1.0, v2, 1.0
	v_mul_f32_e32 v10, v8, v6
	v_fma_f32 v12, -v4, v10, v8
	v_fmac_f32_e32 v10, v12, v6
	v_fma_f32 v4, -v4, v10, v8
	v_div_fmas_f32 v4, v4, v6, v10
	v_div_fixup_f32 v2, v4, v2, 1.0
	s_waitcnt lgkmcnt(0)
; __device__ __forceinline__ float sigmoid_f(float x) { return 1.f / (1.f + __expf(-x)); }
; template <int NT, int BM, int BN, bool PLAIN, int NSTAGE, bool EPI_LDS>
; __device__ __forceinline__ void gemm_tile(const Params& p, const GemmDesc& g, bf16_t* lds, const int tid) {
;     ...
;     for (int i = 0; i < NIT; ++i) {
;       const int id = tid + NT * i;
;       const int row = id / PPR, pc = id % PPR;
;       u32x4 v = *(const u32x4*)(ct + row * CST + pc * 8);
;       bf16_t* op = o + (long)(m0e + row) * ldo + n0e + pc * 8;
;       if (g.epi == E_MERGE0 || g.epi == E_MERGEN) {
;         const u32x4 gt = *(const u32x4*)(((bf16_t*)(p.ws + OFF_proj)) + (long)(m0e + row) * LDP + gcol + n0e + pc * 8);
;         u32x4 pv = u32x4{0u, 0u, 0u, 0u};
;         if (g.epi == E_MERGEN) pv = *(const u32x4*)op;
; #pragma unroll
;         for (int e = 0; e < 4; ++e) {
;           const float g0 = sigmoid_f(__uint_as_float(gt[e] << 16)), g1 = sigmoid_f(__uint_as_float(gt[e] & 0xffff0000u));
;           const float a0 = __uint_as_float(v[e] << 16), a1 = __uint_as_float(v[e] & 0xffff0000u);
;           const float p0 = __uint_as_float(pv[e] << 16), p1 = __uint_as_float(pv[e] & 0xffff0000u);
;           v[e] = pack2(p0 + g0 * a0, p1 + g1 * a1);
;         }
;       }
;       *(u32x4*)op = v;
	v_lshlrev_b32_e32 v14, 16, v148
	v_and_b32_e32 v15, 0xffff0000, v148
	v_fma_f32 v2, v2, v14, v16
	v_fma_f32 v3, v3, v15, v17
	v_cvt_pk_bf16_f32 v156, v2, v3
	v_lshlrev_b32_e32 v2, 16, v195
	v_and_b32_e32 v3, 0xffff0000, v195
	v_mul_f32_e32 v2, 0xbfb8aa3b, v2
	v_mul_f32_e32 v3, 0xbfb8aa3b, v3
	v_exp_f32_e32 v2, v2
	v_exp_f32_e32 v3, v3
	v_add_f32_e32 v2, 1.0, v2
	v_add_f32_e32 v3, 1.0, v3
	v_div_scale_f32 v5, s[30:31], v3, v3, 1.0
	v_div_scale_f32 v4, s[30:31], v2, v2, 1.0
	v_rcp_f32_e32 v7, v5
	v_rcp_f32_e32 v6, v4
	v_fma_f32 v9, -v5, v7, 1.0
	v_fma_f32 v8, -v4, v6, 1.0
	v_fmac_f32_e32 v7, v9, v7
	v_fmac_f32_e32 v6, v8, v6
	v_div_scale_f32 v9, vcc, 1.0, v3, 1.0
	v_mul_f32_e32 v11, v9, v7
	v_fma_f32 v13, -v5, v11, v9
	v_fmac_f32_e32 v11, v13, v7
	v_fma_f32 v5, -v5, v11, v9
	v_div_fmas_f32 v5, v5, v7, v11
	v_div_fixup_f32 v3, v5, v3, 1.0
	v_div_scale_f32 v8, vcc, 1.0, v2, 1.0
	v_mul_f32_e32 v10, v8, v6
	v_fma_f32 v12, -v4, v10, v8
	v_fmac_f32_e32 v10, v12, v6
	v_fma_f32 v4, -v4, v10, v8
	v_div_fmas_f32 v4, v4, v6, v10
	v_div_fixup_f32 v2, v4, v2, 1.0
	v_lshlrev_b32_e32 v14, 16, v149
	v_and_b32_e32 v15, 0xffff0000, v149
	v_fma_f32 v2, v2, v14, v16
	v_fma_f32 v3, v3, v15, v17
	v_cvt_pk_bf16_f32 v157, v2, v3
	v_lshlrev_b32_e32 v2, 16, v196
	v_and_b32_e32 v3, 0xffff0000, v196
	v_mul_f32_e32 v2, 0xbfb8aa3b, v2
	v_mul_f32_e32 v3, 0xbfb8aa3b, v3
	v_exp_f32_e32 v2, v2
	v_exp_f32_e32 v3, v3
	v_add_f32_e32 v2, 1.0, v2
	v_add_f32_e32 v3, 1.0, v3
	v_div_scale_f32 v5, s[30:31], v3, v3, 1.0
	v_div_scale_f32 v4, s[30:31], v2, v2, 1.0
	v_rcp_f32_e32 v7, v5
	v_rcp_f32_e32 v6, v4
	v_fma_f32 v9, -v5, v7, 1.0
	v_fma_f32 v8, -v4, v6, 1.0
	v_fmac_f32_e32 v7, v9, v7
	v_fmac_f32_e32 v6, v8, v6
	v_div_scale_f32 v9, vcc, 1.0, v3, 1.0
	v_mul_f32_e32 v11, v9, v7
	v_fma_f32 v13, -v5, v11, v9
	v_fmac_f32_e32 v11, v13, v7
	v_fma_f32 v5, -v5, v11, v9
	v_div_fmas_f32 v5, v5, v7, v11
	v_div_fixup_f32 v3, v5, v3, 1.0
	v_div_scale_f32 v8, vcc, 1.0, v2, 1.0
	v_mul_f32_e32 v10, v8, v6
	v_fma_f32 v12, -v4, v10, v8
	v_fmac_f32_e32 v10, v12, v6
	v_fma_f32 v4, -v4, v10, v8
	v_div_fmas_f32 v4, v4, v6, v10
	v_div_fixup_f32 v2, v4, v2, 1.0
	v_lshlrev_b32_e32 v14, 16, v150
	v_and_b32_e32 v15, 0xffff0000, v150
	v_fma_f32 v2, v2, v14, v16
	v_fma_f32 v3, v3, v15, v17
	v_cvt_pk_bf16_f32 v158, v2, v3
	v_lshlrev_b32_e32 v2, 16, v197
	v_and_b32_e32 v3, 0xffff0000, v197
	v_mul_f32_e32 v2, 0xbfb8aa3b, v2
	v_mul_f32_e32 v3, 0xbfb8aa3b, v3
	v_exp_f32_e32 v2, v2
	v_exp_f32_e32 v3, v3
	v_add_f32_e32 v2, 1.0, v2
	v_add_f32_e32 v3, 1.0, v3
	v_div_scale_f32 v5, s[30:31], v3, v3, 1.0
	v_div_scale_f32 v4, s[30:31], v2, v2, 1.0
	v_rcp_f32_e32 v7, v5
	v_rcp_f32_e32 v6, v4
	v_fma_f32 v9, -v5, v7, 1.0
	v_fma_f32 v8, -v4, v6, 1.0
	v_fmac_f32_e32 v7, v9, v7
	v_fmac_f32_e32 v6, v8, v6
	v_div_scale_f32 v9, vcc, 1.0, v3, 1.0
	v_mul_f32_e32 v11, v9, v7
	v_fma_f32 v13, -v5, v11, v9
	v_fmac_f32_e32 v11, v13, v7
	v_fma_f32 v5, -v5, v11, v9
	v_div_fmas_f32 v5, v5, v7, v11
	v_div_fixup_f32 v3, v5, v3, 1.0
	v_div_scale_f32 v8, vcc, 1.0, v2, 1.0
	v_mul_f32_e32 v10, v8, v6
	v_fma_f32 v12, -v4, v10, v8
	v_fmac_f32_e32 v10, v12, v6
	v_fma_f32 v4, -v4, v10, v8
	v_div_fmas_f32 v4, v4, v6, v10
	v_div_fixup_f32 v2, v4, v2, 1.0
	v_lshlrev_b32_e32 v14, 16, v151
	v_and_b32_e32 v15, 0xffff0000, v151
	v_fma_f32 v2, v2, v14, v16
	v_fma_f32 v3, v3, v15, v17
	v_cvt_pk_bf16_f32 v159, v2, v3
	global_load_dwordx4 v[194:197], v160, s[60:61]
	s_add_u32 s60, s60, 0x51000
	s_addc_u32 s61, s61, 0
	global_store_dwordx4 v19, v[156:159], s[64:65]
	s_add_u32 s64, s64, 0x10000
	s_addc_u32 s65, s65, 0
	ds_read_b128 v[148:151], v18
	v_add_u32_e32 v18, 0x2200, v18
	s_waitcnt vmcnt(6)
	v_lshlrev_b32_e32 v2, 16, v198
	v_and_b32_e32 v3, 0xffff0000, v198
	v_mul_f32_e32 v2, 0xbfb8aa3b, v2
	v_mul_f32_e32 v3, 0xbfb8aa3b, v3
	v_exp_f32_e32 v2, v2
	v_exp_f32_e32 v3, v3
	v_add_f32_e32 v2, 1.0, v2
	v_add_f32_e32 v3, 1.0, v3
	v_div_scale_f32 v5, s[30:31], v3, v3, 1.0
	v_div_scale_f32 v4, s[30:31], v2, v2, 1.0
	v_rcp_f32_e32 v7, v5
	v_rcp_f32_e32 v6, v4
	v_fma_f32 v9, -v5, v7, 1.0
	v_fma_f32 v8, -v4, v6, 1.0
	v_fmac_f32_e32 v7, v9, v7
	v_fmac_f32_e32 v6, v8, v6
	v_div_scale_f32 v9, vcc, 1.0, v3, 1.0
	v_mul_f32_e32 v11, v9, v7
	v_fma_f32 v13, -v5, v11, v9
	v_fmac_f32_e32 v11, v13, v7
	v_fma_f32 v5, -v5, v11, v9
	v_div_fmas_f32 v5, v5, v7, v11
	v_div_fixup_f32 v3, v5, v3, 1.0
	v_div_scale_f32 v8, vcc, 1.0, v2, 1.0
	v_mul_f32_e32 v10, v8, v6
	v_fma_f32 v12, -v4, v10, v8
	v_fmac_f32_e32 v10, v12, v6
	v_fma_f32 v4, -v4, v10, v8
	v_div_fmas_f32 v4, v4, v6, v10
	v_div_fixup_f32 v2, v4, v2, 1.0
	s_waitcnt lgkmcnt(0)
; __device__ __forceinline__ float sigmoid_f(float x) { return 1.f / (1.f + __expf(-x)); }
; template <int NT, int BM, int BN, bool PLAIN, int NSTAGE, bool EPI_LDS>
; __device__ __forceinline__ void gemm_tile(const Params& p, const GemmDesc& g, bf16_t* lds, const int tid) {
;     ...
;     for (int i = 0; i < NIT; ++i) {
;       const int id = tid + NT * i;
;       const int row = id / PPR, pc = id % PPR;
;       u32x4 v = *(const u32x4*)(ct + row * CST + pc * 8);
;       bf16_t* op = o + (long)(m0e + row) * ldo + n0e + pc * 8;
;       if (g.epi == E_MERGE0 || g.epi == E_MERGEN) {
;         const u32x4 gt = *(const u32x4*)(((bf16_t*)(p.ws + OFF_proj)) + (long)(m0e + row) * LDP + gcol + n0e + pc * 8);
;         u32x4 pv = u32x4{0u, 0u, 0u, 0u};
;         if (g.epi == E_MERGEN) pv = *(const u32x4*)op;
; #pragma unroll
;         for (int e = 0; e < 4; ++e) {
;           const float g0 = sigmoid_f(__uint_as_float(gt[e] << 16)), g1 = sigmoid_f(__uint_as_float(gt[e] & 0xffff0000u));
;           const float a0 = __uint_as_float(v[e] << 16), a1 = __uint_as_float(v[e] & 0xffff0000u);
;           const float p0 = __uint_as_float(pv[e] << 16), p1 = __uint_as_float(pv[e] & 0xffff0000u);
;           v[e] = pack2(p0 + g0 * a0, p1 + g1 * a1);
;         }
;       }
;       *(u32x4*)op = v;
	v_lshlrev_b32_e32 v14, 16, v148
	v_and_b32_e32 v15, 0xffff0000, v148
	v_fma_f32 v2, v2, v14, v16
	v_fma_f32 v3, v3, v15, v17
	v_cvt_pk_bf16_f32 v156, v2, v3
	v_lshlrev_b32_e32 v2, 16, v199
	v_and_b32_e32 v3, 0xffff0000, v199
	v_mul_f32_e32 v2, 0xbfb8aa3b, v2
	v_mul_f32_e32 v3, 0xbfb8aa3b, v3
	v_exp_f32_e32 v2, v2
	v_exp_f32_e32 v3, v3
	v_add_f32_e32 v2, 1.0, v2
	v_add_f32_e32 v3, 1.0, v3
	v_div_scale_f32 v5, s[30:31], v3, v3, 1.0
	v_div_scale_f32 v4, s[30:31], v2, v2, 1.0
	v_rcp_f32_e32 v7, v5
	v_rcp_f32_e32 v6, v4
	v_fma_f32 v9, -v5, v7, 1.0
	v_fma_f32 v8, -v4, v6, 1.0
	v_fmac_f32_e32 v7, v9, v7
	v_fmac_f32_e32 v6, v8, v6
	v_div_scale_f32 v9, vcc, 1.0, v3, 1.0
	v_mul_f32_e32 v11, v9, v7
	v_fma_f32 v13, -v5, v11, v9
	v_fmac_f32_e32 v11, v13, v7
	v_fma_f32 v5, -v5, v11, v9
	v_div_fmas_f32 v5, v5, v7, v11
	v_div_fixup_f32 v3, v5, v3, 1.0
	v_div_scale_f32 v8, vcc, 1.0, v2, 1.0
	v_mul_f32_e32 v10, v8, v6
	v_fma_f32 v12, -v4, v10, v8
	v_fmac_f32_e32 v10, v12, v6
	v_fma_f32 v4, -v4, v10, v8
	v_div_fmas_f32 v4, v4, v6, v10
	v_div_fixup_f32 v2, v4, v2, 1.0
	v_lshlrev_b32_e32 v14, 16, v149
	v_and_b32_e32 v15, 0xffff0000, v149
	v_fma_f32 v2, v2, v14, v16
	v_fma_f32 v3, v3, v15, v17
	v_cvt_pk_bf16_f32 v157, v2, v3
	v_lshlrev_b32_e32 v2, 16, v200
	v_and_b32_e32 v3, 0xffff0000, v200
	v_mul_f32_e32 v2, 0xbfb8aa3b, v2
	v_mul_f32_e32 v3, 0xbfb8aa3b, v3
	v_exp_f32_e32 v2, v2
	v_exp_f32_e32 v3, v3
	v_add_f32_e32 v2, 1.0, v2
	v_add_f32_e32 v3, 1.0, v3
	v_div_scale_f32 v5, s[30:31], v3, v3, 1.0
	v_div_scale_f32 v4, s[30:31], v2, v2, 1.0
	v_rcp_f32_e32 v7, v5
	v_rcp_f32_e32 v6, v4
	v_fma_f32 v9, -v5, v7, 1.0
	v_fma_f32 v8, -v4, v6, 1.0
	v_fmac_f32_e32 v7, v9, v7
	v_fmac_f32_e32 v6, v8, v6
	v_div_scale_f32 v9, vcc, 1.0, v3, 1.0
	v_mul_f32_e32 v11, v9, v7
	v_fma_f32 v13, -v5, v11, v9
	v_fmac_f32_e32 v11, v13, v7
	v_fma_f32 v5, -v5, v11, v9
	v_div_fmas_f32 v5, v5, v7, v11
	v_div_fixup_f32 v3, v5, v3, 1.0
	v_div_scale_f32 v8, vcc, 1.0, v2, 1.0
	v_mul_f32_e32 v10, v8, v6
	v_fma_f32 v12, -v4, v10, v8
	v_fmac_f32_e32 v10, v12, v6
	v_fma_f32 v4, -v4, v10, v8
	v_div_fmas_f32 v4, v4, v6, v10
	v_div_fixup_f32 v2, v4, v2, 1.0
	v_lshlrev_b32_e32 v14, 16, v150
	v_and_b32_e32 v15, 0xffff0000, v150
	v_fma_f32 v2, v2, v14, v16
	v_fma_f32 v3, v3, v15, v17
	v_cvt_pk_bf16_f32 v158, v2, v3
	v_lshlrev_b32_e32 v2, 16, v201
	v_and_b32_e32 v3, 0xffff0000, v201
	v_mul_f32_e32 v2, 0xbfb8aa3b, v2
	v_mul_f32_e32 v3, 0xbfb8aa3b, v3
	v_exp_f32_e32 v2, v2
	v_exp_f32_e32 v3, v3
	v_add_f32_e32 v2, 1.0, v2
	v_add_f32_e32 v3, 1.0, v3
	v_div_scale_f32 v5, s[30:31], v3, v3, 1.0
	v_div_scale_f32 v4, s[30:31], v2, v2, 1.0
	v_rcp_f32_e32 v7, v5
	v_rcp_f32_e32 v6, v4
	v_fma_f32 v9, -v5, v7, 1.0
	v_fma_f32 v8, -v4, v6, 1.0
	v_fmac_f32_e32 v7, v9, v7
	v_fmac_f32_e32 v6, v8, v6
	v_div_scale_f32 v9, vcc, 1.0, v3, 1.0
	v_mul_f32_e32 v11, v9, v7
	v_fma_f32 v13, -v5, v11, v9
	v_fmac_f32_e32 v11, v13, v7
	v_fma_f32 v5, -v5, v11, v9
	v_div_fmas_f32 v5, v5, v7, v11
	v_div_fixup_f32 v3, v5, v3, 1.0
	v_div_scale_f32 v8, vcc, 1.0, v2, 1.0
	v_mul_f32_e32 v10, v8, v6
	v_fma_f32 v12, -v4, v10, v8
	v_fmac_f32_e32 v10, v12, v6
	v_fma_f32 v4, -v4, v10, v8
	v_div_fmas_f32 v4, v4, v6, v10
	v_div_fixup_f32 v2, v4, v2, 1.0
	v_lshlrev_b32_e32 v14, 16, v151
	v_and_b32_e32 v15, 0xffff0000, v151
	v_fma_f32 v2, v2, v14, v16
	v_fma_f32 v3, v3, v15, v17
	v_cvt_pk_bf16_f32 v159, v2, v3
	global_load_dwordx4 v[198:201], v160, s[60:61]
	s_add_u32 s60, s60, 0x51000
	s_addc_u32 s61, s61, 0
	global_store_dwordx4 v19, v[156:159], s[64:65]
	s_add_u32 s64, s64, 0x10000
	s_addc_u32 s65, s65, 0
	s_add_i32 s57, s57, 1
	s_cmp_eq_u32 s57, 3
	s_cselect_b32 s0, 0x510000, 0
	s_cselect_b32 s2, 0x100000, 0
	s_sub_u32 s60, s60, s0
	s_subb_u32 s61, s61, 0
	s_cmp_lt_u32 s57, 4
	s_cbranch_scc1 .Lmy_merge0_loop
	s_branch .LBB0_888

; __device__ __forceinline__ float sigmoid_f(float x) { return 1.f / (1.f + __expf(-x)); }
; template <int NT, int BM, int BN, bool PLAIN, int NSTAGE, bool EPI_LDS>
; __device__ __forceinline__ void gemm_tile(const Params& p, const GemmDesc& g, bf16_t* lds, const int tid) {
;     ...
;     for (int i = 0; i < NIT; ++i) {
;       const int id = tid + NT * i;
;       const int row = id / PPR, pc = id % PPR;
;       u32x4 v = *(const u32x4*)(ct + row * CST + pc * 8);
;       bf16_t* op = o + (long)(m0e + row) * ldo + n0e + pc * 8;
;       if (g.epi == E_MERGE0 || g.epi == E_MERGEN) {
;         const u32x4 gt = *(const u32x4*)(((bf16_t*)(p.ws + OFF_proj)) + (long)(m0e + row) * LDP + gcol + n0e + pc * 8);
;         u32x4 pv = u32x4{0u, 0u, 0u, 0u};
;         if (g.epi == E_MERGEN) pv = *(const u32x4*)op;
; #pragma unroll
;         for (int e = 0; e < 4; ++e) {
;           const float g0 = sigmoid_f(__uint_as_float(gt[e] << 16)), g1 = sigmoid_f(__uint_as_float(gt[e] & 0xffff0000u));
;           const float a0 = __uint_as_float(v[e] << 16), a1 = __uint_as_float(v[e] & 0xffff0000u);
;           const float p0 = __uint_as_float(pv[e] << 16), p1 = __uint_as_float(pv[e] & 0xffff0000u);
;           v[e] = pack2(p0 + g0 * a0, p1 + g1 * a1);
;         }
;       }
;       *(u32x4*)op = v;
.Lmy_mergeN_loop:
	ds_read_b128 v[148:151], v18
	v_add_u32_e32 v18, 0x2200, v18
	s_waitcnt vmcnt(6)
	v_lshlrev_b32_e32 v2, 16, v186
	v_and_b32_e32 v3, 0xffff0000, v186
	v_mul_f32_e32 v2, 0xbfb8aa3b, v2
	v_mul_f32_e32 v3, 0xbfb8aa3b, v3
	v_exp_f32_e32 v2, v2
	v_exp_f32_e32 v3, v3
	v_add_f32_e32 v2, 1.0, v2
	v_add_f32_e32 v3, 1.0, v3
	v_div_scale_f32 v5, s[30:31], v3, v3, 1.0
	v_div_scale_f32 v4, s[30:31], v2, v2, 1.0
	v_rcp_f32_e32 v7, v5
	v_rcp_f32_e32 v6, v4
	v_fma_f32 v9, -v5, v7, 1.0
	v_fma_f32 v8, -v4, v6, 1.0
	v_fmac_f32_e32 v7, v9, v7
	v_fmac_f32_e32 v6, v8, v6
	v_div_scale_f32 v9, vcc, 1.0, v3, 1.0
	v_mul_f32_e32 v11, v9, v7
	v_fma_f32 v13, -v5, v11, v9
	v_fmac_f32_e32 v11, v13, v7
	v_fma_f32 v5, -v5, v11, v9
	v_div_fmas_f32 v5, v5, v7, v11
	v_div_fixup_f32 v3, v5, v3, 1.0
	v_div_scale_f32 v8, vcc, 1.0, v2, 1.0
	v_mul_f32_e32 v10, v8, v6
	v_fma_f32 v12, -v4, v10, v8
	v_fmac_f32_e32 v10, v12, v6
	v_fma_f32 v4, -v4, v10, v8
	v_div_fmas_f32 v4, v4, v6, v10
	v_div_fixup_f32 v2, v4, v2, 1.0
	s_waitcnt lgkmcnt(0)
	v_lshlrev_b32_e32 v14, 16, v148
	v_and_b32_e32 v15, 0xffff0000, v148
	v_lshlrev_b32_e32 v16, 16, v226
	v_and_b32_e32 v17, 0xffff0000, v226
	v_fma_f32 v2, v2, v14, v16
	v_fma_f32 v3, v3, v15, v17
	v_cvt_pk_bf16_f32 v156, v2, v3
	v_lshlrev_b32_e32 v2, 16, v187
	v_and_b32_e32 v3, 0xffff0000, v187
	v_mul_f32_e32 v2, 0xbfb8aa3b, v2
	v_mul_f32_e32 v3, 0xbfb8aa3b, v3
	v_exp_f32_e32 v2, v2
	v_exp_f32_e32 v3, v3
	v_add_f32_e32 v2, 1.0, v2
	v_add_f32_e32 v3, 1.0, v3
	v_div_scale_f32 v5, s[30:31], v3, v3, 1.0
	v_div_scale_f32 v4, s[30:31], v2, v2, 1.0
	v_rcp_f32_e32 v7, v5
	v_rcp_f32_e32 v6, v4
	v_fma_f32 v9, -v5, v7, 1.0
	v_fma_f32 v8, -v4, v6, 1.0
	v_fmac_f32_e32 v7, v9, v7
	v_fmac_f32_e32 v6, v8, v6
	v_div_scale_f32 v9, vcc, 1.0, v3, 1.0
	v_mul_f32_e32 v11, v9, v7
	v_fma_f32 v13, -v5, v11, v9
	v_fmac_f32_e32 v11, v13, v7
	v_fma_f32 v5, -v5, v11, v9
	v_div_fmas_f32 v5, v5, v7, v11
	v_div_fixup_f32 v3, v5, v3, 1.0
	v_div_scale_f32 v8, vcc, 1.0, v2, 1.0
	v_mul_f32_e32 v10, v8, v6
	v_fma_f32 v12, -v4, v10, v8
	v_fmac_f32_e32 v10, v12, v6
	v_fma_f32 v4, -v4, v10, v8
	v_div_fmas_f32 v4, v4, v6, v10
	v_div_fixup_f32 v2, v4, v2, 1.0
	v_lshlrev_b32_e32 v14, 16, v149
	v_and_b32_e32 v15, 0xffff0000, v149
	v_lshlrev_b32_e32 v16, 16, v227
	v_and_b32_e32 v17, 0xffff0000, v227
	v_fma_f32 v2, v2, v14, v16
	v_fma_f32 v3, v3, v15, v17
	v_cvt_pk_bf16_f32 v157, v2, v3
	v_lshlrev_b32_e32 v2, 16, v188
	v_and_b32_e32 v3, 0xffff0000, v188
	v_mul_f32_e32 v2, 0xbfb8aa3b, v2
	v_mul_f32_e32 v3, 0xbfb8aa3b, v3
	v_exp_f32_e32 v2, v2
	v_exp_f32_e32 v3, v3
	v_add_f32_e32 v2, 1.0, v2
	v_add_f32_e32 v3, 1.0, v3
	v_div_scale_f32 v5, s[30:31], v3, v3, 1.0
	v_div_scale_f32 v4, s[30:31], v2, v2, 1.0
	v_rcp_f32_e32 v7, v5
	v_rcp_f32_e32 v6, v4
	v_fma_f32 v9, -v5, v7, 1.0
	v_fma_f32 v8, -v4, v6, 1.0
	v_fmac_f32_e32 v7, v9, v7
	v_fmac_f32_e32 v6, v8, v6
	v_div_scale_f32 v9, vcc, 1.0, v3, 1.0
	v_mul_f32_e32 v11, v9, v7
	v_fma_f32 v13, -v5, v11, v9
	v_fmac_f32_e32 v11, v13, v7
	v_fma_f32 v5, -v5, v11, v9
	v_div_fmas_f32 v5, v5, v7, v11
	v_div_fixup_f32 v3, v5, v3, 1.0
	v_div_scale_f32 v8, vcc, 1.0, v2, 1.0
	v_mul_f32_e32 v10, v8, v6
	v_fma_f32 v12, -v4, v10, v8
	v_fmac_f32_e32 v10, v12, v6
	v_fma_f32 v4, -v4, v10, v8
	v_div_fmas_f32 v4, v4, v6, v10
	v_div_fixup_f32 v2, v4, v2, 1.0
	v_lshlrev_b32_e32 v14, 16, v150
	v_and_b32_e32 v15, 0xffff0000, v150
	v_lshlrev_b32_e32 v16, 16, v228
	v_and_b32_e32 v17, 0xffff0000, v228
	v_fma_f32 v2, v2, v14, v16
	v_fma_f32 v3, v3, v15, v17
	v_cvt_pk_bf16_f32 v158, v2, v3
	v_lshlrev_b32_e32 v2, 16, v189
	v_and_b32_e32 v3, 0xffff0000, v189
	v_mul_f32_e32 v2, 0xbfb8aa3b, v2
	v_mul_f32_e32 v3, 0xbfb8aa3b, v3
	v_exp_f32_e32 v2, v2
	v_exp_f32_e32 v3, v3
	v_add_f32_e32 v2, 1.0, v2
	v_add_f32_e32 v3, 1.0, v3
	v_div_scale_f32 v5, s[30:31], v3, v3, 1.0
	v_div_scale_f32 v4, s[30:31], v2, v2, 1.0
	v_rcp_f32_e32 v7, v5
	v_rcp_f32_e32 v6, v4
	v_fma_f32 v9, -v5, v7, 1.0
	v_fma_f32 v8, -v4, v6, 1.0
	v_fmac_f32_e32 v7, v9, v7
	v_fmac_f32_e32 v6, v8, v6
	v_div_scale_f32 v9, vcc, 1.0, v3, 1.0
	v_mul_f32_e32 v11, v9, v7
	v_fma_f32 v13, -v5, v11, v9
	v_fmac_f32_e32 v11, v13, v7
	v_fma_f32 v5, -v5, v11, v9
	v_div_fmas_f32 v5, v5, v7, v11
	v_div_fixup_f32 v3, v5, v3, 1.0
	v_div_scale_f32 v8, vcc, 1.0, v2, 1.0
	v_mul_f32_e32 v10, v8, v6
	v_fma_f32 v12, -v4, v10, v8
	v_fmac_f32_e32 v10, v12, v6
	v_fma_f32 v4, -v4, v10, v8
	v_div_fmas_f32 v4, v4, v6, v10
	v_div_fixup_f32 v2, v4, v2, 1.0
	v_lshlrev_b32_e32 v14, 16, v151
	v_and_b32_e32 v15, 0xffff0000, v151
	v_lshlrev_b32_e32 v16, 16, v229
	v_and_b32_e32 v17, 0xffff0000, v229
	v_fma_f32 v2, v2, v14, v16
	v_fma_f32 v3, v3, v15, v17
	v_cvt_pk_bf16_f32 v159, v2, v3
	global_load_dwordx4 v[186:189], v160, s[60:61]
	global_load_dwordx4 v[226:229], v19, s[62:63]
	s_add_u32 s60, s60, 0x51000
	s_addc_u32 s61, s61, 0
	s_add_u32 s62, s62, 0x10000
	s_addc_u32 s63, s63, 0
	global_store_dwordx4 v19, v[156:159], s[64:65]
	s_add_u32 s64, s64, 0x10000
	s_addc_u32 s65, s65, 0
	ds_read_b128 v[148:151], v18
	v_add_u32_e32 v18, 0x2200, v18
	s_waitcnt vmcnt(7)
	v_lshlrev_b32_e32 v2, 16, v190
	v_and_b32_e32 v3, 0xffff0000, v190
	v_mul_f32_e32 v2, 0xbfb8aa3b, v2
	v_mul_f32_e32 v3, 0xbfb8aa3b, v3
	v_exp_f32_e32 v2, v2
	v_exp_f32_e32 v3, v3
	v_add_f32_e32 v2, 1.0, v2
	v_add_f32_e32 v3, 1.0, v3
	v_div_scale_f32 v5, s[30:31], v3, v3, 1.0
	v_div_scale_f32 v4, s[30:31], v2, v2, 1.0
	v_rcp_f32_e32 v7, v5
	v_rcp_f32_e32 v6, v4
	v_fma_f32 v9, -v5, v7, 1.0
	v_fma_f32 v8, -v4, v6, 1.0
	v_fmac_f32_e32 v7, v9, v7
	v_fmac_f32_e32 v6, v8, v6
	v_div_scale_f32 v9, vcc, 1.0, v3, 1.0
	v_mul_f32_e32 v11, v9, v7
	v_fma_f32 v13, -v5, v11, v9
	v_fmac_f32_e32 v11, v13, v7
	v_fma_f32 v5, -v5, v11, v9
	v_div_fmas_f32 v5, v5, v7, v11
	v_div_fixup_f32 v3, v5, v3, 1.0
	v_div_scale_f32 v8, vcc, 1.0, v2, 1.0
	v_mul_f32_e32 v10, v8, v6
	v_fma_f32 v12, -v4, v10, v8
	v_fmac_f32_e32 v10, v12, v6
	v_fma_f32 v4, -v4, v10, v8
	v_div_fmas_f32 v4, v4, v6, v10
	v_div_fixup_f32 v2, v4, v2, 1.0
	s_waitcnt lgkmcnt(0)
; __device__ __forceinline__ float sigmoid_f(float x) { return 1.f / (1.f + __expf(-x)); }
; template <int NT, int BM, int BN, bool PLAIN, int NSTAGE, bool EPI_LDS>
; __device__ __forceinline__ void gemm_tile(const Params& p, const GemmDesc& g, bf16_t* lds, const int tid) {
;     ...
;     for (int i = 0; i < NIT; ++i) {
;       const int id = tid + NT * i;
;       const int row = id / PPR, pc = id % PPR;
;       u32x4 v = *(const u32x4*)(ct + row * CST + pc * 8);
;       bf16_t* op = o + (long)(m0e + row) * ldo + n0e + pc * 8;
;       if (g.epi == E_MERGE0 || g.epi == E_MERGEN) {
;         const u32x4 gt = *(const u32x4*)(((bf16_t*)(p.ws + OFF_proj)) + (long)(m0e + row) * LDP + gcol + n0e + pc * 8);
;         u32x4 pv = u32x4{0u, 0u, 0u, 0u};
;         if (g.epi == E_MERGEN) pv = *(const u32x4*)op;
; #pragma unroll
;         for (int e = 0; e < 4; ++e) {
;           const float g0 = sigmoid_f(__uint_as_float(gt[e] << 16)), g1 = sigmoid_f(__uint_as_float(gt[e] & 0xffff0000u));
;           const float a0 = __uint_as_float(v[e] << 16), a1 = __uint_as_float(v[e] & 0xffff0000u);
;           const float p0 = __uint_as_float(pv[e] << 16), p1 = __uint_as_float(pv[e] & 0xffff0000u);
;           v[e] = pack2(p0 + g0 * a0, p1 + g1 * a1);
;         }
;       }
;       *(u32x4*)op = v;
	v_lshlrev_b32_e32 v14, 16, v148
	v_and_b32_e32 v15, 0xffff0000, v148
	v_lshlrev_b32_e32 v16, 16, v230
	v_and_b32_e32 v17, 0xffff0000, v230
	v_fma_f32 v2, v2, v14, v16
	v_fma_f32 v3, v3, v15, v17
	v_cvt_pk_bf16_f32 v156, v2, v3
	v_lshlrev_b32_e32 v2, 16, v191
	v_and_b32_e32 v3, 0xffff0000, v191
	v_mul_f32_e32 v2, 0xbfb8aa3b, v2
	v_mul_f32_e32 v3, 0xbfb8aa3b, v3
	v_exp_f32_e32 v2, v2
	v_exp_f32_e32 v3, v3
	v_add_f32_e32 v2, 1.0, v2
	v_add_f32_e32 v3, 1.0, v3
	v_div_scale_f32 v5, s[30:31], v3, v3, 1.0
	v_div_scale_f32 v4, s[30:31], v2, v2, 1.0
	v_rcp_f32_e32 v7, v5
	v_rcp_f32_e32 v6, v4
	v_fma_f32 v9, -v5, v7, 1.0
	v_fma_f32 v8, -v4, v6, 1.0
	v_fmac_f32_e32 v7, v9, v7
	v_fmac_f32_e32 v6, v8, v6
	v_div_scale_f32 v9, vcc, 1.0, v3, 1.0
	v_mul_f32_e32 v11, v9, v7
	v_fma_f32 v13, -v5, v11, v9
	v_fmac_f32_e32 v11, v13, v7
	v_fma_f32 v5, -v5, v11, v9
	v_div_fmas_f32 v5, v5, v7, v11
	v_div_fixup_f32 v3, v5, v3, 1.0
	v_div_scale_f32 v8, vcc, 1.0, v2, 1.0
	v_mul_f32_e32 v10, v8, v6
	v_fma_f32 v12, -v4, v10, v8
	v_fmac_f32_e32 v10, v12, v6
	v_fma_f32 v4, -v4, v10, v8
	v_div_fmas_f32 v4, v4, v6, v10
	v_div_fixup_f32 v2, v4, v2, 1.0
	v_lshlrev_b32_e32 v14, 16, v149
	v_and_b32_e32 v15, 0xffff0000, v149
	v_lshlrev_b32_e32 v16, 16, v231
	v_and_b32_e32 v17, 0xffff0000, v231
	v_fma_f32 v2, v2, v14, v16
	v_fma_f32 v3, v3, v15, v17
	v_cvt_pk_bf16_f32 v157, v2, v3
	v_lshlrev_b32_e32 v2, 16, v192
	v_and_b32_e32 v3, 0xffff0000, v192
	v_mul_f32_e32 v2, 0xbfb8aa3b, v2
	v_mul_f32_e32 v3, 0xbfb8aa3b, v3
	v_exp_f32_e32 v2, v2
	v_exp_f32_e32 v3, v3
	v_add_f32_e32 v2, 1.0, v2
	v_add_f32_e32 v3, 1.0, v3
	v_div_scale_f32 v5, s[30:31], v3, v3, 1.0
	v_div_scale_f32 v4, s[30:31], v2, v2, 1.0
	v_rcp_f32_e32 v7, v5
	v_rcp_f32_e32 v6, v4
	v_fma_f32 v9, -v5, v7, 1.0
	v_fma_f32 v8, -v4, v6, 1.0
	v_fmac_f32_e32 v7, v9, v7
	v_fmac_f32_e32 v6, v8, v6
	v_div_scale_f32 v9, vcc, 1.0, v3, 1.0
	v_mul_f32_e32 v11, v9, v7
	v_fma_f32 v13, -v5, v11, v9
	v_fmac_f32_e32 v11, v13, v7
	v_fma_f32 v5, -v5, v11, v9
	v_div_fmas_f32 v5, v5, v7, v11
	v_div_fixup_f32 v3, v5, v3, 1.0
	v_div_scale_f32 v8, vcc, 1.0, v2, 1.0
	v_mul_f32_e32 v10, v8, v6
	v_fma_f32 v12, -v4, v10, v8
	v_fmac_f32_e32 v10, v12, v6
	v_fma_f32 v4, -v4, v10, v8
	v_div_fmas_f32 v4, v4, v6, v10
	v_div_fixup_f32 v2, v4, v2, 1.0
	v_lshlrev_b32_e32 v14, 16, v150
	v_and_b32_e32 v15, 0xffff0000, v150
	v_lshlrev_b32_e32 v16, 16, v232
	v_and_b32_e32 v17, 0xffff0000, v232
	v_fma_f32 v2, v2, v14, v16
	v_fma_f32 v3, v3, v15, v17
	v_cvt_pk_bf16_f32 v158, v2, v3
	v_lshlrev_b32_e32 v2, 16, v193
	v_and_b32_e32 v3, 0xffff0000, v193
	v_mul_f32_e32 v2, 0xbfb8aa3b, v2
	v_mul_f32_e32 v3, 0xbfb8aa3b, v3
	v_exp_f32_e32 v2, v2
	v_exp_f32_e32 v3, v3
	v_add_f32_e32 v2, 1.0, v2
	v_add_f32_e32 v3, 1.0, v3
	v_div_scale_f32 v5, s[30:31], v3, v3, 1.0
	v_div_scale_f32 v4, s[30:31], v2, v2, 1.0
	v_rcp_f32_e32 v7, v5
	v_rcp_f32_e32 v6, v4
	v_fma_f32 v9, -v5, v7, 1.0
	v_fma_f32 v8, -v4, v6, 1.0
	v_fmac_f32_e32 v7, v9, v7
	v_fmac_f32_e32 v6, v8, v6
	v_div_scale_f32 v9, vcc, 1.0, v3, 1.0
	v_mul_f32_e32 v11, v9, v7
	v_fma_f32 v13, -v5, v11, v9
	v_fmac_f32_e32 v11, v13, v7
	v_fma_f32 v5, -v5, v11, v9
	v_div_fmas_f32 v5, v5, v7, v11
	v_div_fixup_f32 v3, v5, v3, 1.0
	v_div_scale_f32 v8, vcc, 1.0, v2, 1.0
	v_mul_f32_e32 v10, v8, v6
	v_fma_f32 v12, -v4, v10, v8
	v_fmac_f32_e32 v10, v12, v6
	v_fma_f32 v4, -v4, v10, v8
	v_div_fmas_f32 v4, v4, v6, v10
	v_div_fixup_f32 v2, v4, v2, 1.0
	v_lshlrev_b32_e32 v14, 16, v151
	v_and_b32_e32 v15, 0xffff0000, v151
	v_lshlrev_b32_e32 v16, 16, v233
	v_and_b32_e32 v17, 0xffff0000, v233
	v_fma_f32 v2, v2, v14, v16
	v_fma_f32 v3, v3, v15, v17
	v_cvt_pk_bf16_f32 v159, v2, v3
	global_load_dwordx4 v[190:193], v160, s[60:61]
	global_load_dwordx4 v[230:233], v19, s[62:63]
	s_add_u32 s60, s60, 0x51000
	s_addc_u32 s61, s61, 0
	s_add_u32 s62, s62, 0x10000
	s_addc_u32 s63, s63, 0
	global_store_dwordx4 v19, v[156:159], s[64:65]
	s_add_u32 s64, s64, 0x10000
	s_addc_u32 s65, s65, 0
	ds_read_b128 v[148:151], v18
	v_add_u32_e32 v18, 0x2200, v18
	s_waitcnt vmcnt(8)
	v_lshlrev_b32_e32 v2, 16, v194
	v_and_b32_e32 v3, 0xffff0000, v194
	v_mul_f32_e32 v2, 0xbfb8aa3b, v2
	v_mul_f32_e32 v3, 0xbfb8aa3b, v3
	v_exp_f32_e32 v2, v2
	v_exp_f32_e32 v3, v3
	v_add_f32_e32 v2, 1.0, v2
	v_add_f32_e32 v3, 1.0, v3
	v_div_scale_f32 v5, s[30:31], v3, v3, 1.0
	v_div_scale_f32 v4, s[30:31], v2, v2, 1.0
	v_rcp_f32_e32 v7, v5
	v_rcp_f32_e32 v6, v4
	v_fma_f32 v9, -v5, v7, 1.0
	v_fma_f32 v8, -v4, v6, 1.0
	v_fmac_f32_e32 v7, v9, v7
	v_fmac_f32_e32 v6, v8, v6
	v_div_scale_f32 v9, vcc, 1.0, v3, 1.0
	v_mul_f32_e32 v11, v9, v7
	v_fma_f32 v13, -v5, v11, v9
	v_fmac_f32_e32 v11, v13, v7
	v_fma_f32 v5, -v5, v11, v9
	v_div_fmas_f32 v5, v5, v7, v11
	v_div_fixup_f32 v3, v5, v3, 1.0
	v_div_scale_f32 v8, vcc, 1.0, v2, 1.0
	v_mul_f32_e32 v10, v8, v6
	v_fma_f32 v12, -v4, v10, v8
	v_fmac_f32_e32 v10, v12, v6
	v_fma_f32 v4, -v4, v10, v8
	v_div_fmas_f32 v4, v4, v6, v10
	v_div_fixup_f32 v2, v4, v2, 1.0
	s_waitcnt lgkmcnt(0)
; __device__ __forceinline__ float sigmoid_f(float x) { return 1.f / (1.f + __expf(-x)); }
; template <int NT, int BM, int BN, bool PLAIN, int NSTAGE, bool EPI_LDS>
; __device__ __forceinline__ void gemm_tile(const Params& p, const GemmDesc& g, bf16_t* lds, const int tid) {
;     ...
;     for (int i = 0; i < NIT; ++i) {
;       const int id = tid + NT * i;
;       const int row = id / PPR, pc = id % PPR;
;       u32x4 v = *(const u32x4*)(ct + row * CST + pc * 8);
;       bf16_t* op = o + (long)(m0e + row) * ldo + n0e + pc * 8;
;       if (g.epi == E_MERGE0 || g.epi == E_MERGEN) {
;         const u32x4 gt = *(const u32x4*)(((bf16_t*)(p.ws + OFF_proj)) + (long)(m0e + row) * LDP + gcol + n0e + pc * 8);
;         u32x4 pv = u32x4{0u, 0u, 0u, 0u};
;         if (g.epi == E_MERGEN) pv = *(const u32x4*)op;
; #pragma unroll
;         for (int e = 0; e < 4; ++e) {
;           const float g0 = sigmoid_f(__uint_as_float(gt[e] << 16)), g1 = sigmoid_f(__uint_as_float(gt[e] & 0xffff0000u));
;           const float a0 = __uint_as_float(v[e] << 16), a1 = __uint_as_float(v[e] & 0xffff0000u);
;           const float p0 = __uint_as_float(pv[e] << 16), p1 = __uint_as_float(pv[e] & 0xffff0000u);
;           v[e] = pack2(p0 + g0 * a0, p1 + g1 * a1);
;         }
;       }
;       *(u32x4*)op = v;
	v_lshlrev_b32_e32 v14, 16, v148
	v_and_b32_e32 v15, 0xffff0000, v148
	v_lshlrev_b32_e32 v16, 16, v234
	v_and_b32_e32 v17, 0xffff0000, v234
	v_fma_f32 v2, v2, v14, v16
	v_fma_f32 v3, v3, v15, v17
	v_cvt_pk_bf16_f32 v156, v2, v3
	v_lshlrev_b32_e32 v2, 16, v195
	v_and_b32_e32 v3, 0xffff0000, v195
	v_mul_f32_e32 v2, 0xbfb8aa3b, v2
	v_mul_f32_e32 v3, 0xbfb8aa3b, v3
	v_exp_f32_e32 v2, v2
	v_exp_f32_e32 v3, v3
	v_add_f32_e32 v2, 1.0, v2
	v_add_f32_e32 v3, 1.0, v3
	v_div_scale_f32 v5, s[30:31], v3, v3, 1.0
	v_div_scale_f32 v4, s[30:31], v2, v2, 1.0
	v_rcp_f32_e32 v7, v5
	v_rcp_f32_e32 v6, v4
	v_fma_f32 v9, -v5, v7, 1.0
	v_fma_f32 v8, -v4, v6, 1.0
	v_fmac_f32_e32 v7, v9, v7
	v_fmac_f32_e32 v6, v8, v6
	v_div_scale_f32 v9, vcc, 1.0, v3, 1.0
	v_mul_f32_e32 v11, v9, v7
	v_fma_f32 v13, -v5, v11, v9
	v_fmac_f32_e32 v11, v13, v7
	v_fma_f32 v5, -v5, v11, v9
	v_div_fmas_f32 v5, v5, v7, v11
	v_div_fixup_f32 v3, v5, v3, 1.0
	v_div_scale_f32 v8, vcc, 1.0, v2, 1.0
	v_mul_f32_e32 v10, v8, v6
	v_fma_f32 v12, -v4, v10, v8
	v_fmac_f32_e32 v10, v12, v6
	v_fma_f32 v4, -v4, v10, v8
	v_div_fmas_f32 v4, v4, v6, v10
	v_div_fixup_f32 v2, v4, v2, 1.0
	v_lshlrev_b32_e32 v14, 16, v149
	v_and_b32_e32 v15, 0xffff0000, v149
	v_lshlrev_b32_e32 v16, 16, v235
	v_and_b32_e32 v17, 0xffff0000, v235
	v_fma_f32 v2, v2, v14, v16
	v_fma_f32 v3, v3, v15, v17
	v_cvt_pk_bf16_f32 v157, v2, v3
	v_lshlrev_b32_e32 v2, 16, v196
	v_and_b32_e32 v3, 0xffff0000, v196
	v_mul_f32_e32 v2, 0xbfb8aa3b, v2
	v_mul_f32_e32 v3, 0xbfb8aa3b, v3
	v_exp_f32_e32 v2, v2
	v_exp_f32_e32 v3, v3
	v_add_f32_e32 v2, 1.0, v2
	v_add_f32_e32 v3, 1.0, v3
	v_div_scale_f32 v5, s[30:31], v3, v3, 1.0
	v_div_scale_f32 v4, s[30:31], v2, v2, 1.0
	v_rcp_f32_e32 v7, v5
	v_rcp_f32_e32 v6, v4
	v_fma_f32 v9, -v5, v7, 1.0
	v_fma_f32 v8, -v4, v6, 1.0
	v_fmac_f32_e32 v7, v9, v7
	v_fmac_f32_e32 v6, v8, v6
	v_div_scale_f32 v9, vcc, 1.0, v3, 1.0
	v_mul_f32_e32 v11, v9, v7
	v_fma_f32 v13, -v5, v11, v9
	v_fmac_f32_e32 v11, v13, v7
	v_fma_f32 v5, -v5, v11, v9
	v_div_fmas_f32 v5, v5, v7, v11
	v_div_fixup_f32 v3, v5, v3, 1.0
	v_div_scale_f32 v8, vcc, 1.0, v2, 1.0
	v_mul_f32_e32 v10, v8, v6
	v_fma_f32 v12, -v4, v10, v8
	v_fmac_f32_e32 v10, v12, v6
	v_fma_f32 v4, -v4, v10, v8
	v_div_fmas_f32 v4, v4, v6, v10
	v_div_fixup_f32 v2, v4, v2, 1.0
	v_lshlrev_b32_e32 v14, 16, v150
	v_and_b32_e32 v15, 0xffff0000, v150
	v_lshlrev_b32_e32 v16, 16, v236
	v_and_b32_e32 v17, 0xffff0000, v236
	v_fma_f32 v2, v2, v14, v16
	v_fma_f32 v3, v3, v15, v17
	v_cvt_pk_bf16_f32 v158, v2, v3
	v_lshlrev_b32_e32 v2, 16, v197
	v_and_b32_e32 v3, 0xffff0000, v197
	v_mul_f32_e32 v2, 0xbfb8aa3b, v2
	v_mul_f32_e32 v3, 0xbfb8aa3b, v3
	v_exp_f32_e32 v2, v2
	v_exp_f32_e32 v3, v3
	v_add_f32_e32 v2, 1.0, v2
	v_add_f32_e32 v3, 1.0, v3
	v_div_scale_f32 v5, s[30:31], v3, v3, 1.0
	v_div_scale_f32 v4, s[30:31], v2, v2, 1.0
	v_rcp_f32_e32 v7, v5
	v_rcp_f32_e32 v6, v4
	v_fma_f32 v9, -v5, v7, 1.0
	v_fma_f32 v8, -v4, v6, 1.0
	v_fmac_f32_e32 v7, v9, v7
	v_fmac_f32_e32 v6, v8, v6
	v_div_scale_f32 v9, vcc, 1.0, v3, 1.0
	v_mul_f32_e32 v11, v9, v7
	v_fma_f32 v13, -v5, v11, v9
	v_fmac_f32_e32 v11, v13, v7
	v_fma_f32 v5, -v5, v11, v9
	v_div_fmas_f32 v5, v5, v7, v11
	v_div_fixup_f32 v3, v5, v3, 1.0
	v_div_scale_f32 v8, vcc, 1.0, v2, 1.0
	v_mul_f32_e32 v10, v8, v6
	v_fma_f32 v12, -v4, v10, v8
	v_fmac_f32_e32 v10, v12, v6
	v_fma_f32 v4, -v4, v10, v8
	v_div_fmas_f32 v4, v4, v6, v10
	v_div_fixup_f32 v2, v4, v2, 1.0
	v_lshlrev_b32_e32 v14, 16, v151
	v_and_b32_e32 v15, 0xffff0000, v151
	v_lshlrev_b32_e32 v16, 16, v237
	v_and_b32_e32 v17, 0xffff0000, v237
	v_fma_f32 v2, v2, v14, v16
	v_fma_f32 v3, v3, v15, v17
	v_cvt_pk_bf16_f32 v159, v2, v3
	global_load_dwordx4 v[194:197], v160, s[60:61]
	global_load_dwordx4 v[234:237], v19, s[62:63]
	s_add_u32 s60, s60, 0x51000
	s_addc_u32 s61, s61, 0
	s_add_u32 s62, s62, 0x10000
	s_addc_u32 s63, s63, 0
	global_store_dwordx4 v19, v[156:159], s[64:65]
	s_add_u32 s64, s64, 0x10000
	s_addc_u32 s65, s65, 0
	ds_read_b128 v[148:151], v18
	v_add_u32_e32 v18, 0x2200, v18
	s_waitcnt vmcnt(9)
	v_lshlrev_b32_e32 v2, 16, v198
	v_and_b32_e32 v3, 0xffff0000, v198
	v_mul_f32_e32 v2, 0xbfb8aa3b, v2
	v_mul_f32_e32 v3, 0xbfb8aa3b, v3
	v_exp_f32_e32 v2, v2
	v_exp_f32_e32 v3, v3
	v_add_f32_e32 v2, 1.0, v2
	v_add_f32_e32 v3, 1.0, v3
	v_div_scale_f32 v5, s[30:31], v3, v3, 1.0
	v_div_scale_f32 v4, s[30:31], v2, v2, 1.0
	v_rcp_f32_e32 v7, v5
	v_rcp_f32_e32 v6, v4
	v_fma_f32 v9, -v5, v7, 1.0
	v_fma_f32 v8, -v4, v6, 1.0
	v_fmac_f32_e32 v7, v9, v7
	v_fmac_f32_e32 v6, v8, v6
	v_div_scale_f32 v9, vcc, 1.0, v3, 1.0
	v_mul_f32_e32 v11, v9, v7
	v_fma_f32 v13, -v5, v11, v9
	v_fmac_f32_e32 v11, v13, v7
	v_fma_f32 v5, -v5, v11, v9
	v_div_fmas_f32 v5, v5, v7, v11
	v_div_fixup_f32 v3, v5, v3, 1.0
	v_div_scale_f32 v8, vcc, 1.0, v2, 1.0
	v_mul_f32_e32 v10, v8, v6
	v_fma_f32 v12, -v4, v10, v8
	v_fmac_f32_e32 v10, v12, v6
	v_fma_f32 v4, -v4, v10, v8
	v_div_fmas_f32 v4, v4, v6, v10
	v_div_fixup_f32 v2, v4, v2, 1.0
	s_waitcnt lgkmcnt(0)
; __device__ __forceinline__ float sigmoid_f(float x) { return 1.f / (1.f + __expf(-x)); }
; template <int NT, int BM, int BN, bool PLAIN, int NSTAGE, bool EPI_LDS>
; __device__ __forceinline__ void gemm_tile(const Params& p, const GemmDesc& g, bf16_t* lds, const int tid) {
;     ...
;     for (int i = 0; i < NIT; ++i) {
;       const int id = tid + NT * i;
;       const int row = id / PPR, pc = id % PPR;
;       u32x4 v = *(const u32x4*)(ct + row * CST + pc * 8);
;       bf16_t* op = o + (long)(m0e + row) * ldo + n0e + pc * 8;
;       if (g.epi == E_MERGE0 || g.epi == E_MERGEN) {
;         const u32x4 gt = *(const u32x4*)(((bf16_t*)(p.ws + OFF_proj)) + (long)(m0e + row) * LDP + gcol + n0e + pc * 8);
;         u32x4 pv = u32x4{0u, 0u, 0u, 0u};
;         if (g.epi == E_MERGEN) pv = *(const u32x4*)op;
; #pragma unroll
;         for (int e = 0; e < 4; ++e) {
;           const float g0 = sigmoid_f(__uint_as_float(gt[e] << 16)), g1 = sigmoid_f(__uint_as_float(gt[e] & 0xffff0000u));
;           const float a0 = __uint_as_float(v[e] << 16), a1 = __uint_as_float(v[e] & 0xffff0000u);
;           const float p0 = __uint_as_float(pv[e] << 16), p1 = __uint_as_float(pv[e] & 0xffff0000u);
;           v[e] = pack2(p0 + g0 * a0, p1 + g1 * a1);
;         }
;       }
;       *(u32x4*)op = v;
	v_lshlrev_b32_e32 v14, 16, v148
	v_and_b32_e32 v15, 0xffff0000, v148
	v_lshlrev_b32_e32 v16, 16, v238
	v_and_b32_e32 v17, 0xffff0000, v238
	v_fma_f32 v2, v2, v14, v16
	v_fma_f32 v3, v3, v15, v17
	v_cvt_pk_bf16_f32 v156, v2, v3
	v_lshlrev_b32_e32 v2, 16, v199
	v_and_b32_e32 v3, 0xffff0000, v199
	v_mul_f32_e32 v2, 0xbfb8aa3b, v2
	v_mul_f32_e32 v3, 0xbfb8aa3b, v3
	v_exp_f32_e32 v2, v2
	v_exp_f32_e32 v3, v3
	v_add_f32_e32 v2, 1.0, v2
	v_add_f32_e32 v3, 1.0, v3
	v_div_scale_f32 v5, s[30:31], v3, v3, 1.0
	v_div_scale_f32 v4, s[30:31], v2, v2, 1.0
	v_rcp_f32_e32 v7, v5
	v_rcp_f32_e32 v6, v4
	v_fma_f32 v9, -v5, v7, 1.0
	v_fma_f32 v8, -v4, v6, 1.0
	v_fmac_f32_e32 v7, v9, v7
	v_fmac_f32_e32 v6, v8, v6
	v_div_scale_f32 v9, vcc, 1.0, v3, 1.0
	v_mul_f32_e32 v11, v9, v7
	v_fma_f32 v13, -v5, v11, v9
	v_fmac_f32_e32 v11, v13, v7
	v_fma_f32 v5, -v5, v11, v9
	v_div_fmas_f32 v5, v5, v7, v11
	v_div_fixup_f32 v3, v5, v3, 1.0
	v_div_scale_f32 v8, vcc, 1.0, v2, 1.0
	v_mul_f32_e32 v10, v8, v6
	v_fma_f32 v12, -v4, v10, v8
	v_fmac_f32_e32 v10, v12, v6
	v_fma_f32 v4, -v4, v10, v8
	v_div_fmas_f32 v4, v4, v6, v10
	v_div_fixup_f32 v2, v4, v2, 1.0
	v_lshlrev_b32_e32 v14, 16, v149
	v_and_b32_e32 v15, 0xffff0000, v149
	v_lshlrev_b32_e32 v16, 16, v239
	v_and_b32_e32 v17, 0xffff0000, v239
	v_fma_f32 v2, v2, v14, v16
	v_fma_f32 v3, v3, v15, v17
	v_cvt_pk_bf16_f32 v157, v2, v3
	v_lshlrev_b32_e32 v2, 16, v200
	v_and_b32_e32 v3, 0xffff0000, v200
	v_mul_f32_e32 v2, 0xbfb8aa3b, v2
	v_mul_f32_e32 v3, 0xbfb8aa3b, v3
	v_exp_f32_e32 v2, v2
	v_exp_f32_e32 v3, v3
	v_add_f32_e32 v2, 1.0, v2
	v_add_f32_e32 v3, 1.0, v3
	v_div_scale_f32 v5, s[30:31], v3, v3, 1.0
	v_div_scale_f32 v4, s[30:31], v2, v2, 1.0
	v_rcp_f32_e32 v7, v5
	v_rcp_f32_e32 v6, v4
	v_fma_f32 v9, -v5, v7, 1.0
	v_fma_f32 v8, -v4, v6, 1.0
	v_fmac_f32_e32 v7, v9, v7
	v_fmac_f32_e32 v6, v8, v6
	v_div_scale_f32 v9, vcc, 1.0, v3, 1.0
	v_mul_f32_e32 v11, v9, v7
	v_fma_f32 v13, -v5, v11, v9
	v_fmac_f32_e32 v11, v13, v7
	v_fma_f32 v5, -v5, v11, v9
	v_div_fmas_f32 v5, v5, v7, v11
	v_div_fixup_f32 v3, v5, v3, 1.0
	v_div_scale_f32 v8, vcc, 1.0, v2, 1.0
	v_mul_f32_e32 v10, v8, v6
	v_fma_f32 v12, -v4, v10, v8
	v_fmac_f32_e32 v10, v12, v6
	v_fma_f32 v4, -v4, v10, v8
	v_div_fmas_f32 v4, v4, v6, v10
	v_div_fixup_f32 v2, v4, v2, 1.0
	v_lshlrev_b32_e32 v14, 16, v150
	v_and_b32_e32 v15, 0xffff0000, v150
	v_lshlrev_b32_e32 v16, 16, v240
	v_and_b32_e32 v17, 0xffff0000, v240
	v_fma_f32 v2, v2, v14, v16
	v_fma_f32 v3, v3, v15, v17
	v_cvt_pk_bf16_f32 v158, v2, v3
	v_lshlrev_b32_e32 v2, 16, v201
	v_and_b32_e32 v3, 0xffff0000, v201
	v_mul_f32_e32 v2, 0xbfb8aa3b, v2
	v_mul_f32_e32 v3, 0xbfb8aa3b, v3
	v_exp_f32_e32 v2, v2
	v_exp_f32_e32 v3, v3
	v_add_f32_e32 v2, 1.0, v2
	v_add_f32_e32 v3, 1.0, v3
	v_div_scale_f32 v5, s[30:31], v3, v3, 1.0
	v_div_scale_f32 v4, s[30:31], v2, v2, 1.0
	v_rcp_f32_e32 v7, v5
	v_rcp_f32_e32 v6, v4
	v_fma_f32 v9, -v5, v7, 1.0
	v_fma_f32 v8, -v4, v6, 1.0
	v_fmac_f32_e32 v7, v9, v7
	v_fmac_f32_e32 v6, v8, v6
	v_div_scale_f32 v9, vcc, 1.0, v3, 1.0
	v_mul_f32_e32 v11, v9, v7
	v_fma_f32 v13, -v5, v11, v9
	v_fmac_f32_e32 v11, v13, v7
	v_fma_f32 v5, -v5, v11, v9
	v_div_fmas_f32 v5, v5, v7, v11
	v_div_fixup_f32 v3, v5, v3, 1.0
	v_div_scale_f32 v8, vcc, 1.0, v2, 1.0
	v_mul_f32_e32 v10, v8, v6
	v_fma_f32 v12, -v4, v10, v8
	v_fmac_f32_e32 v10, v12, v6
	v_fma_f32 v4, -v4, v10, v8
	v_div_fmas_f32 v4, v4, v6, v10
	v_div_fixup_f32 v2, v4, v2, 1.0
	v_lshlrev_b32_e32 v14, 16, v151
	v_and_b32_e32 v15, 0xffff0000, v151
	v_lshlrev_b32_e32 v16, 16, v241
	v_and_b32_e32 v17, 0xffff0000, v241
	v_fma_f32 v2, v2, v14, v16
	v_fma_f32 v3, v3, v15, v17
	v_cvt_pk_bf16_f32 v159, v2, v3
	global_load_dwordx4 v[198:201], v160, s[60:61]
	global_load_dwordx4 v[238:241], v19, s[62:63]
	s_add_u32 s60, s60, 0x51000
	s_addc_u32 s61, s61, 0
	s_add_u32 s62, s62, 0x10000
	s_addc_u32 s63, s63, 0
	global_store_dwordx4 v19, v[156:159], s[64:65]
	s_add_u32 s64, s64, 0x10000
	s_addc_u32 s65, s65, 0
	s_add_i32 s57, s57, 1
	s_cmp_eq_u32 s57, 3
	s_cselect_b32 s0, 0x510000, 0
	s_cselect_b32 s2, 0x100000, 0
	s_sub_u32 s60, s60, s0
	s_subb_u32 s61, s61, 0
	s_sub_u32 s62, s62, s2
	s_subb_u32 s63, s63, 0
	s_cmp_lt_u32 s57, 4
	s_cbranch_scc1 .Lmy_mergeN_loop
	s_branch .LBB0_888

; __device__ __forceinline__ float sigmoid_f(float x) { return 1.f / (1.f + __expf(-x)); }
; template <int NT, int BM, int BN, bool PLAIN, int NSTAGE, bool EPI_LDS>
; __device__ __forceinline__ void gemm_tile(const Params& p, const GemmDesc& g, bf16_t* lds, const int tid) {
;     ...
;       if (g.epi == E_MERGE0 || g.epi == E_MERGEN) {
;         const u32x4 gt = *(const u32x4*)(((bf16_t*)(p.ws + OFF_proj)) + (long)(m0e + row) * LDP + gcol + n0e + pc * 8);
;         u32x4 pv = u32x4{0u, 0u, 0u, 0u};
;         if (g.epi == E_MERGEN) pv = *(const u32x4*)op;
; #pragma unroll
;         for (int e = 0; e < 4; ++e) {
;           const float g0 = sigmoid_f(__uint_as_float(gt[e] << 16)), g1 = sigmoid_f(__uint_as_float(gt[e] & 0xffff0000u));
;           const float a0 = __uint_as_float(v[e] << 16), a1 = __uint_as_float(v[e] & 0xffff0000u);
;           const float p0 = __uint_as_float(pv[e] << 16), p1 = __uint_as_float(pv[e] & 0xffff0000u);
;           v[e] = pack2(p0 + g0 * a0, p1 + g1 * a1);
;         }
;       }
;       *(u32x4*)op = v;
.LBB0_963:
	s_waitcnt vmcnt(0)
	v_lshlrev_b32_e32 v0, 16, v10
	v_mul_f32_e32 v0, 0xbfb8aa3b, v0
	v_exp_f32_e32 v16, v0
	v_and_b32_e32 v0, 0xffff0000, v10
	v_mul_f32_e32 v0, 0xbfb8aa3b, v0
	v_exp_f32_e32 v17, v0
	v_and_b32_e32 v21, 0xffff0000, v2
	v_pk_add_f32 v[16:17], v[16:17], 1.0 op_sel_hi:[1,0]
	s_nop 0
	v_div_scale_f32 v0, s[0:1], v17, v17, 1.0
	v_rcp_f32_e32 v10, v0
	s_nop 0
	v_fma_f32 v18, -v0, v10, 1.0
	v_fmac_f32_e32 v10, v18, v10
	v_div_scale_f32 v18, vcc, 1.0, v17, 1.0
	v_mul_f32_e32 v19, v18, v10
	v_fma_f32 v20, -v0, v19, v18
	v_fmac_f32_e32 v19, v20, v10
	v_fma_f32 v0, -v0, v19, v18
	v_div_fmas_f32 v0, v0, v10, v19
	v_div_fixup_f32 v17, v0, v17, 1.0
	v_div_scale_f32 v0, s[0:1], v16, v16, 1.0
	v_rcp_f32_e32 v10, v0
	s_nop 0
	v_fma_f32 v18, -v0, v10, 1.0
	v_fmac_f32_e32 v10, v18, v10
	v_div_scale_f32 v18, vcc, 1.0, v16, 1.0
	v_mul_f32_e32 v19, v18, v10
	v_fma_f32 v20, -v0, v19, v18
	v_fmac_f32_e32 v19, v20, v10
	v_fma_f32 v0, -v0, v19, v18
	v_div_fmas_f32 v0, v0, v10, v19
	v_div_fixup_f32 v16, v0, v16, 1.0
	v_lshlrev_b32_e32 v0, 16, v11
	v_mul_f32_e32 v0, 0xbfb8aa3b, v0
	v_exp_f32_e32 v10, v0
	v_and_b32_e32 v0, 0xffff0000, v11
	v_mul_f32_e32 v0, 0xbfb8aa3b, v0
	v_exp_f32_e32 v11, v0
	v_lshlrev_b32_e32 v20, 16, v2
	s_waitcnt lgkmcnt(0)
	v_lshlrev_b32_e32 v18, 16, v6
	v_and_b32_e32 v19, 0xffff0000, v6
	v_pk_add_f32 v[10:11], v[10:11], 1.0 op_sel_hi:[1,0]
	v_pk_fma_f32 v[16:17], v[16:17], v[18:19], v[20:21]
	v_div_scale_f32 v0, s[0:1], v11, v11, 1.0
	v_rcp_f32_e32 v2, v0
	v_cvt_pk_bf16_f32 v6, v16, v17
	v_fma_f32 v16, -v0, v2, 1.0
	v_fmac_f32_e32 v2, v16, v2
	v_div_scale_f32 v16, vcc, 1.0, v11, 1.0
	v_mul_f32_e32 v17, v16, v2
	v_fma_f32 v18, -v0, v17, v16
	v_fmac_f32_e32 v17, v18, v2
	v_fma_f32 v0, -v0, v17, v16
	v_div_fmas_f32 v0, v0, v2, v17
	v_div_fixup_f32 v11, v0, v11, 1.0
	v_div_scale_f32 v0, s[0:1], v10, v10, 1.0
	v_rcp_f32_e32 v2, v0
	s_nop 0
	v_fma_f32 v16, -v0, v2, 1.0
	v_fmac_f32_e32 v2, v16, v2
	v_div_scale_f32 v16, vcc, 1.0, v10, 1.0
	v_mul_f32_e32 v17, v16, v2
	v_fma_f32 v18, -v0, v17, v16
	v_fmac_f32_e32 v17, v18, v2
	v_fma_f32 v0, -v0, v17, v16
	v_div_fmas_f32 v0, v0, v2, v17
	v_div_fixup_f32 v10, v0, v10, 1.0
	v_lshlrev_b32_e32 v16, 16, v7
	v_and_b32_e32 v17, 0xffff0000, v7
	v_lshlrev_b32_e32 v2, 16, v3
	v_and_b32_e32 v3, 0xffff0000, v3
	v_lshlrev_b32_e32 v0, 16, v12
	v_pk_fma_f32 v[2:3], v[10:11], v[16:17], v[2:3]
	v_mul_f32_e32 v0, 0xbfb8aa3b, v0
	v_cvt_pk_bf16_f32 v7, v2, v3
	v_exp_f32_e32 v2, v0
	v_and_b32_e32 v0, 0xffff0000, v12
	v_mul_f32_e32 v0, 0xbfb8aa3b, v0
	v_exp_f32_e32 v3, v0
	v_and_b32_e32 v17, 0xffff0000, v4
	v_pk_add_f32 v[2:3], v[2:3], 1.0 op_sel_hi:[1,0]
	s_nop 0
	v_div_scale_f32 v0, s[0:1], v3, v3, 1.0
	v_rcp_f32_e32 v10, v0
	s_nop 0
	v_fma_f32 v11, -v0, v10, 1.0
	v_fmac_f32_e32 v10, v11, v10
	v_div_scale_f32 v11, vcc, 1.0, v3, 1.0
	v_mul_f32_e32 v12, v11, v10
	v_fma_f32 v16, -v0, v12, v11
	v_fmac_f32_e32 v12, v16, v10
	v_fma_f32 v0, -v0, v12, v11
	v_div_fmas_f32 v0, v0, v10, v12
	v_div_fixup_f32 v3, v0, v3, 1.0
	v_div_scale_f32 v0, s[0:1], v2, v2, 1.0
	v_rcp_f32_e32 v10, v0
	s_nop 0
	v_fma_f32 v11, -v0, v10, 1.0
	v_fmac_f32_e32 v10, v11, v10
	v_div_scale_f32 v11, vcc, 1.0, v2, 1.0
	v_mul_f32_e32 v12, v11, v10
	v_fma_f32 v16, -v0, v12, v11
	v_fmac_f32_e32 v12, v16, v10
	v_fma_f32 v0, -v0, v12, v11
	v_div_fmas_f32 v0, v0, v10, v12
	v_div_fixup_f32 v2, v0, v2, 1.0
	v_lshlrev_b32_e32 v10, 16, v8
	v_and_b32_e32 v11, 0xffff0000, v8
	v_lshlrev_b32_e32 v16, 16, v4
	v_lshlrev_b32_e32 v0, 16, v13
	v_pk_fma_f32 v[2:3], v[2:3], v[10:11], v[16:17]
	v_mul_f32_e32 v0, 0xbfb8aa3b, v0
	v_cvt_pk_bf16_f32 v8, v2, v3
	v_exp_f32_e32 v2, v0
	v_and_b32_e32 v0, 0xffff0000, v13
	v_mul_f32_e32 v0, 0xbfb8aa3b, v0
	v_exp_f32_e32 v3, v0
	v_add_f32_e32 v2, 1.0, v2
	v_add_f32_e32 v3, 1.0, v3
	v_div_scale_f32 v0, s[0:1], v3, v3, 1.0
	v_rcp_f32_e32 v4, v0
	s_nop 0
	v_fma_f32 v10, -v0, v4, 1.0
	v_fmac_f32_e32 v4, v10, v4
	v_div_scale_f32 v10, vcc, 1.0, v3, 1.0
	v_mul_f32_e32 v11, v10, v4
	v_fma_f32 v12, -v0, v11, v10
	v_fmac_f32_e32 v11, v12, v4
	v_fma_f32 v0, -v0, v11, v10
	v_div_fmas_f32 v0, v0, v4, v11
	v_div_fixup_f32 v3, v0, v3, 1.0
	v_div_scale_f32 v0, s[0:1], v2, v2, 1.0
	v_rcp_f32_e32 v4, v0
	s_nop 0
	v_fma_f32 v10, -v0, v4, 1.0
	v_fmac_f32_e32 v4, v10, v4
	v_div_scale_f32 v10, vcc, 1.0, v2, 1.0
	v_mul_f32_e32 v11, v10, v4
	v_fma_f32 v12, -v0, v11, v10
	v_fmac_f32_e32 v11, v12, v4
	v_fma_f32 v0, -v0, v11, v10
	v_div_fmas_f32 v0, v0, v4, v11
	v_div_fixup_f32 v2, v0, v2, 1.0
	v_lshlrev_b32_e32 v10, 16, v9
	v_and_b32_e32 v11, 0xffff0000, v9
	v_lshlrev_b32_e32 v4, 16, v5
	v_and_b32_e32 v5, 0xffff0000, v5
	v_pk_fma_f32 v[2:3], v[2:3], v[10:11], v[4:5]
	s_nop 0
	v_cvt_pk_bf16_f32 v9, v2, v3
